# removed per-k-tile s_setprio raise/lower in all MFMA GEMM k-loops (on top of EpiRes epilogue change)
# speedup vs baseline: 1.0195x; 1.0053x over previous
.LBB0_84:
	s_add_i32 s3, s24, 2
	v_add_u32_e32 v181, v144, v145
	ds_read_b128 v[80:83], v181 offset:16384
	ds_read_b128 v[84:87], v181 offset:18432
	ds_read_b128 v[88:91], v181 offset:20480
	ds_read_b128 v[92:95], v181 offset:22528
	v_add_u32_e32 v180, v143, v145
	ds_read_b128 v[64:67], v180
	s_add_i32 s24, s24, 4
	ds_read_b128 v[68:71], v180 offset:2048
	s_min_u32 s24, s24, 15
	s_lshl_b32 s92, s24, 7
	ds_read_b128 v[72:75], v180 offset:4096
	ds_read_b128 v[76:79], v180 offset:6144
	v_add_u32_e32 v182, v143, v146
	v_add_u32_e32 v186, v144, v146
	v_lshl_add_u64 v[224:225], v[138:139], 0, s[92:93]
	ds_read_b128 v[192:195], v182
	ds_read_b128 v[196:199], v182 offset:2048
	ds_read_b128 v[200:203], v182 offset:4096
	ds_read_b128 v[204:207], v182 offset:6144
	ds_read_b128 v[208:211], v186 offset:16384
	ds_read_b128 v[212:215], v186 offset:18432
	ds_read_b128 v[216:219], v186 offset:20480
	ds_read_b128 v[220:223], v186 offset:22528
	s_waitcnt lgkmcnt(11)
	v_mfma_f32_16x16x32_bf16 v[60:63], v[80:83], v[64:67], v[60:63]
	v_mfma_f32_16x16x32_bf16 v[56:59], v[84:87], v[64:67], v[56:59]
	v_mfma_f32_16x16x32_bf16 v[52:55], v[88:91], v[64:67], v[52:55]
	v_mfma_f32_16x16x32_bf16 v[48:51], v[92:95], v[64:67], v[48:51]
	global_load_dwordx4 v[64:67], v[224:225], off
	s_waitcnt vmcnt(6)
	ds_write_b128 v156, v[96:99] offset:32768
	v_add_co_u32_e32 v96, vcc, s11, v224
	s_waitcnt lgkmcnt(11)
	v_mfma_f32_16x16x32_bf16 v[44:47], v[80:83], v[68:71], v[44:47]
	v_addc_co_u32_e32 v97, vcc, 0, v225, vcc
	v_mfma_f32_16x16x32_bf16 v[40:43], v[84:87], v[68:71], v[40:43]
	v_mfma_f32_16x16x32_bf16 v[36:39], v[88:91], v[68:71], v[36:39]
	v_mfma_f32_16x16x32_bf16 v[32:35], v[92:95], v[68:71], v[32:35]
	global_load_dwordx4 v[68:71], v[96:97], off
	v_add_co_u32_e32 v96, vcc, s33, v224
	ds_write_b128 v156, v[100:103] offset:36864
	s_nop 0
	v_addc_co_u32_e32 v97, vcc, 0, v225, vcc
	s_waitcnt lgkmcnt(11)
	v_mfma_f32_16x16x32_bf16 v[28:31], v[80:83], v[72:75], v[28:31]
	v_mfma_f32_16x16x32_bf16 v[24:27], v[84:87], v[72:75], v[24:27]
	v_mfma_f32_16x16x32_bf16 v[20:23], v[88:91], v[72:75], v[20:23]
	v_mfma_f32_16x16x32_bf16 v[16:19], v[92:95], v[72:75], v[16:19]
	global_load_dwordx4 v[72:75], v[96:97], off
	ds_write_b128 v156, v[104:107] offset:40960
	s_waitcnt lgkmcnt(11)
	v_mfma_f32_16x16x32_bf16 v[12:15], v[80:83], v[76:79], v[12:15]
	v_add_co_u32_e32 v80, vcc, s59, v224
	v_mfma_f32_16x16x32_bf16 v[0:3], v[92:95], v[76:79], v[0:3]
	s_nop 0
	v_addc_co_u32_e32 v81, vcc, 0, v225, vcc
	v_lshl_add_u64 v[92:93], v[140:141], 0, s[92:93]
	v_mfma_f32_16x16x32_bf16 v[8:11], v[84:87], v[76:79], v[8:11]
	v_add_co_u32_e32 v84, vcc, s11, v92
	s_nop 1
	v_addc_co_u32_e32 v85, vcc, 0, v93, vcc
	v_mfma_f32_16x16x32_bf16 v[4:7], v[88:91], v[76:79], v[4:7]
	v_add_co_u32_e32 v88, vcc, s33, v92
	global_load_dwordx4 v[76:79], v[80:81], off
	s_nop 0
	v_addc_co_u32_e32 v89, vcc, 0, v93, vcc
	s_waitcnt vmcnt(7)
	ds_write_b128 v156, v[112:115] offset:45056
	s_waitcnt lgkmcnt(7)
	v_mfma_f32_16x16x32_bf16 v[60:63], v[208:211], v[192:195], v[60:63]
	s_waitcnt lgkmcnt(6)
	v_mfma_f32_16x16x32_bf16 v[56:59], v[212:215], v[192:195], v[56:59]
	s_waitcnt lgkmcnt(5)
	v_mfma_f32_16x16x32_bf16 v[52:55], v[216:219], v[192:195], v[52:55]
	s_waitcnt lgkmcnt(4)
	v_mfma_f32_16x16x32_bf16 v[48:51], v[220:223], v[192:195], v[48:51]
	global_load_dwordx4 v[80:83], v[92:93], off
	v_add_co_u32_e32 v92, vcc, s59, v92
	ds_write_b128 v156, v[108:111] offset:49152
	s_nop 0
	v_addc_co_u32_e32 v93, vcc, 0, v93, vcc
	v_mfma_f32_16x16x32_bf16 v[44:47], v[208:211], v[196:199], v[44:47]
	v_mfma_f32_16x16x32_bf16 v[40:43], v[212:215], v[196:199], v[40:43]
	v_mfma_f32_16x16x32_bf16 v[36:39], v[216:219], v[196:199], v[36:39]
	v_mfma_f32_16x16x32_bf16 v[32:35], v[220:223], v[196:199], v[32:35]
	global_load_dwordx4 v[84:87], v[84:85], off
	s_waitcnt vmcnt(8)
	ds_write_b128 v156, v[116:119] offset:53248
	v_mfma_f32_16x16x32_bf16 v[28:31], v[208:211], v[200:203], v[28:31]
	v_mfma_f32_16x16x32_bf16 v[24:27], v[212:215], v[200:203], v[24:27]
	v_mfma_f32_16x16x32_bf16 v[20:23], v[216:219], v[200:203], v[20:23]
	v_mfma_f32_16x16x32_bf16 v[16:19], v[220:223], v[200:203], v[16:19]
	global_load_dwordx4 v[88:91], v[88:89], off
	s_waitcnt vmcnt(8)
	ds_write_b128 v156, v[120:123] offset:57344
	v_mfma_f32_16x16x32_bf16 v[12:15], v[208:211], v[204:207], v[12:15]
	v_mfma_f32_16x16x32_bf16 v[8:11], v[212:215], v[204:207], v[8:11]
	v_mfma_f32_16x16x32_bf16 v[4:7], v[216:219], v[204:207], v[4:7]
	v_mfma_f32_16x16x32_bf16 v[0:3], v[220:223], v[204:207], v[0:3]
	global_load_dwordx4 v[92:95], v[92:93], off
	s_waitcnt vmcnt(8)
	ds_write_b128 v156, v[124:127] offset:61440
	s_waitcnt lgkmcnt(0)
	s_barrier
	ds_read_b128 v[112:115], v181 offset:49152
	ds_read_b128 v[116:119], v181 offset:51200
	ds_read_b128 v[120:123], v181 offset:53248
	ds_read_b128 v[124:127], v181 offset:55296
	ds_read_b128 v[96:99], v180 offset:32768
	ds_read_b128 v[100:103], v180 offset:34816
	s_min_u32 s24, s3, 12
	s_lshl_b32 s92, s24, 7
	ds_read_b128 v[104:107], v180 offset:36864
	v_lshl_add_u64 v[224:225], v[138:139], 0, s[92:93]
	ds_read_b128 v[108:111], v180 offset:38912
	ds_read_b128 v[192:195], v182 offset:32768
	ds_read_b128 v[196:199], v182 offset:34816
	ds_read_b128 v[200:203], v182 offset:36864
	ds_read_b128 v[204:207], v182 offset:38912
	ds_read_b128 v[208:211], v186 offset:49152
	ds_read_b128 v[212:215], v186 offset:51200
	ds_read_b128 v[216:219], v186 offset:53248
	ds_read_b128 v[220:223], v186 offset:55296
	s_waitcnt lgkmcnt(11)
	v_mfma_f32_16x16x32_bf16 v[60:63], v[112:115], v[96:99], v[60:63]
	v_mfma_f32_16x16x32_bf16 v[56:59], v[116:119], v[96:99], v[56:59]
	v_mfma_f32_16x16x32_bf16 v[52:55], v[120:123], v[96:99], v[52:55]
	v_mfma_f32_16x16x32_bf16 v[48:51], v[124:127], v[96:99], v[48:51]
	global_load_dwordx4 v[96:99], v[224:225], off offset:384
	s_waitcnt vmcnt(8)
	ds_write_b128 v156, v[64:67]
	v_add_co_u32_e32 v64, vcc, s11, v224
	s_waitcnt lgkmcnt(11)
	v_mfma_f32_16x16x32_bf16 v[44:47], v[112:115], v[100:103], v[44:47]
	v_addc_co_u32_e32 v65, vcc, 0, v225, vcc
	v_mfma_f32_16x16x32_bf16 v[40:43], v[116:119], v[100:103], v[40:43]
	v_mfma_f32_16x16x32_bf16 v[36:39], v[120:123], v[100:103], v[36:39]
	v_mfma_f32_16x16x32_bf16 v[32:35], v[124:127], v[100:103], v[32:35]
	global_load_dwordx4 v[100:103], v[64:65], off offset:384
	v_add_co_u32_e32 v64, vcc, s33, v224
	s_waitcnt vmcnt(8)
	ds_write_b128 v156, v[68:71] offset:4096
	v_addc_co_u32_e32 v65, vcc, 0, v225, vcc
	s_waitcnt lgkmcnt(11)
	v_mfma_f32_16x16x32_bf16 v[28:31], v[112:115], v[104:107], v[28:31]
	v_mfma_f32_16x16x32_bf16 v[24:27], v[116:119], v[104:107], v[24:27]
	v_mfma_f32_16x16x32_bf16 v[20:23], v[120:123], v[104:107], v[20:23]
	v_mfma_f32_16x16x32_bf16 v[16:19], v[124:127], v[104:107], v[16:19]
	global_load_dwordx4 v[104:107], v[64:65], off offset:384
	v_add_co_u32_e32 v64, vcc, s59, v224
	s_waitcnt vmcnt(8)
	ds_write_b128 v156, v[72:75] offset:8192
	v_addc_co_u32_e32 v65, vcc, 0, v225, vcc
	s_waitcnt lgkmcnt(11)
	v_mfma_f32_16x16x32_bf16 v[12:15], v[112:115], v[108:111], v[12:15]
	v_mfma_f32_16x16x32_bf16 v[8:11], v[116:119], v[108:111], v[8:11]
	v_mfma_f32_16x16x32_bf16 v[4:7], v[120:123], v[108:111], v[4:7]
	v_mfma_f32_16x16x32_bf16 v[0:3], v[124:127], v[108:111], v[0:3]
	global_load_dwordx4 v[112:115], v[64:65], off offset:384
	v_lshl_add_u64 v[64:65], v[140:141], 0, s[92:93]
	v_add_co_u32_e32 v66, vcc, s11, v64
	s_waitcnt vmcnt(8)
	ds_write_b128 v156, v[76:79] offset:12288
	v_addc_co_u32_e32 v67, vcc, 0, v65, vcc
	s_waitcnt lgkmcnt(7)
	v_mfma_f32_16x16x32_bf16 v[60:63], v[208:211], v[192:195], v[60:63]
	s_waitcnt lgkmcnt(6)
	v_mfma_f32_16x16x32_bf16 v[56:59], v[212:215], v[192:195], v[56:59]
	s_waitcnt lgkmcnt(5)
	v_mfma_f32_16x16x32_bf16 v[52:55], v[216:219], v[192:195], v[52:55]
	s_waitcnt lgkmcnt(4)
	v_mfma_f32_16x16x32_bf16 v[48:51], v[220:223], v[192:195], v[48:51]
	global_load_dwordx4 v[108:111], v[64:65], off offset:384
	s_waitcnt vmcnt(8)
	ds_write_b128 v156, v[80:83] offset:16384
	v_mfma_f32_16x16x32_bf16 v[44:47], v[208:211], v[196:199], v[44:47]
	v_mfma_f32_16x16x32_bf16 v[40:43], v[212:215], v[196:199], v[40:43]
	v_mfma_f32_16x16x32_bf16 v[36:39], v[216:219], v[196:199], v[36:39]
	v_mfma_f32_16x16x32_bf16 v[32:35], v[220:223], v[196:199], v[32:35]
	global_load_dwordx4 v[116:119], v[66:67], off offset:384
	v_add_co_u32_e32 v66, vcc, s33, v64
	s_waitcnt vmcnt(8)
	ds_write_b128 v156, v[84:87] offset:20480
	v_addc_co_u32_e32 v67, vcc, 0, v65, vcc
	v_add_co_u32_e32 v64, vcc, s59, v64
	v_mfma_f32_16x16x32_bf16 v[28:31], v[208:211], v[200:203], v[28:31]
	s_nop 0
	v_addc_co_u32_e32 v65, vcc, 0, v65, vcc
	v_mfma_f32_16x16x32_bf16 v[24:27], v[212:215], v[200:203], v[24:27]
	v_mfma_f32_16x16x32_bf16 v[20:23], v[216:219], v[200:203], v[20:23]
	v_mfma_f32_16x16x32_bf16 v[16:19], v[220:223], v[200:203], v[16:19]
	global_load_dwordx4 v[120:123], v[66:67], off offset:384
	s_waitcnt vmcnt(8)
	ds_write_b128 v156, v[88:91] offset:24576
	v_mfma_f32_16x16x32_bf16 v[12:15], v[208:211], v[204:207], v[12:15]
	v_mfma_f32_16x16x32_bf16 v[8:11], v[212:215], v[204:207], v[8:11]
	v_mfma_f32_16x16x32_bf16 v[4:7], v[216:219], v[204:207], v[4:7]
	v_mfma_f32_16x16x32_bf16 v[0:3], v[220:223], v[204:207], v[0:3]
	global_load_dwordx4 v[124:127], v[64:65], off offset:384
	s_waitcnt vmcnt(8)
	ds_write_b128 v156, v[92:95] offset:28672
	s_cmp_lt_u32 s3, 14
	s_mov_b32 s24, s3
	s_waitcnt lgkmcnt(0)
	s_barrier
	s_cbranch_scc1 .LBB0_84
	s_and_saveexec_b64 s[24:25], s[36:37]
	s_cbranch_execz .LBB0_82
	v_add_f32_e32 v64, 0, v128
	v_add_f32_e32 v64, v64, v157
	v_add_f32_e32 v64, v64, v158
	v_add_f32_e32 v64, v64, v159
	v_add_f32_e32 v64, v64, v160
	v_add_f32_e32 v64, v64, v161
	v_add_f32_e32 v64, v64, v162
	v_add_f32_e32 v64, v64, v163
	v_add_f32_e32 v64, v64, v164
	v_add_f32_e32 v64, v64, v165
	v_add_f32_e32 v64, v64, v168
	v_add_f32_e32 v64, v64, v175
	v_add_f32_e32 v64, v64, v179
	v_add_f32_e32 v64, v64, v183
	v_add_f32_e32 v64, v64, v190
	v_add_f32_e32 v64, v64, v191
	v_fmamk_f32 v64, v64, 0x3a800000, v167
	s_mov_b32 s3, 0x800000
	v_mul_f32_e32 v65, 0x4b800000, v64
	v_cmp_gt_f32_e32 vcc, s3, v64
	s_nop 1
	v_cndmask_b32_e32 v64, v64, v65, vcc
	v_rsq_f32_e32 v64, v64
	s_nop 0
	v_mul_f32_e32 v65, 0x45800000, v64
	v_cndmask_b32_e32 v64, v64, v65, vcc
	ds_write_b32 v155, v64
	s_branch .LBB0_82

.LBB0_92:
	s_add_i32 s0, s1, 2
	v_add_u32_e32 v111, v104, v105
	ds_read_b128 v[136:139], v111 offset:16384
	ds_read_b128 v[140:143], v111 offset:18432
	ds_read_b128 v[144:147], v111 offset:20480
	ds_read_b128 v[148:151], v111 offset:22528
	v_add_u32_e32 v110, v103, v105
	ds_read_b128 v[116:119], v110
	s_add_i32 s1, s1, 4
	ds_read_b128 v[120:123], v110 offset:2048
	s_min_u32 s1, s1, 15
	v_add_u32_e32 v113, v104, v114
	s_lshl_b32 s92, s1, 7
	ds_read_b128 v[124:127], v110 offset:4096
	v_add_u32_e32 v112, v103, v114
	ds_read_b128 v[194:197], v113 offset:16384
	ds_read_b128 v[198:201], v113 offset:18432
	ds_read_b128 v[202:205], v113 offset:20480
	ds_read_b128 v[206:209], v113 offset:22528
	v_lshl_add_u64 v[164:165], v[98:99], 0, s[92:93]
	ds_read_b128 v[132:135], v110 offset:6144
	ds_read_b128 v[152:155], v112
	ds_read_b128 v[156:159], v112 offset:2048
	ds_read_b128 v[160:163], v112 offset:4096
	ds_read_b128 v[190:193], v112 offset:6144
	s_waitcnt lgkmcnt(11)
	v_mfma_f32_16x16x32_bf16 v[92:95], v[136:139], v[116:119], v[92:95]
	v_mfma_f32_16x16x32_bf16 v[88:91], v[140:143], v[116:119], v[88:91]
	v_mfma_f32_16x16x32_bf16 v[52:55], v[144:147], v[116:119], v[52:55]
	v_mfma_f32_16x16x32_bf16 v[48:51], v[148:151], v[116:119], v[48:51]
	global_load_dwordx4 v[116:119], v[164:165], off
	s_waitcnt vmcnt(6)
	ds_write_b128 v109, v[56:59] offset:32768
	v_add_co_u32_e32 v56, vcc, s11, v164
	s_waitcnt lgkmcnt(11)
	v_mfma_f32_16x16x32_bf16 v[44:47], v[136:139], v[120:123], v[44:47]
	v_addc_co_u32_e32 v57, vcc, 0, v165, vcc
	v_mfma_f32_16x16x32_bf16 v[40:43], v[140:143], v[120:123], v[40:43]
	v_mfma_f32_16x16x32_bf16 v[36:39], v[144:147], v[120:123], v[36:39]
	v_mfma_f32_16x16x32_bf16 v[32:35], v[148:151], v[120:123], v[32:35]
	global_load_dwordx4 v[120:123], v[56:57], off
	v_add_co_u32_e32 v56, vcc, s33, v164
	ds_write_b128 v109, v[60:63] offset:36864
	s_nop 0
	v_addc_co_u32_e32 v57, vcc, 0, v165, vcc
	s_waitcnt lgkmcnt(11)
	v_mfma_f32_16x16x32_bf16 v[28:31], v[136:139], v[124:127], v[28:31]
	v_mfma_f32_16x16x32_bf16 v[24:27], v[140:143], v[124:127], v[24:27]
	v_mfma_f32_16x16x32_bf16 v[20:23], v[144:147], v[124:127], v[20:23]
	v_mfma_f32_16x16x32_bf16 v[16:19], v[148:151], v[124:127], v[16:19]
	global_load_dwordx4 v[124:127], v[56:57], off
	v_add_co_u32_e32 v56, vcc, s59, v164
	ds_write_b128 v109, v[64:67] offset:40960
	s_nop 0
	v_addc_co_u32_e32 v57, vcc, 0, v165, vcc
	v_lshl_add_u64 v[64:65], v[100:101], 0, s[92:93]
	v_add_co_u32_e32 v66, vcc, s11, v64
	s_waitcnt lgkmcnt(7)
	v_mfma_f32_16x16x32_bf16 v[12:15], v[136:139], v[132:135], v[12:15]
	v_addc_co_u32_e32 v67, vcc, 0, v65, vcc
	v_mfma_f32_16x16x32_bf16 v[8:11], v[140:143], v[132:135], v[8:11]
	v_mfma_f32_16x16x32_bf16 v[4:7], v[144:147], v[132:135], v[4:7]
	v_mfma_f32_16x16x32_bf16 v[0:3], v[148:151], v[132:135], v[0:3]
	global_load_dwordx4 v[132:135], v[56:57], off
	s_waitcnt vmcnt(7)
	ds_write_b128 v109, v[72:75] offset:45056
	s_waitcnt lgkmcnt(7)
	v_mfma_f32_16x16x32_bf16 v[56:59], v[194:197], v[152:155], v[92:95]
	v_mfma_f32_16x16x32_bf16 v[60:63], v[198:201], v[152:155], v[88:91]
	v_mfma_f32_16x16x32_bf16 v[52:55], v[202:205], v[152:155], v[52:55]
	v_mfma_f32_16x16x32_bf16 v[48:51], v[206:209], v[152:155], v[48:51]
	global_load_dwordx4 v[136:139], v[64:65], off
	ds_write_b128 v109, v[68:71] offset:49152
	s_waitcnt lgkmcnt(7)
	v_mfma_f32_16x16x32_bf16 v[44:47], v[194:197], v[156:159], v[44:47]
	v_mfma_f32_16x16x32_bf16 v[40:43], v[198:201], v[156:159], v[40:43]
	v_mfma_f32_16x16x32_bf16 v[36:39], v[202:205], v[156:159], v[36:39]
	v_mfma_f32_16x16x32_bf16 v[32:35], v[206:209], v[156:159], v[32:35]
	global_load_dwordx4 v[140:143], v[66:67], off
	v_add_co_u32_e32 v66, vcc, s33, v64
	s_waitcnt vmcnt(8)
	ds_write_b128 v109, v[76:79] offset:53248
	v_addc_co_u32_e32 v67, vcc, 0, v65, vcc
	v_add_co_u32_e32 v64, vcc, s59, v64
	s_waitcnt lgkmcnt(7)
	v_mfma_f32_16x16x32_bf16 v[28:31], v[194:197], v[160:163], v[28:31]
	v_addc_co_u32_e32 v65, vcc, 0, v65, vcc
	v_mfma_f32_16x16x32_bf16 v[24:27], v[198:201], v[160:163], v[24:27]
	v_mfma_f32_16x16x32_bf16 v[20:23], v[202:205], v[160:163], v[20:23]
	v_mfma_f32_16x16x32_bf16 v[16:19], v[206:209], v[160:163], v[16:19]
	global_load_dwordx4 v[144:147], v[66:67], off
	s_waitcnt vmcnt(8)
	ds_write_b128 v109, v[80:83] offset:57344
	s_waitcnt lgkmcnt(7)
	v_mfma_f32_16x16x32_bf16 v[12:15], v[194:197], v[190:193], v[12:15]
	v_mfma_f32_16x16x32_bf16 v[8:11], v[198:201], v[190:193], v[8:11]
	v_mfma_f32_16x16x32_bf16 v[4:7], v[202:205], v[190:193], v[4:7]
	v_mfma_f32_16x16x32_bf16 v[0:3], v[206:209], v[190:193], v[0:3]
	global_load_dwordx4 v[148:151], v[64:65], off
	s_waitcnt vmcnt(8)
	ds_write_b128 v109, v[84:87] offset:61440
	s_waitcnt lgkmcnt(0)
	s_barrier
	ds_read_b128 v[84:87], v111 offset:51200
	ds_read_b128 v[80:83], v111 offset:49152
	ds_read_b128 v[88:91], v111 offset:53248
	ds_read_b128 v[92:95], v111 offset:55296
	ds_read_b128 v[64:67], v110 offset:32768
	s_min_u32 s1, s0, 12
	s_lshl_b32 s92, s1, 7
	ds_read_b128 v[68:71], v110 offset:34816
	v_lshl_add_u64 v[164:165], v[98:99], 0, s[92:93]
	ds_read_b128 v[72:75], v110 offset:36864
	ds_read_b128 v[76:79], v110 offset:38912
	ds_read_b128 v[152:155], v112 offset:32768
	ds_read_b128 v[156:159], v112 offset:34816
	ds_read_b128 v[160:163], v112 offset:36864
	ds_read_b128 v[190:193], v112 offset:38912
	ds_read_b128 v[194:197], v113 offset:49152
	ds_read_b128 v[198:201], v113 offset:51200
	ds_read_b128 v[202:205], v113 offset:53248
	ds_read_b128 v[206:209], v113 offset:55296
	s_waitcnt lgkmcnt(11)
	v_mfma_f32_16x16x32_bf16 v[214:217], v[84:87], v[64:67], v[60:63]
	v_mfma_f32_16x16x32_bf16 v[210:213], v[80:83], v[64:67], v[56:59]
	s_nop 1
	v_add_co_u32_e32 v60, vcc, s11, v164
	s_nop 1
	v_addc_co_u32_e32 v61, vcc, 0, v165, vcc
	v_mfma_f32_16x16x32_bf16 v[52:55], v[88:91], v[64:67], v[52:55]
	v_mfma_f32_16x16x32_bf16 v[48:51], v[92:95], v[64:67], v[48:51]
	v_add_co_u32_e32 v64, vcc, s33, v164
	global_load_dwordx4 v[56:59], v[164:165], off offset:384
	s_nop 0
	v_addc_co_u32_e32 v65, vcc, 0, v165, vcc
	s_waitcnt vmcnt(8)
	ds_write_b128 v109, v[116:119]
	s_waitcnt lgkmcnt(11)
	v_mfma_f32_16x16x32_bf16 v[44:47], v[80:83], v[68:71], v[44:47]
	v_mfma_f32_16x16x32_bf16 v[40:43], v[84:87], v[68:71], v[40:43]
	v_mfma_f32_16x16x32_bf16 v[36:39], v[88:91], v[68:71], v[36:39]
	v_mfma_f32_16x16x32_bf16 v[32:35], v[92:95], v[68:71], v[32:35]
	v_add_co_u32_e32 v68, vcc, s59, v164
	global_load_dwordx4 v[60:63], v[60:61], off offset:384
	s_waitcnt vmcnt(8)
	ds_write_b128 v109, v[120:123] offset:4096
	s_waitcnt lgkmcnt(11)
	v_mfma_f32_16x16x32_bf16 v[28:31], v[80:83], v[72:75], v[28:31]
	v_addc_co_u32_e32 v69, vcc, 0, v165, vcc
	v_mfma_f32_16x16x32_bf16 v[24:27], v[84:87], v[72:75], v[24:27]
	v_mfma_f32_16x16x32_bf16 v[20:23], v[88:91], v[72:75], v[20:23]
	v_mfma_f32_16x16x32_bf16 v[16:19], v[92:95], v[72:75], v[16:19]
	global_load_dwordx4 v[64:67], v[64:65], off offset:384
	s_waitcnt vmcnt(8)
	ds_write_b128 v109, v[124:127] offset:8192
	s_waitcnt lgkmcnt(11)
	v_mfma_f32_16x16x32_bf16 v[8:11], v[84:87], v[76:79], v[8:11]
	v_lshl_add_u64 v[84:85], v[100:101], 0, s[92:93]
	v_mfma_f32_16x16x32_bf16 v[12:15], v[80:83], v[76:79], v[12:15]
	v_mfma_f32_16x16x32_bf16 v[4:7], v[88:91], v[76:79], v[4:7]
	v_mfma_f32_16x16x32_bf16 v[0:3], v[92:95], v[76:79], v[0:3]
	v_add_co_u32_e32 v76, vcc, s11, v84
	global_load_dwordx4 v[72:75], v[68:69], off offset:384
	s_nop 0
	v_addc_co_u32_e32 v77, vcc, 0, v85, vcc
	v_add_co_u32_e32 v80, vcc, s33, v84
	s_waitcnt vmcnt(8)
	ds_write_b128 v109, v[132:135] offset:12288
	v_addc_co_u32_e32 v81, vcc, 0, v85, vcc
	s_waitcnt lgkmcnt(7)
	v_mfma_f32_16x16x32_bf16 v[92:95], v[194:197], v[152:155], v[210:213]
	s_waitcnt lgkmcnt(6)
	v_mfma_f32_16x16x32_bf16 v[88:91], v[198:201], v[152:155], v[214:217]
	s_waitcnt lgkmcnt(5)
	v_mfma_f32_16x16x32_bf16 v[52:55], v[202:205], v[152:155], v[52:55]
	s_waitcnt lgkmcnt(4)
	v_mfma_f32_16x16x32_bf16 v[48:51], v[206:209], v[152:155], v[48:51]
	global_load_dwordx4 v[68:71], v[84:85], off offset:384
	v_add_co_u32_e32 v84, vcc, s59, v84
	s_waitcnt vmcnt(8)
	ds_write_b128 v109, v[136:139] offset:16384
	v_addc_co_u32_e32 v85, vcc, 0, v85, vcc
	v_mfma_f32_16x16x32_bf16 v[44:47], v[194:197], v[156:159], v[44:47]
	v_mfma_f32_16x16x32_bf16 v[40:43], v[198:201], v[156:159], v[40:43]
	v_mfma_f32_16x16x32_bf16 v[36:39], v[202:205], v[156:159], v[36:39]
	v_mfma_f32_16x16x32_bf16 v[32:35], v[206:209], v[156:159], v[32:35]
	global_load_dwordx4 v[76:79], v[76:77], off offset:384
	s_waitcnt vmcnt(8)
	ds_write_b128 v109, v[140:143] offset:20480
	v_mfma_f32_16x16x32_bf16 v[28:31], v[194:197], v[160:163], v[28:31]
	v_mfma_f32_16x16x32_bf16 v[24:27], v[198:201], v[160:163], v[24:27]
	v_mfma_f32_16x16x32_bf16 v[20:23], v[202:205], v[160:163], v[20:23]
	v_mfma_f32_16x16x32_bf16 v[16:19], v[206:209], v[160:163], v[16:19]
	global_load_dwordx4 v[80:83], v[80:81], off offset:384
	s_waitcnt vmcnt(8)
	ds_write_b128 v109, v[144:147] offset:24576
	v_mfma_f32_16x16x32_bf16 v[12:15], v[194:197], v[190:193], v[12:15]
	v_mfma_f32_16x16x32_bf16 v[8:11], v[198:201], v[190:193], v[8:11]
	v_mfma_f32_16x16x32_bf16 v[4:7], v[202:205], v[190:193], v[4:7]
	v_mfma_f32_16x16x32_bf16 v[0:3], v[206:209], v[190:193], v[0:3]
	global_load_dwordx4 v[84:87], v[84:85], off offset:384
	s_waitcnt vmcnt(8)
	ds_write_b128 v109, v[148:151] offset:28672
	s_cmp_lt_u32 s0, 14
	s_mov_b32 s1, s0
	s_waitcnt lgkmcnt(0)
	s_barrier
	s_cbranch_scc1 .LBB0_92
	s_mul_i32 s0, s69, 0x12000
	v_readlane_b32 s16, v250, 25
	s_add_u32 s24, s16, s0
	v_readlane_b32 s0, v251, 5
	v_lshlrev_b32_e32 v114, 6, v102
	v_readlane_b32 s17, v250, 26
	s_waitcnt vmcnt(5)
	v_add_u32_e32 v64, s0, v108
	v_readlane_b32 s0, v251, 6
	v_add_u32_e32 v56, 0xffffe000, v64
	v_or_b32_e32 v62, v64, v107
	v_or_b32_e32 v65, s0, v114
	v_lshrrev_b32_e32 v56, 10, v56
	s_movk_i32 s0, 0x1800
	v_mad_u32_u24 v56, v56, s0, s0
	v_cmp_lt_i32_e32 vcc, s13, v62
	s_addc_u32 s25, s17, 0
	v_lshlrev_b32_e32 v115, 2, v97
	v_cndmask_b32_e32 v56, 0, v56, vcc
	s_add_u32 s40, s24, 0x2000
	v_or_b32_e32 v58, v65, v115
	v_ashrrev_i32_e32 v57, 31, v56
	s_addc_u32 s41, s25, 0
	s_waitcnt vmcnt(4)
	v_lshlrev_b64 v[74:75], 2, v[56:57]
	v_ashrrev_i32_e32 v59, 31, v58
	v_ashrrev_i32_e32 v63, 31, v62
	v_lshl_add_u64 v[56:57], s[40:41], 0, v[74:75]
	v_lshlrev_b64 v[60:61], 2, v[58:59]
	v_readlane_b32 s0, v250, 15
	s_waitcnt vmcnt(1)
	v_lshl_add_u64 v[82:83], v[56:57], 0, v[60:61]
	v_lshlrev_b64 v[56:57], 12, v[62:63]
	v_readlane_b32 s1, v250, 16
	v_readlane_b32 s16, v250, 21
	v_lshlrev_b64 v[78:79], 11, v[62:63]
	v_lshl_add_u64 v[56:57], s[0:1], 0, v[56:57]
	s_waitcnt vmcnt(0)
	v_lshl_add_u64 v[84:85], v[56:57], 0, v[60:61]
	global_load_dwordx4 v[116:119], v[82:83], off
	global_load_dwordx4 v[120:123], v[82:83], off offset:64
	global_load_dwordx4 v[124:127], v[82:83], off offset:128
	global_load_dwordx4 v[132:135], v[82:83], off offset:192
	global_load_dwordx4 v[190:193], v[84:85], off
	global_load_dwordx4 v[194:197], v[84:85], off offset:64
	global_load_dwordx4 v[198:201], v[84:85], off offset:128
	global_load_dwordx4 v[202:205], v[84:85], off offset:192
	v_add_co_u32_e32 v164, vcc, 0x10000, v84
	s_nop 1
	v_addc_co_u32_e32 v165, vcc, 0, v85, vcc
	v_add_co_u32_e32 v222, vcc, 0x20000, v84
	s_nop 1
	v_addc_co_u32_e32 v223, vcc, 0, v85, vcc
	v_add_co_u32_e32 v224, vcc, 0x30000, v84
	s_nop 1
	v_addc_co_u32_e32 v225, vcc, 0, v85, vcc
	global_load_dwordx4 v[206:209], v[164:165], off
	global_load_dwordx4 v[210:213], v[164:165], off offset:64
	global_load_dwordx4 v[214:217], v[164:165], off offset:128
	global_load_dwordx4 v[218:221], v[164:165], off offset:192
	s_lshl_b32 s0, s69, 12
	v_readlane_b32 s68, v250, 41
	v_readlane_b32 s72, v250, 45
	v_readlane_b32 s73, v250, 46
	s_add_u32 s0, s72, s0
	s_addc_u32 s1, s73, 0
	s_add_u32 s42, s24, 0x4000
	s_addc_u32 s43, s25, 0
	v_lshl_add_u64 v[74:75], s[42:43], 0, v[74:75]
	v_lshl_add_u64 v[56:57], s[0:1], 0, v[60:61]
	v_lshl_add_u64 v[86:87], v[74:75], 0, v[60:61]
	v_readlane_b32 s17, v250, 22
	v_readlane_b32 s69, v250, 42
	v_readlane_b32 s69, v254, 49
	v_lshl_add_u64 v[78:79], s[16:17], 0, v[78:79]
	s_mul_i32 s24, s69, 0x140000
	s_add_u32 s24, s86, s24
	v_lshrrev_b32_e32 v65, 6, v65
	s_mov_b32 s16, 0xa000
	s_addc_u32 s25, s87, 0
	s_add_u32 s26, s24, 0xaf1a000
	s_addc_u32 s27, s25, 0
	v_cmp_eq_u32_e64 s[36:37], 0, v97
	v_readlane_b32 s70, v250, 43
	v_readlane_b32 s71, v250, 44
	v_readlane_b32 s74, v250, 47
	v_readlane_b32 s75, v250, 48
	v_readlane_b32 s76, v250, 49
	v_readlane_b32 s77, v250, 50
	v_readlane_b32 s78, v250, 51
	v_readlane_b32 s79, v250, 52
	v_readlane_b32 s80, v250, 53
	v_readlane_b32 s81, v250, 54
	v_readlane_b32 s82, v250, 55
	v_readlane_b32 s83, v250, 56
	s_waitcnt vmcnt(4)
	v_pk_fma_f32 v[68:69], v[94:95], v[118:119], v[192:193]
	v_pk_fma_f32 v[66:67], v[92:93], v[116:117], v[190:191]
	global_store_dwordx4 v[84:85], v[66:69], off
	global_load_dwordx4 v[136:139], v[56:57], off
	global_load_dwordx4 v[140:143], v[56:57], off offset:64
	global_load_dwordx4 v[144:147], v[56:57], off offset:128
	global_load_dwordx4 v[148:151], v[56:57], off offset:192
	global_load_dwordx4 v[152:155], v[86:87], off
	global_load_dwordx4 v[156:159], v[86:87], off offset:64
	global_load_dwordx4 v[160:163], v[86:87], off offset:128
	global_load_dwordx4 v[180:183], v[86:87], off offset:192
	v_lshl_add_u64 v[92:93], v[58:59], 1, v[78:79]
	s_waitcnt vmcnt(0)
	v_pk_mul_f32 v[72:73], v[68:69], v[138:139]
	v_pk_mul_f32 v[70:71], v[66:67], v[136:137]
	s_waitcnt vmcnt(0)
	v_pk_add_f32 v[76:77], v[154:155], 1.0 op_sel_hi:[1,0]
	v_pk_add_f32 v[74:75], v[152:153], 1.0 op_sel_hi:[1,0]
	v_pk_mul_f32 v[72:73], v[72:73], v[76:77]
	v_pk_mul_f32 v[70:71], v[70:71], v[74:75]
	v_and_b32_sdwa v76, v73, v170 dst_sel:DWORD dst_unused:UNUSED_PAD src0_sel:WORD_1 src1_sel:DWORD
	v_and_b32_sdwa v77, v71, v170 dst_sel:DWORD dst_unused:UNUSED_PAD src0_sel:WORD_1 src1_sel:DWORD
	v_and_b32_sdwa v74, v72, v170 dst_sel:DWORD dst_unused:UNUSED_PAD src0_sel:WORD_1 src1_sel:DWORD
	v_and_b32_sdwa v75, v70, v170 dst_sel:DWORD dst_unused:UNUSED_PAD src0_sel:WORD_1 src1_sel:DWORD
	v_add3_u32 v73, v73, v76, s56
	v_add3_u32 v71, v71, v77, s56
	v_add3_u32 v70, v70, v75, s56
	v_add3_u32 v72, v72, v74, s56
	v_and_b32_e32 v73, 0xffff0000, v73
	v_and_b32_e32 v74, 0xffff0000, v71
	v_or_b32_sdwa v71, v73, v72 dst_sel:DWORD dst_unused:UNUSED_PAD src0_sel:DWORD src1_sel:WORD_1
	v_or_b32_sdwa v70, v74, v70 dst_sel:DWORD dst_unused:UNUSED_PAD src0_sel:DWORD src1_sel:WORD_1
	global_store_dwordx2 v[92:93], v[70:71], off
	s_nop 0
	s_waitcnt vmcnt(0)
	v_pk_fma_f32 v[72:73], v[90:91], v[122:123], v[196:197]
	v_pk_fma_f32 v[70:71], v[88:89], v[120:121], v[194:195]
	global_store_dwordx4 v[84:85], v[70:73], off offset:64
	v_pk_mul_f32 v[76:77], v[72:73], v[142:143]
	v_pk_mul_f32 v[74:75], v[70:71], v[140:141]
	v_pk_add_f32 v[80:81], v[158:159], 1.0 op_sel_hi:[1,0]
	v_pk_add_f32 v[78:79], v[156:157], 1.0 op_sel_hi:[1,0]
	v_pk_mul_f32 v[76:77], v[76:77], v[80:81]
	v_pk_mul_f32 v[74:75], v[74:75], v[78:79]
	v_and_b32_sdwa v80, v77, v170 dst_sel:DWORD dst_unused:UNUSED_PAD src0_sel:WORD_1 src1_sel:DWORD
	v_and_b32_sdwa v81, v75, v170 dst_sel:DWORD dst_unused:UNUSED_PAD src0_sel:WORD_1 src1_sel:DWORD
	v_and_b32_sdwa v78, v76, v170 dst_sel:DWORD dst_unused:UNUSED_PAD src0_sel:WORD_1 src1_sel:DWORD
	v_and_b32_sdwa v79, v74, v170 dst_sel:DWORD dst_unused:UNUSED_PAD src0_sel:WORD_1 src1_sel:DWORD
	v_add3_u32 v77, v77, v80, s56
	v_add3_u32 v75, v75, v81, s56
	v_add3_u32 v74, v74, v79, s56
	v_add3_u32 v76, v76, v78, s56
	v_and_b32_e32 v77, 0xffff0000, v77
	v_and_b32_e32 v78, 0xffff0000, v75
	v_or_b32_sdwa v75, v77, v76 dst_sel:DWORD dst_unused:UNUSED_PAD src0_sel:DWORD src1_sel:WORD_1
	v_or_b32_sdwa v74, v78, v74 dst_sel:DWORD dst_unused:UNUSED_PAD src0_sel:DWORD src1_sel:WORD_1
	global_store_dwordx2 v[92:93], v[74:75], off offset:32
	s_nop 0
	v_pk_fma_f32 v[54:55], v[54:55], v[126:127], v[200:201]
	v_pk_fma_f32 v[52:53], v[52:53], v[124:125], v[198:199]
	global_store_dwordx4 v[84:85], v[52:55], off offset:128
	v_pk_mul_f32 v[76:77], v[54:55], v[146:147]
	v_pk_mul_f32 v[74:75], v[52:53], v[144:145]
	v_pk_add_f32 v[80:81], v[162:163], 1.0 op_sel_hi:[1,0]
	v_pk_add_f32 v[78:79], v[160:161], 1.0 op_sel_hi:[1,0]
	v_pk_mul_f32 v[76:77], v[76:77], v[80:81]
	v_pk_mul_f32 v[74:75], v[74:75], v[78:79]
	v_and_b32_sdwa v80, v77, v170 dst_sel:DWORD dst_unused:UNUSED_PAD src0_sel:WORD_1 src1_sel:DWORD
	v_and_b32_sdwa v81, v75, v170 dst_sel:DWORD dst_unused:UNUSED_PAD src0_sel:WORD_1 src1_sel:DWORD
	v_and_b32_sdwa v78, v76, v170 dst_sel:DWORD dst_unused:UNUSED_PAD src0_sel:WORD_1 src1_sel:DWORD
	v_and_b32_sdwa v79, v74, v170 dst_sel:DWORD dst_unused:UNUSED_PAD src0_sel:WORD_1 src1_sel:DWORD
	v_add3_u32 v77, v77, v80, s56
	v_add3_u32 v75, v75, v81, s56
	v_add3_u32 v74, v74, v79, s56
	v_add3_u32 v76, v76, v78, s56
	v_and_b32_e32 v77, 0xffff0000, v77
	v_and_b32_e32 v78, 0xffff0000, v75
	v_or_b32_sdwa v75, v77, v76 dst_sel:DWORD dst_unused:UNUSED_PAD src0_sel:DWORD src1_sel:WORD_1
	v_or_b32_sdwa v74, v78, v74 dst_sel:DWORD dst_unused:UNUSED_PAD src0_sel:DWORD src1_sel:WORD_1
	global_store_dwordx2 v[92:93], v[74:75], off offset:64
	s_nop 0
	v_pk_fma_f32 v[76:77], v[50:51], v[134:135], v[204:205]
	v_pk_fma_f32 v[74:75], v[48:49], v[132:133], v[202:203]
	global_store_dwordx4 v[84:85], v[74:77], off offset:192
	s_nop 0
	v_mbcnt_lo_u32_b32 v48, -1, 0
	v_mbcnt_hi_u32_b32 v48, -1, v48
	v_and_b32_e32 v50, 64, v48
	v_xor_b32_e32 v49, 16, v48
	v_add_u32_e32 v50, 64, v50
	v_xor_b32_e32 v51, 32, v48
	v_cmp_lt_i32_e32 vcc, v49, v50
	s_nop 1
	v_cndmask_b32_e32 v49, v48, v49, vcc
	v_cmp_lt_i32_e32 vcc, v51, v50
	v_lshlrev_b32_e32 v105, 2, v49
	s_nop 0
	v_cndmask_b32_e32 v50, v48, v51, vcc
	v_lshlrev_b32_e32 v104, 2, v50
	v_mul_f32_e32 v50, v67, v67
	v_mul_f32_e32 v51, v71, v71
	v_fmac_f32_e32 v50, v66, v66
	v_fmac_f32_e32 v51, v70, v70
	v_fmac_f32_e32 v50, v68, v68
	v_fmac_f32_e32 v51, v72, v72
	v_fmac_f32_e32 v50, v69, v69
	v_fmac_f32_e32 v51, v73, v73
	v_add_f32_e32 v50, v50, v51
	v_mul_f32_e32 v51, v53, v53
	v_fmac_f32_e32 v51, v52, v52
	v_fmac_f32_e32 v51, v54, v54
	v_fmac_f32_e32 v51, v55, v55
	v_add_f32_e32 v50, v50, v51
	v_mul_f32_e32 v51, v75, v75
	v_fmac_f32_e32 v51, v74, v74
	v_fmac_f32_e32 v51, v76, v76
	v_fmac_f32_e32 v51, v77, v77
	v_add_f32_e32 v50, v50, v51
	ds_bpermute_b32 v51, v105, v50
	v_mul_lo_u32 v48, v65, s16
	v_ashrrev_i32_e32 v49, 31, v48
	v_lshl_add_u64 v[48:49], s[26:27], 0, v[48:49]
	v_lshl_add_u64 v[48:49], v[62:63], 2, v[48:49]
	s_waitcnt lgkmcnt(0)
	v_add_f32_e32 v50, v50, v51
	ds_bpermute_b32 v51, v104, v50
	v_pk_mul_f32 v[52:53], v[76:77], v[150:151]
	v_pk_mul_f32 v[54:55], v[74:75], v[148:149]
	v_pk_add_f32 v[66:67], v[182:183], 1.0 op_sel_hi:[1,0]
	v_pk_add_f32 v[68:69], v[180:181], 1.0 op_sel_hi:[1,0]
	v_pk_mul_f32 v[52:53], v[52:53], v[66:67]
	v_pk_mul_f32 v[54:55], v[54:55], v[68:69]
	v_and_b32_sdwa v67, v53, v170 dst_sel:DWORD dst_unused:UNUSED_PAD src0_sel:WORD_1 src1_sel:DWORD
	v_and_b32_sdwa v68, v55, v170 dst_sel:DWORD dst_unused:UNUSED_PAD src0_sel:WORD_1 src1_sel:DWORD
	v_and_b32_sdwa v65, v52, v170 dst_sel:DWORD dst_unused:UNUSED_PAD src0_sel:WORD_1 src1_sel:DWORD
	v_and_b32_sdwa v66, v54, v170 dst_sel:DWORD dst_unused:UNUSED_PAD src0_sel:WORD_1 src1_sel:DWORD
	v_add3_u32 v53, v53, v67, s56
	v_add3_u32 v55, v55, v68, s56
	v_add3_u32 v54, v54, v66, s56
	v_add3_u32 v52, v52, v65, s56
	v_and_b32_e32 v53, 0xffff0000, v53
	v_and_b32_e32 v55, 0xffff0000, v55
	v_or_b32_sdwa v53, v53, v52 dst_sel:DWORD dst_unused:UNUSED_PAD src0_sel:DWORD src1_sel:WORD_1
	v_or_b32_sdwa v52, v55, v54 dst_sel:DWORD dst_unused:UNUSED_PAD src0_sel:DWORD src1_sel:WORD_1
	global_store_dwordx2 v[92:93], v[52:53], off offset:96
	s_and_saveexec_b64 s[24:25], s[36:37]
	s_cbranch_execz .LBB0_95
	s_waitcnt lgkmcnt(0)
	v_add_f32_e32 v50, v50, v51
	global_store_dword v[48:49], v50, off

.LBB0_106:
	s_add_i32 s29, s44, 2
	ds_read_b128 v[136:139], v111 offset:16384
	ds_read_b128 v[140:143], v111 offset:18432
	ds_read_b128 v[144:147], v111 offset:20480
	ds_read_b128 v[148:151], v111 offset:22528
	ds_read_b128 v[116:119], v110
	s_add_i32 s44, s44, 4
	ds_read_b128 v[120:123], v110 offset:2048
	s_min_u32 s44, s44, 15
	s_lshl_b32 s92, s44, 7
	ds_read_b128 v[124:127], v110 offset:4096
	ds_read_b128 v[194:197], v113 offset:16384
	ds_read_b128 v[198:201], v113 offset:18432
	ds_read_b128 v[202:205], v113 offset:20480
	ds_read_b128 v[206:209], v113 offset:22528
	v_lshl_add_u64 v[164:165], v[100:101], 0, s[92:93]
	ds_read_b128 v[132:135], v110 offset:6144
	ds_read_b128 v[152:155], v112
	ds_read_b128 v[156:159], v112 offset:2048
	ds_read_b128 v[160:163], v112 offset:4096
	ds_read_b128 v[190:193], v112 offset:6144
	s_waitcnt lgkmcnt(11)
	v_mfma_f32_16x16x32_bf16 v[92:95], v[136:139], v[116:119], v[92:95]
	v_mfma_f32_16x16x32_bf16 v[88:91], v[140:143], v[116:119], v[88:91]
	v_mfma_f32_16x16x32_bf16 v[56:59], v[144:147], v[116:119], v[56:59]
	v_mfma_f32_16x16x32_bf16 v[48:51], v[148:151], v[116:119], v[48:51]
	global_load_dwordx4 v[116:119], v[164:165], off
	s_waitcnt vmcnt(6)
	ds_write_b128 v109, v[52:55] offset:32768
	v_add_co_u32_e32 v52, vcc, s11, v164
	s_waitcnt lgkmcnt(11)
	v_mfma_f32_16x16x32_bf16 v[44:47], v[136:139], v[120:123], v[44:47]
	v_addc_co_u32_e32 v53, vcc, 0, v165, vcc
	v_mfma_f32_16x16x32_bf16 v[40:43], v[140:143], v[120:123], v[40:43]
	v_mfma_f32_16x16x32_bf16 v[36:39], v[144:147], v[120:123], v[36:39]
	v_mfma_f32_16x16x32_bf16 v[32:35], v[148:151], v[120:123], v[32:35]
	global_load_dwordx4 v[120:123], v[52:53], off
	v_add_co_u32_e32 v52, vcc, s33, v164
	ds_write_b128 v109, v[60:63] offset:36864
	s_nop 0
	v_addc_co_u32_e32 v53, vcc, 0, v165, vcc
	s_waitcnt lgkmcnt(11)
	v_mfma_f32_16x16x32_bf16 v[28:31], v[136:139], v[124:127], v[28:31]
	v_mfma_f32_16x16x32_bf16 v[24:27], v[140:143], v[124:127], v[24:27]
	v_mfma_f32_16x16x32_bf16 v[20:23], v[144:147], v[124:127], v[20:23]
	v_mfma_f32_16x16x32_bf16 v[16:19], v[148:151], v[124:127], v[16:19]
	global_load_dwordx4 v[124:127], v[52:53], off
	v_add_co_u32_e32 v52, vcc, s59, v164
	ds_write_b128 v109, v[64:67] offset:40960
	s_nop 0
	v_addc_co_u32_e32 v53, vcc, 0, v165, vcc
	v_lshl_add_u64 v[64:65], v[102:103], 0, s[92:93]
	v_add_co_u32_e32 v66, vcc, s11, v64
	s_waitcnt lgkmcnt(7)
	v_mfma_f32_16x16x32_bf16 v[12:15], v[136:139], v[132:135], v[12:15]
	v_addc_co_u32_e32 v67, vcc, 0, v65, vcc
	v_mfma_f32_16x16x32_bf16 v[8:11], v[140:143], v[132:135], v[8:11]
	v_mfma_f32_16x16x32_bf16 v[4:7], v[144:147], v[132:135], v[4:7]
	v_mfma_f32_16x16x32_bf16 v[0:3], v[148:151], v[132:135], v[0:3]
	global_load_dwordx4 v[132:135], v[52:53], off
	s_waitcnt vmcnt(7)
	ds_write_b128 v109, v[72:75] offset:45056
	s_waitcnt lgkmcnt(7)
	v_mfma_f32_16x16x32_bf16 v[52:55], v[194:197], v[152:155], v[92:95]
	v_mfma_f32_16x16x32_bf16 v[60:63], v[198:201], v[152:155], v[88:91]
	v_mfma_f32_16x16x32_bf16 v[56:59], v[202:205], v[152:155], v[56:59]
	v_mfma_f32_16x16x32_bf16 v[48:51], v[206:209], v[152:155], v[48:51]
	global_load_dwordx4 v[136:139], v[64:65], off
	ds_write_b128 v109, v[68:71] offset:49152
	s_waitcnt lgkmcnt(7)
	v_mfma_f32_16x16x32_bf16 v[44:47], v[194:197], v[156:159], v[44:47]
	v_mfma_f32_16x16x32_bf16 v[40:43], v[198:201], v[156:159], v[40:43]
	v_mfma_f32_16x16x32_bf16 v[36:39], v[202:205], v[156:159], v[36:39]
	v_mfma_f32_16x16x32_bf16 v[32:35], v[206:209], v[156:159], v[32:35]
	global_load_dwordx4 v[140:143], v[66:67], off
	v_add_co_u32_e32 v66, vcc, s33, v64
	s_waitcnt vmcnt(8)
	ds_write_b128 v109, v[76:79] offset:53248
	v_addc_co_u32_e32 v67, vcc, 0, v65, vcc
	v_add_co_u32_e32 v64, vcc, s59, v64
	s_waitcnt lgkmcnt(7)
	v_mfma_f32_16x16x32_bf16 v[28:31], v[194:197], v[160:163], v[28:31]
	v_addc_co_u32_e32 v65, vcc, 0, v65, vcc
	v_mfma_f32_16x16x32_bf16 v[24:27], v[198:201], v[160:163], v[24:27]
	v_mfma_f32_16x16x32_bf16 v[20:23], v[202:205], v[160:163], v[20:23]
	v_mfma_f32_16x16x32_bf16 v[16:19], v[206:209], v[160:163], v[16:19]
	global_load_dwordx4 v[144:147], v[66:67], off
	s_waitcnt vmcnt(8)
	ds_write_b128 v109, v[80:83] offset:57344
	s_waitcnt lgkmcnt(7)
	v_mfma_f32_16x16x32_bf16 v[12:15], v[194:197], v[190:193], v[12:15]
	v_mfma_f32_16x16x32_bf16 v[8:11], v[198:201], v[190:193], v[8:11]
	v_mfma_f32_16x16x32_bf16 v[4:7], v[202:205], v[190:193], v[4:7]
	v_mfma_f32_16x16x32_bf16 v[0:3], v[206:209], v[190:193], v[0:3]
	global_load_dwordx4 v[148:151], v[64:65], off
	s_waitcnt vmcnt(8)
	ds_write_b128 v109, v[84:87] offset:61440
	s_waitcnt lgkmcnt(0)
	s_barrier
	ds_read_b128 v[84:87], v111 offset:51200
	ds_read_b128 v[80:83], v111 offset:49152
	ds_read_b128 v[88:91], v111 offset:53248
	ds_read_b128 v[92:95], v111 offset:55296
	ds_read_b128 v[64:67], v110 offset:32768
	s_min_u32 s44, s29, 12
	s_lshl_b32 s92, s44, 7
	ds_read_b128 v[68:71], v110 offset:34816
	v_lshl_add_u64 v[164:165], v[100:101], 0, s[92:93]
	ds_read_b128 v[72:75], v110 offset:36864
	ds_read_b128 v[76:79], v110 offset:38912
	ds_read_b128 v[152:155], v112 offset:32768
	ds_read_b128 v[156:159], v112 offset:34816
	ds_read_b128 v[160:163], v112 offset:36864
	ds_read_b128 v[190:193], v112 offset:38912
	ds_read_b128 v[194:197], v113 offset:49152
	ds_read_b128 v[198:201], v113 offset:51200
	ds_read_b128 v[202:205], v113 offset:53248
	ds_read_b128 v[206:209], v113 offset:55296
	s_waitcnt lgkmcnt(11)
	v_mfma_f32_16x16x32_bf16 v[214:217], v[84:87], v[64:67], v[60:63]
	v_mfma_f32_16x16x32_bf16 v[210:213], v[80:83], v[64:67], v[52:55]
	s_nop 1
	v_add_co_u32_e32 v60, vcc, s11, v164
	s_nop 1
	v_addc_co_u32_e32 v61, vcc, 0, v165, vcc
	v_mfma_f32_16x16x32_bf16 v[56:59], v[88:91], v[64:67], v[56:59]
	v_mfma_f32_16x16x32_bf16 v[48:51], v[92:95], v[64:67], v[48:51]
	v_add_co_u32_e32 v64, vcc, s33, v164
	global_load_dwordx4 v[52:55], v[164:165], off offset:384
	s_nop 0
	v_addc_co_u32_e32 v65, vcc, 0, v165, vcc
	s_waitcnt vmcnt(8)
	ds_write_b128 v109, v[116:119]
	s_waitcnt lgkmcnt(11)
	v_mfma_f32_16x16x32_bf16 v[44:47], v[80:83], v[68:71], v[44:47]
	v_mfma_f32_16x16x32_bf16 v[40:43], v[84:87], v[68:71], v[40:43]
	v_mfma_f32_16x16x32_bf16 v[36:39], v[88:91], v[68:71], v[36:39]
	v_mfma_f32_16x16x32_bf16 v[32:35], v[92:95], v[68:71], v[32:35]
	v_add_co_u32_e32 v68, vcc, s59, v164
	global_load_dwordx4 v[60:63], v[60:61], off offset:384
	s_waitcnt vmcnt(8)
	ds_write_b128 v109, v[120:123] offset:4096
	s_waitcnt lgkmcnt(11)
	v_mfma_f32_16x16x32_bf16 v[28:31], v[80:83], v[72:75], v[28:31]
	v_addc_co_u32_e32 v69, vcc, 0, v165, vcc
	v_mfma_f32_16x16x32_bf16 v[24:27], v[84:87], v[72:75], v[24:27]
	v_mfma_f32_16x16x32_bf16 v[20:23], v[88:91], v[72:75], v[20:23]
	v_mfma_f32_16x16x32_bf16 v[16:19], v[92:95], v[72:75], v[16:19]
	global_load_dwordx4 v[64:67], v[64:65], off offset:384
	s_waitcnt vmcnt(8)
	ds_write_b128 v109, v[124:127] offset:8192
	s_waitcnt lgkmcnt(11)
	v_mfma_f32_16x16x32_bf16 v[8:11], v[84:87], v[76:79], v[8:11]
	v_lshl_add_u64 v[84:85], v[102:103], 0, s[92:93]
	v_mfma_f32_16x16x32_bf16 v[12:15], v[80:83], v[76:79], v[12:15]
	v_mfma_f32_16x16x32_bf16 v[4:7], v[88:91], v[76:79], v[4:7]
	v_mfma_f32_16x16x32_bf16 v[0:3], v[92:95], v[76:79], v[0:3]
	v_add_co_u32_e32 v76, vcc, s11, v84
	global_load_dwordx4 v[72:75], v[68:69], off offset:384
	s_nop 0
	v_addc_co_u32_e32 v77, vcc, 0, v85, vcc
	v_add_co_u32_e32 v80, vcc, s33, v84
	s_waitcnt vmcnt(8)
	ds_write_b128 v109, v[132:135] offset:12288
	v_addc_co_u32_e32 v81, vcc, 0, v85, vcc
	s_waitcnt lgkmcnt(7)
	v_mfma_f32_16x16x32_bf16 v[92:95], v[194:197], v[152:155], v[210:213]
	s_waitcnt lgkmcnt(6)
	v_mfma_f32_16x16x32_bf16 v[88:91], v[198:201], v[152:155], v[214:217]
	s_waitcnt lgkmcnt(5)
	v_mfma_f32_16x16x32_bf16 v[56:59], v[202:205], v[152:155], v[56:59]
	s_waitcnt lgkmcnt(4)
	v_mfma_f32_16x16x32_bf16 v[48:51], v[206:209], v[152:155], v[48:51]
	global_load_dwordx4 v[68:71], v[84:85], off offset:384
	v_add_co_u32_e32 v84, vcc, s59, v84
	s_waitcnt vmcnt(8)
	ds_write_b128 v109, v[136:139] offset:16384
	v_addc_co_u32_e32 v85, vcc, 0, v85, vcc
	v_mfma_f32_16x16x32_bf16 v[44:47], v[194:197], v[156:159], v[44:47]
	v_mfma_f32_16x16x32_bf16 v[40:43], v[198:201], v[156:159], v[40:43]
	v_mfma_f32_16x16x32_bf16 v[36:39], v[202:205], v[156:159], v[36:39]
	v_mfma_f32_16x16x32_bf16 v[32:35], v[206:209], v[156:159], v[32:35]
	global_load_dwordx4 v[76:79], v[76:77], off offset:384
	s_waitcnt vmcnt(8)
	ds_write_b128 v109, v[140:143] offset:20480
	v_mfma_f32_16x16x32_bf16 v[28:31], v[194:197], v[160:163], v[28:31]
	v_mfma_f32_16x16x32_bf16 v[24:27], v[198:201], v[160:163], v[24:27]
	v_mfma_f32_16x16x32_bf16 v[20:23], v[202:205], v[160:163], v[20:23]
	v_mfma_f32_16x16x32_bf16 v[16:19], v[206:209], v[160:163], v[16:19]
	global_load_dwordx4 v[80:83], v[80:81], off offset:384
	s_waitcnt vmcnt(8)
	ds_write_b128 v109, v[144:147] offset:24576
	v_mfma_f32_16x16x32_bf16 v[12:15], v[194:197], v[190:193], v[12:15]
	v_mfma_f32_16x16x32_bf16 v[8:11], v[198:201], v[190:193], v[8:11]
	v_mfma_f32_16x16x32_bf16 v[4:7], v[202:205], v[190:193], v[4:7]
	v_mfma_f32_16x16x32_bf16 v[0:3], v[206:209], v[190:193], v[0:3]
	global_load_dwordx4 v[84:87], v[84:85], off offset:384
	s_waitcnt vmcnt(8)
	ds_write_b128 v109, v[148:151] offset:28672
	s_cmp_lt_u32 s29, 14
	s_mov_b32 s44, s29
	s_waitcnt lgkmcnt(0)
	s_barrier
	s_cbranch_scc1 .LBB0_106
	s_waitcnt vmcnt(5)
	v_add_u32_e32 v64, s24, v108
	v_add_u32_e32 v52, 0xffffe000, v64
	v_or_b32_e32 v62, v64, v107
	v_lshrrev_b32_e32 v52, 10, v52
	s_movk_i32 s16, 0x1800
	v_mad_u32_u24 v52, v52, s16, s16
	v_cmp_lt_i32_e32 vcc, s13, v62
	v_or_b32_e32 v65, s25, v114
	v_or_b32_e32 v54, v65, v115
	v_cndmask_b32_e32 v52, 0, v52, vcc
	v_ashrrev_i32_e32 v53, 31, v52
	s_waitcnt vmcnt(4)
	v_lshlrev_b64 v[74:75], 2, v[52:53]
	v_ashrrev_i32_e32 v55, 31, v54
	v_ashrrev_i32_e32 v63, 31, v62
	v_lshl_add_u64 v[52:53], s[40:41], 0, v[74:75]
	v_lshlrev_b64 v[60:61], 2, v[54:55]
	v_readlane_b32 s16, v250, 15
	s_waitcnt vmcnt(1)
	v_lshl_add_u64 v[82:83], v[52:53], 0, v[60:61]
	v_lshlrev_b64 v[52:53], 12, v[62:63]
	v_readlane_b32 s17, v250, 16
	v_lshl_add_u64 v[74:75], s[42:43], 0, v[74:75]
	s_waitcnt vmcnt(0)
	v_lshl_add_u64 v[86:87], v[74:75], 0, v[60:61]
	v_lshl_add_u64 v[52:53], s[16:17], 0, v[52:53]
	v_lshl_add_u64 v[84:85], v[52:53], 0, v[60:61]
	global_load_dwordx4 v[66:69], v[82:83], off
	global_load_dwordx4 v[70:73], v[84:85], off
	v_lshl_add_u64 v[52:53], s[0:1], 0, v[60:61]
	v_readlane_b32 s16, v250, 21
	v_lshlrev_b64 v[78:79], 11, v[62:63]
	v_readlane_b32 s17, v250, 22
	s_waitcnt vmcnt(0)
	v_pk_fma_f32 v[68:69], v[94:95], v[68:69], v[72:73]
	v_pk_fma_f32 v[66:67], v[92:93], v[66:67], v[70:71]
	global_store_dwordx4 v[84:85], v[66:69], off
	global_load_dwordx4 v[70:73], v[52:53], off
	global_load_dwordx4 v[74:77], v[86:87], off
	v_lshl_add_u64 v[78:79], s[16:17], 0, v[78:79]
	v_lshl_add_u64 v[92:93], v[54:55], 1, v[78:79]
	s_mov_b32 s16, 0xa000
	s_waitcnt vmcnt(1)
	v_pk_mul_f32 v[72:73], v[68:69], v[72:73]
	v_pk_mul_f32 v[70:71], v[66:67], v[70:71]
	s_waitcnt vmcnt(0)
	v_pk_add_f32 v[76:77], v[76:77], 1.0 op_sel_hi:[1,0]
	v_pk_add_f32 v[74:75], v[74:75], 1.0 op_sel_hi:[1,0]
	v_pk_mul_f32 v[72:73], v[72:73], v[76:77]
	v_pk_mul_f32 v[70:71], v[70:71], v[74:75]
	v_and_b32_sdwa v76, v73, v170 dst_sel:DWORD dst_unused:UNUSED_PAD src0_sel:WORD_1 src1_sel:DWORD
	v_and_b32_sdwa v77, v71, v170 dst_sel:DWORD dst_unused:UNUSED_PAD src0_sel:WORD_1 src1_sel:DWORD
	v_and_b32_sdwa v74, v72, v170 dst_sel:DWORD dst_unused:UNUSED_PAD src0_sel:WORD_1 src1_sel:DWORD
	v_and_b32_sdwa v75, v70, v170 dst_sel:DWORD dst_unused:UNUSED_PAD src0_sel:WORD_1 src1_sel:DWORD
	v_add3_u32 v73, v73, v76, s56
	v_add3_u32 v71, v71, v77, s56
	v_add3_u32 v70, v70, v75, s56
	v_add3_u32 v72, v72, v74, s56
	v_and_b32_e32 v73, 0xffff0000, v73
	v_and_b32_e32 v74, 0xffff0000, v71
	v_or_b32_sdwa v71, v73, v72 dst_sel:DWORD dst_unused:UNUSED_PAD src0_sel:DWORD src1_sel:WORD_1
	v_or_b32_sdwa v70, v74, v70 dst_sel:DWORD dst_unused:UNUSED_PAD src0_sel:DWORD src1_sel:WORD_1
	global_store_dwordx2 v[92:93], v[70:71], off
	global_load_dwordx4 v[70:73], v[82:83], off offset:64
	s_nop 0
	global_load_dwordx4 v[74:77], v[84:85], off offset:64
	s_waitcnt vmcnt(0)
	v_pk_fma_f32 v[72:73], v[90:91], v[72:73], v[76:77]
	v_pk_fma_f32 v[70:71], v[88:89], v[70:71], v[74:75]
	global_store_dwordx4 v[84:85], v[70:73], off offset:64
	global_load_dwordx4 v[74:77], v[52:53], off offset:64
	global_load_dwordx4 v[78:81], v[86:87], off offset:64
	s_waitcnt vmcnt(1)
	v_pk_mul_f32 v[76:77], v[72:73], v[76:77]
	v_pk_mul_f32 v[74:75], v[70:71], v[74:75]
	s_waitcnt vmcnt(0)
	v_pk_add_f32 v[80:81], v[80:81], 1.0 op_sel_hi:[1,0]
	v_pk_add_f32 v[78:79], v[78:79], 1.0 op_sel_hi:[1,0]
	v_pk_mul_f32 v[76:77], v[76:77], v[80:81]
	v_pk_mul_f32 v[74:75], v[74:75], v[78:79]
	v_and_b32_sdwa v80, v77, v170 dst_sel:DWORD dst_unused:UNUSED_PAD src0_sel:WORD_1 src1_sel:DWORD
	v_and_b32_sdwa v81, v75, v170 dst_sel:DWORD dst_unused:UNUSED_PAD src0_sel:WORD_1 src1_sel:DWORD
	v_and_b32_sdwa v78, v76, v170 dst_sel:DWORD dst_unused:UNUSED_PAD src0_sel:WORD_1 src1_sel:DWORD
	v_and_b32_sdwa v79, v74, v170 dst_sel:DWORD dst_unused:UNUSED_PAD src0_sel:WORD_1 src1_sel:DWORD
	v_add3_u32 v77, v77, v80, s56
	v_add3_u32 v75, v75, v81, s56
	v_add3_u32 v74, v74, v79, s56
	v_add3_u32 v76, v76, v78, s56
	v_and_b32_e32 v77, 0xffff0000, v77
	v_and_b32_e32 v78, 0xffff0000, v75
	v_or_b32_sdwa v75, v77, v76 dst_sel:DWORD dst_unused:UNUSED_PAD src0_sel:DWORD src1_sel:WORD_1
	v_or_b32_sdwa v74, v78, v74 dst_sel:DWORD dst_unused:UNUSED_PAD src0_sel:DWORD src1_sel:WORD_1
	global_store_dwordx2 v[92:93], v[74:75], off offset:32
	global_load_dwordx4 v[74:77], v[82:83], off offset:128
	s_nop 0
	global_load_dwordx4 v[78:81], v[84:85], off offset:128
	s_waitcnt vmcnt(0)
	v_pk_fma_f32 v[58:59], v[58:59], v[76:77], v[80:81]
	v_pk_fma_f32 v[56:57], v[56:57], v[74:75], v[78:79]
	global_store_dwordx4 v[84:85], v[56:59], off offset:128
	global_load_dwordx4 v[74:77], v[52:53], off offset:128
	global_load_dwordx4 v[78:81], v[86:87], off offset:128
	s_waitcnt vmcnt(1)
	v_pk_mul_f32 v[76:77], v[58:59], v[76:77]
	v_pk_mul_f32 v[74:75], v[56:57], v[74:75]
	s_waitcnt vmcnt(0)
	v_pk_add_f32 v[80:81], v[80:81], 1.0 op_sel_hi:[1,0]
	v_pk_add_f32 v[78:79], v[78:79], 1.0 op_sel_hi:[1,0]
	v_pk_mul_f32 v[76:77], v[76:77], v[80:81]
	v_pk_mul_f32 v[74:75], v[74:75], v[78:79]
	v_and_b32_sdwa v80, v77, v170 dst_sel:DWORD dst_unused:UNUSED_PAD src0_sel:WORD_1 src1_sel:DWORD
	v_and_b32_sdwa v81, v75, v170 dst_sel:DWORD dst_unused:UNUSED_PAD src0_sel:WORD_1 src1_sel:DWORD
	v_and_b32_sdwa v78, v76, v170 dst_sel:DWORD dst_unused:UNUSED_PAD src0_sel:WORD_1 src1_sel:DWORD
	v_and_b32_sdwa v79, v74, v170 dst_sel:DWORD dst_unused:UNUSED_PAD src0_sel:WORD_1 src1_sel:DWORD
	v_add3_u32 v77, v77, v80, s56
	v_add3_u32 v75, v75, v81, s56
	v_add3_u32 v74, v74, v79, s56
	v_add3_u32 v76, v76, v78, s56
	v_and_b32_e32 v77, 0xffff0000, v77
	v_and_b32_e32 v78, 0xffff0000, v75
	v_or_b32_sdwa v75, v77, v76 dst_sel:DWORD dst_unused:UNUSED_PAD src0_sel:DWORD src1_sel:WORD_1
	v_or_b32_sdwa v74, v78, v74 dst_sel:DWORD dst_unused:UNUSED_PAD src0_sel:DWORD src1_sel:WORD_1
	global_store_dwordx2 v[92:93], v[74:75], off offset:64
	global_load_dwordx4 v[74:77], v[82:83], off offset:192
	s_nop 0
	global_load_dwordx4 v[78:81], v[84:85], off offset:192
	s_waitcnt vmcnt(0)
	v_pk_fma_f32 v[76:77], v[50:51], v[76:77], v[80:81]
	v_pk_fma_f32 v[74:75], v[48:49], v[74:75], v[78:79]
	global_store_dwordx4 v[84:85], v[74:77], off offset:192
	global_load_dwordx4 v[78:81], v[52:53], off offset:192
	s_nop 0
	global_load_dwordx4 v[82:85], v[86:87], off offset:192
	v_mul_f32_e32 v48, v67, v67
	v_mul_f32_e32 v49, v71, v71
	v_fmac_f32_e32 v48, v66, v66
	v_fmac_f32_e32 v49, v70, v70
	v_fmac_f32_e32 v48, v68, v68
	v_fmac_f32_e32 v49, v72, v72
	v_fmac_f32_e32 v48, v69, v69
	v_fmac_f32_e32 v49, v73, v73
	v_add_f32_e32 v48, v48, v49
	v_mul_f32_e32 v49, v57, v57
	v_fmac_f32_e32 v49, v56, v56
	v_fmac_f32_e32 v49, v58, v58
	v_fmac_f32_e32 v49, v59, v59
	v_add_f32_e32 v48, v48, v49
	v_mul_f32_e32 v49, v75, v75
	v_fmac_f32_e32 v49, v74, v74
	v_fmac_f32_e32 v49, v76, v76
	v_fmac_f32_e32 v49, v77, v77
	v_add_f32_e32 v50, v48, v49
	ds_bpermute_b32 v51, v105, v50
	v_lshrrev_b32_e32 v48, 6, v65
	v_mul_lo_u32 v48, v48, s16
	v_ashrrev_i32_e32 v49, 31, v48
	v_lshl_add_u64 v[48:49], s[26:27], 0, v[48:49]
	s_waitcnt lgkmcnt(0)
	v_add_f32_e32 v50, v50, v51
	ds_bpermute_b32 v51, v104, v50
	v_lshl_add_u64 v[48:49], v[62:63], 2, v[48:49]
	s_waitcnt vmcnt(1)
	v_pk_mul_f32 v[56:57], v[76:77], v[80:81]
	v_pk_mul_f32 v[58:59], v[74:75], v[78:79]
	s_waitcnt vmcnt(0)
	v_pk_add_f32 v[66:67], v[84:85], 1.0 op_sel_hi:[1,0]
	v_pk_add_f32 v[68:69], v[82:83], 1.0 op_sel_hi:[1,0]
	v_pk_mul_f32 v[56:57], v[56:57], v[66:67]
	v_pk_mul_f32 v[58:59], v[58:59], v[68:69]
	v_and_b32_sdwa v67, v57, v170 dst_sel:DWORD dst_unused:UNUSED_PAD src0_sel:WORD_1 src1_sel:DWORD
	v_and_b32_sdwa v68, v59, v170 dst_sel:DWORD dst_unused:UNUSED_PAD src0_sel:WORD_1 src1_sel:DWORD
	v_and_b32_sdwa v65, v56, v170 dst_sel:DWORD dst_unused:UNUSED_PAD src0_sel:WORD_1 src1_sel:DWORD
	v_and_b32_sdwa v66, v58, v170 dst_sel:DWORD dst_unused:UNUSED_PAD src0_sel:WORD_1 src1_sel:DWORD
	v_add3_u32 v57, v57, v67, s56
	v_add3_u32 v59, v59, v68, s56
	v_add3_u32 v58, v58, v66, s56
	v_add3_u32 v56, v56, v65, s56
	v_and_b32_e32 v57, 0xffff0000, v57
	v_and_b32_e32 v59, 0xffff0000, v59
	v_or_b32_sdwa v57, v57, v56 dst_sel:DWORD dst_unused:UNUSED_PAD src0_sel:DWORD src1_sel:WORD_1
	v_or_b32_sdwa v56, v59, v58 dst_sel:DWORD dst_unused:UNUSED_PAD src0_sel:DWORD src1_sel:WORD_1
	global_store_dwordx2 v[92:93], v[56:57], off offset:96
	s_and_saveexec_b64 s[24:25], s[36:37]
	s_cbranch_execz .LBB0_109
	s_waitcnt lgkmcnt(0)
	v_add_f32_e32 v50, v50, v51
	global_store_dword v[48:49], v50, off

.LBB0_119:
	s_add_i32 s2, s3, 2
	v_add_u32_e32 v127, v89, v90
	ds_read_b128 v[100:103], v127 offset:16384
	ds_read_b128 v[106:109], v127 offset:18432
	ds_read_b128 v[110:113], v127 offset:20480
	ds_read_b128 v[114:117], v127 offset:22528
	v_add_u32_e32 v126, v88, v90
	ds_read_b128 v[92:95], v126
	ds_read_b128 v[96:99], v126 offset:2048
	s_add_i32 s3, s3, 4
	s_min_u32 s3, s3, 15
	v_add_u32_e32 v128, v88, v91
	v_add_u32_e32 v130, v89, v91
	s_lshl_b32 s92, s3, 7
	ds_read_b128 v[118:121], v130 offset:18432
	ds_read_b128 v[122:125], v130 offset:20480
	ds_read_b128 v[132:135], v130 offset:22528
	s_waitcnt lgkmcnt(4)
	v_mfma_f32_16x16x32_bf16 v[76:79], v[100:103], v[92:95], v[76:79]
	v_lshl_add_u64 v[44:45], v[80:81], 0, s[92:93]
	v_add_co_u32_e32 v46, vcc, s11, v44
	v_mfma_f32_16x16x32_bf16 v[68:71], v[106:109], v[92:95], v[68:71]
	s_nop 0
	v_addc_co_u32_e32 v47, vcc, 0, v45, vcc
	v_mfma_f32_16x16x32_bf16 v[52:55], v[110:113], v[92:95], v[52:55]
	v_mfma_f32_16x16x32_bf16 v[40:43], v[114:117], v[92:95], v[40:43]
	s_waitcnt lgkmcnt(3)
	v_mfma_f32_16x16x32_bf16 v[92:95], v[100:103], v[96:99], v[36:39]
	s_nop 2
	ds_read_b128 v[36:39], v128
	v_mfma_f32_16x16x32_bf16 v[100:103], v[106:109], v[96:99], v[8:11]
	v_mfma_f32_16x16x32_bf16 v[106:109], v[110:113], v[96:99], v[4:7]
	ds_read_b128 v[110:113], v128 offset:2048
	v_mfma_f32_16x16x32_bf16 v[96:99], v[114:117], v[96:99], v[0:3]
	ds_read_b128 v[114:117], v130 offset:16384
	global_load_dwordx4 v[72:75], v[44:45], off
	s_waitcnt vmcnt(1)
	ds_write_b128 v87, v[12:15] offset:53248
	global_load_dwordx4 v[64:67], v[46:47], off
	v_add_co_u32_e32 v46, vcc, s33, v44
	ds_write_b128 v87, v[16:19] offset:49152
	s_nop 0
	v_addc_co_u32_e32 v47, vcc, 0, v45, vcc
	v_add_co_u32_e32 v44, vcc, s59, v44
	global_load_dwordx4 v[60:63], v[46:47], off
	s_nop 0
	v_addc_co_u32_e32 v45, vcc, 0, v45, vcc
	ds_write_b128 v87, v[20:23] offset:45056
	global_load_dwordx4 v[56:59], v[44:45], off
	v_lshl_add_u64 v[44:45], v[82:83], 0, s[92:93]
	ds_write_b128 v87, v[28:31] offset:32768
	s_waitcnt lgkmcnt(4)
	v_mfma_f32_16x16x32_bf16 v[0:3], v[114:117], v[36:39], v[76:79]
	v_mfma_f32_16x16x32_bf16 v[4:7], v[118:121], v[36:39], v[68:71]
	global_load_dwordx4 v[48:51], v[44:45], off
	v_add_co_u32_e32 v44, vcc, s11, v44
	ds_write_b128 v87, v[32:35] offset:36864
	s_nop 0
	v_addc_co_u32_e32 v45, vcc, 0, v45, vcc
	v_mfma_f32_16x16x32_bf16 v[8:11], v[122:125], v[36:39], v[52:55]
	v_mfma_f32_16x16x32_bf16 v[36:39], v[132:135], v[36:39], v[40:43]
	global_load_dwordx4 v[44:47], v[44:45], off
	ds_write_b128 v87, v[24:27] offset:40960
	v_mfma_f32_16x16x32_bf16 v[40:43], v[114:117], v[110:113], v[92:95]
	v_mfma_f32_16x16x32_bf16 v[52:55], v[118:121], v[110:113], v[100:103]
	v_mfma_f32_16x16x32_bf16 v[68:71], v[122:125], v[110:113], v[106:109]
	v_mfma_f32_16x16x32_bf16 v[76:79], v[132:135], v[110:113], v[96:99]
	s_waitcnt lgkmcnt(0)
	s_barrier
	ds_read_b128 v[100:103], v127 offset:49152
	ds_read_b128 v[106:109], v127 offset:51200
	ds_read_b128 v[110:113], v127 offset:53248
	ds_read_b128 v[114:117], v127 offset:55296
	ds_read_b128 v[92:95], v126 offset:32768
	ds_read_b128 v[96:99], v126 offset:34816
	s_min_u32 s3, s2, 12
	s_lshl_b32 s92, s3, 7
	ds_read_b128 v[118:121], v130 offset:51200
	ds_read_b128 v[122:125], v130 offset:53248
	ds_read_b128 v[132:135], v130 offset:55296
	s_waitcnt lgkmcnt(4)
	v_mfma_f32_16x16x32_bf16 v[0:3], v[100:103], v[92:95], v[0:3]
	v_lshl_add_u64 v[12:13], v[80:81], 0, s[92:93]
	v_add_co_u32_e32 v14, vcc, s11, v12
	v_mfma_f32_16x16x32_bf16 v[4:7], v[106:109], v[92:95], v[4:7]
	s_nop 0
	v_addc_co_u32_e32 v15, vcc, 0, v13, vcc
	v_mfma_f32_16x16x32_bf16 v[8:11], v[110:113], v[92:95], v[8:11]
	v_mfma_f32_16x16x32_bf16 v[36:39], v[114:117], v[92:95], v[36:39]
	s_waitcnt lgkmcnt(3)
	v_mfma_f32_16x16x32_bf16 v[92:95], v[100:103], v[96:99], v[40:43]
	s_nop 2
	ds_read_b128 v[40:43], v128 offset:32768
	v_mfma_f32_16x16x32_bf16 v[100:103], v[106:109], v[96:99], v[52:55]
	v_mfma_f32_16x16x32_bf16 v[106:109], v[110:113], v[96:99], v[68:71]
	ds_read_b128 v[110:113], v128 offset:34816
	v_mfma_f32_16x16x32_bf16 v[96:99], v[114:117], v[96:99], v[76:79]
	ds_read_b128 v[114:117], v130 offset:49152
	global_load_dwordx4 v[28:31], v[12:13], off offset:384
	s_waitcnt vmcnt(1)
	ds_write_b128 v87, v[44:47] offset:20480
	global_load_dwordx4 v[32:35], v[14:15], off offset:384
	v_add_co_u32_e32 v14, vcc, s33, v12
	ds_write_b128 v87, v[48:51] offset:16384
	s_nop 0
	v_addc_co_u32_e32 v15, vcc, 0, v13, vcc
	v_add_co_u32_e32 v12, vcc, s59, v12
	global_load_dwordx4 v[24:27], v[14:15], off offset:384
	s_nop 0
	v_addc_co_u32_e32 v13, vcc, 0, v13, vcc
	ds_write_b128 v87, v[56:59] offset:12288
	global_load_dwordx4 v[20:23], v[12:13], off offset:384
	v_lshl_add_u64 v[12:13], v[82:83], 0, s[92:93]
	ds_write_b128 v87, v[72:75]
	s_waitcnt lgkmcnt(4)
	v_mfma_f32_16x16x32_bf16 v[76:79], v[114:117], v[40:43], v[0:3]
	v_mfma_f32_16x16x32_bf16 v[68:71], v[118:121], v[40:43], v[4:7]
	global_load_dwordx4 v[16:19], v[12:13], off offset:384
	v_add_co_u32_e32 v12, vcc, s11, v12
	ds_write_b128 v87, v[64:67] offset:4096
	s_nop 0
	v_addc_co_u32_e32 v13, vcc, 0, v13, vcc
	v_mfma_f32_16x16x32_bf16 v[52:55], v[122:125], v[40:43], v[8:11]
	v_mfma_f32_16x16x32_bf16 v[40:43], v[132:135], v[40:43], v[36:39]
	global_load_dwordx4 v[12:15], v[12:13], off offset:384
	ds_write_b128 v87, v[60:63] offset:8192
	v_mfma_f32_16x16x32_bf16 v[36:39], v[114:117], v[110:113], v[92:95]
	v_mfma_f32_16x16x32_bf16 v[8:11], v[118:121], v[110:113], v[100:103]
	v_mfma_f32_16x16x32_bf16 v[4:7], v[122:125], v[110:113], v[106:109]
	v_mfma_f32_16x16x32_bf16 v[0:3], v[132:135], v[110:113], v[96:99]
	s_cmp_lt_u32 s2, 14
	s_mov_b32 s3, s2
	s_waitcnt lgkmcnt(0)
	s_barrier
	s_cbranch_scc1 .LBB0_119
	v_readlane_b32 s2, v251, 18
	s_waitcnt vmcnt(1)
	s_nop 0
	v_add_u32_e32 v18, s2, v86
	v_readlane_b32 s2, v251, 19
	s_waitcnt vmcnt(0)
	v_add_u32_e32 v13, 0xffffe000, v18
	v_or_b32_e32 v12, v18, v85
	v_lshl_or_b32 v19, v84, 2, s2
	v_lshrrev_b32_e32 v13, 10, v13
	s_movk_i32 s2, 0x1800
	v_mad_u32_u24 v13, v13, s2, s2
	v_cmp_lt_i32_e32 vcc, s13, v12
	v_lshlrev_b32_e32 v128, 2, v19
	v_readlane_b32 s2, v250, 15
	v_cndmask_b32_e32 v14, 0, v13, vcc
	v_ashrrev_i32_e32 v15, 31, v14
	v_lshlrev_b64 v[24:25], 2, v[14:15]
	v_ashrrev_i32_e32 v13, 31, v12
	v_lshl_add_u64 v[14:15], s[40:41], 0, v[24:25]
	v_lshl_add_u64 v[48:49], v[14:15], 0, v[128:129]
	v_lshlrev_b64 v[14:15], 12, v[12:13]
	v_readlane_b32 s3, v250, 16
	v_lshl_add_u64 v[28:29], s[42:43], 0, v[24:25]
	v_lshlrev_b64 v[32:33], 11, v[12:13]
	v_lshl_add_u64 v[14:15], s[2:3], 0, v[14:15]
	v_lshl_add_u64 v[50:51], v[14:15], 0, v[128:129]
	global_load_dwordx4 v[72:75], v[48:49], off
	global_load_dwordx4 v[80:83], v[48:49], off offset:64
	global_load_dwordx4 v[88:91], v[48:49], off offset:128
	global_load_dwordx4 v[136:139], v[48:49], off offset:192
	global_load_dwordx4 v[194:197], v[50:51], off
	global_load_dwordx4 v[198:201], v[50:51], off offset:64
	global_load_dwordx4 v[202:205], v[50:51], off offset:128
	global_load_dwordx4 v[206:209], v[50:51], off offset:192
	v_add_co_u32_e32 v58, vcc, 0x10000, v50
	s_nop 1
	v_addc_co_u32_e32 v59, vcc, 0, v51, vcc
	global_load_dwordx4 v[210:213], v[58:59], off
	global_load_dwordx4 v[214:217], v[58:59], off offset:64
	global_load_dwordx4 v[218:221], v[58:59], off offset:128
	global_load_dwordx4 v[222:225], v[58:59], off offset:192
	v_readlane_b32 s2, v250, 21
	v_readlane_b32 s3, v250, 22
	v_cmp_eq_u32_e32 vcc, 0, v84
	s_waitcnt vmcnt(4)
	v_pk_fma_f32 v[22:23], v[78:79], v[74:75], v[196:197]
	v_pk_fma_f32 v[20:21], v[76:77], v[72:73], v[194:195]
	global_store_dwordx4 v[50:51], v[20:23], off
	v_lshl_add_u64 v[14:15], v[28:29], 0, v[128:129]
	global_load_dwordx4 v[140:143], v128, s[0:1]
	global_load_dwordx4 v[144:147], v128, s[0:1] offset:64
	global_load_dwordx4 v[148:151], v128, s[0:1] offset:128
	global_load_dwordx4 v[152:155], v128, s[0:1] offset:192
	global_load_dwordx4 v[156:159], v[14:15], off
	global_load_dwordx4 v[160:163], v[14:15], off offset:64
	global_load_dwordx4 v[180:183], v[14:15], off offset:128
	global_load_dwordx4 v[190:193], v[14:15], off offset:192
	v_lshlrev_b32_e32 v16, 1, v19
	v_mov_b32_e32 v17, v129
	v_lshl_add_u64 v[32:33], s[2:3], 0, v[32:33]
	v_lshl_add_u64 v[56:57], v[32:33], 0, v[16:17]
	s_waitcnt vmcnt(0)
	v_pk_mul_f32 v[26:27], v[22:23], v[142:143]
	v_pk_mul_f32 v[24:25], v[20:21], v[140:141]
	s_waitcnt vmcnt(0)
	v_pk_add_f32 v[30:31], v[158:159], 1.0 op_sel_hi:[1,0]
	v_pk_add_f32 v[28:29], v[156:157], 1.0 op_sel_hi:[1,0]
	v_pk_mul_f32 v[26:27], v[26:27], v[30:31]
	v_pk_mul_f32 v[24:25], v[24:25], v[28:29]
	v_and_b32_sdwa v19, v26, v170 dst_sel:DWORD dst_unused:UNUSED_PAD src0_sel:WORD_1 src1_sel:DWORD
	v_and_b32_sdwa v29, v27, v170 dst_sel:DWORD dst_unused:UNUSED_PAD src0_sel:WORD_1 src1_sel:DWORD
	v_and_b32_sdwa v30, v25, v170 dst_sel:DWORD dst_unused:UNUSED_PAD src0_sel:WORD_1 src1_sel:DWORD
	v_and_b32_sdwa v28, v24, v170 dst_sel:DWORD dst_unused:UNUSED_PAD src0_sel:WORD_1 src1_sel:DWORD
	v_add3_u32 v19, v26, v19, s56
	v_add3_u32 v26, v27, v29, s56
	v_add3_u32 v25, v25, v30, s56
	v_add3_u32 v24, v24, v28, s56
	v_and_b32_e32 v26, 0xffff0000, v26
	v_and_b32_e32 v27, 0xffff0000, v25
	v_or_b32_sdwa v25, v26, v19 dst_sel:DWORD dst_unused:UNUSED_PAD src0_sel:DWORD src1_sel:WORD_1
	v_or_b32_sdwa v24, v27, v24 dst_sel:DWORD dst_unused:UNUSED_PAD src0_sel:DWORD src1_sel:WORD_1
	global_store_dwordx2 v[56:57], v[24:25], off
	s_nop 0
	s_waitcnt vmcnt(0)
	v_pk_fma_f32 v[26:27], v[70:71], v[82:83], v[200:201]
	v_pk_fma_f32 v[24:25], v[68:69], v[80:81], v[198:199]
	global_store_dwordx4 v[50:51], v[24:27], off offset:64
	v_pk_mul_f32 v[30:31], v[26:27], v[146:147]
	v_pk_mul_f32 v[28:29], v[24:25], v[144:145]
	v_pk_add_f32 v[34:35], v[162:163], 1.0 op_sel_hi:[1,0]
	v_pk_add_f32 v[32:33], v[160:161], 1.0 op_sel_hi:[1,0]
	v_pk_mul_f32 v[30:31], v[30:31], v[34:35]
	v_pk_mul_f32 v[28:29], v[28:29], v[32:33]
	v_and_b32_sdwa v19, v30, v170 dst_sel:DWORD dst_unused:UNUSED_PAD src0_sel:WORD_1 src1_sel:DWORD
	v_and_b32_sdwa v33, v31, v170 dst_sel:DWORD dst_unused:UNUSED_PAD src0_sel:WORD_1 src1_sel:DWORD
	v_and_b32_sdwa v34, v29, v170 dst_sel:DWORD dst_unused:UNUSED_PAD src0_sel:WORD_1 src1_sel:DWORD
	v_and_b32_sdwa v32, v28, v170 dst_sel:DWORD dst_unused:UNUSED_PAD src0_sel:WORD_1 src1_sel:DWORD
	v_add3_u32 v19, v30, v19, s56
	v_add3_u32 v30, v31, v33, s56
	v_add3_u32 v29, v29, v34, s56
	v_add3_u32 v28, v28, v32, s56
	v_and_b32_e32 v30, 0xffff0000, v30
	v_and_b32_e32 v31, 0xffff0000, v29
	v_or_b32_sdwa v29, v30, v19 dst_sel:DWORD dst_unused:UNUSED_PAD src0_sel:DWORD src1_sel:WORD_1
	v_or_b32_sdwa v28, v31, v28 dst_sel:DWORD dst_unused:UNUSED_PAD src0_sel:DWORD src1_sel:WORD_1
	global_store_dwordx2 v[56:57], v[28:29], off offset:32
	s_nop 0
	v_pk_fma_f32 v[30:31], v[54:55], v[90:91], v[204:205]
	v_pk_fma_f32 v[28:29], v[52:53], v[88:89], v[202:203]
	global_store_dwordx4 v[50:51], v[28:31], off offset:128
	v_pk_mul_f32 v[34:35], v[30:31], v[150:151]
	v_pk_mul_f32 v[32:33], v[28:29], v[148:149]
	v_pk_add_f32 v[46:47], v[182:183], 1.0 op_sel_hi:[1,0]
	v_pk_add_f32 v[44:45], v[180:181], 1.0 op_sel_hi:[1,0]
	v_pk_mul_f32 v[34:35], v[34:35], v[46:47]
	v_pk_mul_f32 v[32:33], v[32:33], v[44:45]
	v_and_b32_sdwa v19, v34, v170 dst_sel:DWORD dst_unused:UNUSED_PAD src0_sel:WORD_1 src1_sel:DWORD
	v_and_b32_sdwa v45, v35, v170 dst_sel:DWORD dst_unused:UNUSED_PAD src0_sel:WORD_1 src1_sel:DWORD
	v_and_b32_sdwa v46, v33, v170 dst_sel:DWORD dst_unused:UNUSED_PAD src0_sel:WORD_1 src1_sel:DWORD
	v_and_b32_sdwa v44, v32, v170 dst_sel:DWORD dst_unused:UNUSED_PAD src0_sel:WORD_1 src1_sel:DWORD
	v_add3_u32 v19, v34, v19, s56
	v_add3_u32 v34, v35, v45, s56
	v_add3_u32 v33, v33, v46, s56
	v_add3_u32 v32, v32, v44, s56
	v_and_b32_e32 v34, 0xffff0000, v34
	v_and_b32_e32 v35, 0xffff0000, v33
	v_or_b32_sdwa v33, v34, v19 dst_sel:DWORD dst_unused:UNUSED_PAD src0_sel:DWORD src1_sel:WORD_1
	v_or_b32_sdwa v32, v35, v32 dst_sel:DWORD dst_unused:UNUSED_PAD src0_sel:DWORD src1_sel:WORD_1
	global_store_dwordx2 v[56:57], v[32:33], off offset:64
	s_nop 0
	v_pk_fma_f32 v[34:35], v[42:43], v[138:139], v[208:209]
	v_pk_fma_f32 v[32:33], v[40:41], v[136:137], v[206:207]
	global_store_dwordx4 v[50:51], v[32:35], off offset:192
	v_mul_f32_e32 v14, v21, v21
	v_mul_f32_e32 v15, v25, v25
	v_fmac_f32_e32 v14, v20, v20
	v_fmac_f32_e32 v15, v24, v24
	v_fmac_f32_e32 v14, v22, v22
	v_fmac_f32_e32 v15, v26, v26
	v_fmac_f32_e32 v14, v23, v23
	v_fmac_f32_e32 v15, v27, v27
	v_add_f32_e32 v14, v14, v15
	v_mul_f32_e32 v15, v29, v29
	v_fmac_f32_e32 v15, v28, v28
	v_fmac_f32_e32 v15, v30, v30
	v_fmac_f32_e32 v15, v31, v31
	v_add_f32_e32 v14, v14, v15
	v_mul_f32_e32 v15, v33, v33
	v_fmac_f32_e32 v15, v32, v32
	v_fmac_f32_e32 v15, v34, v34
	v_fmac_f32_e32 v15, v35, v35
	v_add_f32_e32 v14, v14, v15
	ds_bpermute_b32 v15, v105, v14
	s_waitcnt lgkmcnt(0)
	v_add_f32_e32 v14, v14, v15
	ds_bpermute_b32 v15, v104, v14
	v_pk_mul_f32 v[20:21], v[34:35], v[154:155]
	v_pk_mul_f32 v[22:23], v[32:33], v[152:153]
	v_pk_add_f32 v[24:25], v[192:193], 1.0 op_sel_hi:[1,0]
	v_pk_add_f32 v[26:27], v[190:191], 1.0 op_sel_hi:[1,0]
	v_pk_mul_f32 v[20:21], v[20:21], v[24:25]
	v_pk_mul_f32 v[22:23], v[22:23], v[26:27]
	v_and_b32_sdwa v19, v20, v170 dst_sel:DWORD dst_unused:UNUSED_PAD src0_sel:WORD_1 src1_sel:DWORD
	v_and_b32_sdwa v25, v21, v170 dst_sel:DWORD dst_unused:UNUSED_PAD src0_sel:WORD_1 src1_sel:DWORD
	v_and_b32_sdwa v26, v23, v170 dst_sel:DWORD dst_unused:UNUSED_PAD src0_sel:WORD_1 src1_sel:DWORD
	v_and_b32_sdwa v24, v22, v170 dst_sel:DWORD dst_unused:UNUSED_PAD src0_sel:WORD_1 src1_sel:DWORD
	v_add3_u32 v19, v20, v19, s56
	v_add3_u32 v20, v21, v25, s56
	v_add3_u32 v21, v23, v26, s56
	v_add3_u32 v22, v22, v24, s56
	v_and_b32_e32 v20, 0xffff0000, v20
	v_and_b32_e32 v23, 0xffff0000, v21
	v_or_b32_sdwa v21, v20, v19 dst_sel:DWORD dst_unused:UNUSED_PAD src0_sel:DWORD src1_sel:WORD_1
	v_or_b32_sdwa v20, v23, v22 dst_sel:DWORD dst_unused:UNUSED_PAD src0_sel:DWORD src1_sel:WORD_1
	global_store_dwordx2 v[56:57], v[20:21], off offset:96
	s_and_saveexec_b64 s[2:3], vcc
	s_cbranch_execz .LBB0_122
	v_readlane_b32 s16, v253, 20
	s_add_u32 s24, s26, s16
	s_addc_u32 s25, s27, 0
	v_lshl_add_u64 v[20:21], v[12:13], 2, s[24:25]
	s_waitcnt lgkmcnt(0)
	v_add_f32_e32 v13, v14, v15
	global_store_dword v[20:21], v13, off

.LBB0_236:
	s_add_i32 s24, s25, 2
	v_add_u32_e32 v111, v104, v105
	ds_read_b128 v[136:139], v111 offset:16384
	ds_read_b128 v[140:143], v111 offset:18432
	ds_read_b128 v[144:147], v111 offset:20480
	ds_read_b128 v[148:151], v111 offset:22528
	v_add_u32_e32 v110, v103, v105
	ds_read_b128 v[116:119], v110
	s_add_i32 s25, s25, 4
	ds_read_b128 v[120:123], v110 offset:2048
	s_min_u32 s25, s25, 63
	v_add_u32_e32 v113, v104, v114
	s_lshl_b32 s92, s25, 7
	ds_read_b128 v[124:127], v110 offset:4096
	v_add_u32_e32 v112, v103, v114
	ds_read_b128 v[194:197], v113 offset:16384
	ds_read_b128 v[198:201], v113 offset:18432
	ds_read_b128 v[202:205], v113 offset:20480
	ds_read_b128 v[206:209], v113 offset:22528
	v_lshl_add_u64 v[164:165], v[98:99], 0, s[92:93]
	ds_read_b128 v[132:135], v110 offset:6144
	ds_read_b128 v[152:155], v112
	ds_read_b128 v[156:159], v112 offset:2048
	ds_read_b128 v[160:163], v112 offset:4096
	ds_read_b128 v[190:193], v112 offset:6144
	s_waitcnt lgkmcnt(11)
	v_mfma_f32_16x16x32_bf16 v[92:95], v[136:139], v[116:119], v[92:95]
	v_mfma_f32_16x16x32_bf16 v[56:59], v[140:143], v[116:119], v[56:59]
	v_mfma_f32_16x16x32_bf16 v[52:55], v[144:147], v[116:119], v[52:55]
	v_mfma_f32_16x16x32_bf16 v[48:51], v[148:151], v[116:119], v[48:51]
	global_load_dwordx4 v[116:119], v[164:165], off
	s_waitcnt vmcnt(6)
	ds_write_b128 v109, v[60:63] offset:32768
	v_add_co_u32_e32 v60, vcc, s7, v164
	s_waitcnt lgkmcnt(11)
	v_mfma_f32_16x16x32_bf16 v[44:47], v[136:139], v[120:123], v[44:47]
	v_addc_co_u32_e32 v61, vcc, 0, v165, vcc
	v_mfma_f32_16x16x32_bf16 v[40:43], v[140:143], v[120:123], v[40:43]
	v_mfma_f32_16x16x32_bf16 v[36:39], v[144:147], v[120:123], v[36:39]
	v_mfma_f32_16x16x32_bf16 v[32:35], v[148:151], v[120:123], v[32:35]
	global_load_dwordx4 v[120:123], v[60:61], off
	v_add_co_u32_e32 v60, vcc, s52, v164
	ds_write_b128 v109, v[64:67] offset:36864
	s_nop 0
	v_addc_co_u32_e32 v61, vcc, 0, v165, vcc
	s_waitcnt lgkmcnt(11)
	v_mfma_f32_16x16x32_bf16 v[28:31], v[136:139], v[124:127], v[28:31]
	v_lshl_add_u64 v[64:65], v[100:101], 0, s[92:93]
	v_mfma_f32_16x16x32_bf16 v[24:27], v[140:143], v[124:127], v[24:27]
	v_mfma_f32_16x16x32_bf16 v[20:23], v[144:147], v[124:127], v[20:23]
	v_mfma_f32_16x16x32_bf16 v[16:19], v[148:151], v[124:127], v[16:19]
	global_load_dwordx4 v[124:127], v[60:61], off
	v_add_co_u32_e32 v60, vcc, s34, v164
	ds_write_b128 v109, v[68:71] offset:40960
	s_nop 0
	v_addc_co_u32_e32 v61, vcc, 0, v165, vcc
	v_add_co_u32_e32 v66, vcc, s7, v64
	s_waitcnt lgkmcnt(7)
	v_mfma_f32_16x16x32_bf16 v[12:15], v[136:139], v[132:135], v[12:15]
	v_addc_co_u32_e32 v67, vcc, 0, v65, vcc
	v_mfma_f32_16x16x32_bf16 v[8:11], v[140:143], v[132:135], v[8:11]
	v_mfma_f32_16x16x32_bf16 v[4:7], v[144:147], v[132:135], v[4:7]
	v_mfma_f32_16x16x32_bf16 v[0:3], v[148:151], v[132:135], v[0:3]
	global_load_dwordx4 v[132:135], v[60:61], off
	s_waitcnt vmcnt(7)
	ds_write_b128 v109, v[76:79] offset:45056
	s_waitcnt lgkmcnt(7)
	v_mfma_f32_16x16x32_bf16 v[60:63], v[194:197], v[152:155], v[92:95]
	v_mfma_f32_16x16x32_bf16 v[56:59], v[198:201], v[152:155], v[56:59]
	v_mfma_f32_16x16x32_bf16 v[52:55], v[202:205], v[152:155], v[52:55]
	v_mfma_f32_16x16x32_bf16 v[48:51], v[206:209], v[152:155], v[48:51]
	global_load_dwordx4 v[136:139], v[64:65], off
	ds_write_b128 v109, v[72:75] offset:49152
	s_waitcnt lgkmcnt(7)
	v_mfma_f32_16x16x32_bf16 v[44:47], v[194:197], v[156:159], v[44:47]
	v_mfma_f32_16x16x32_bf16 v[40:43], v[198:201], v[156:159], v[40:43]
	v_mfma_f32_16x16x32_bf16 v[36:39], v[202:205], v[156:159], v[36:39]
	v_mfma_f32_16x16x32_bf16 v[32:35], v[206:209], v[156:159], v[32:35]
	global_load_dwordx4 v[140:143], v[66:67], off
	v_add_co_u32_e32 v66, vcc, s52, v64
	s_waitcnt vmcnt(8)
	ds_write_b128 v109, v[80:83] offset:53248
	v_addc_co_u32_e32 v67, vcc, 0, v65, vcc
	v_add_co_u32_e32 v64, vcc, s34, v64
	s_waitcnt lgkmcnt(7)
	v_mfma_f32_16x16x32_bf16 v[28:31], v[194:197], v[160:163], v[28:31]
	v_addc_co_u32_e32 v65, vcc, 0, v65, vcc
	v_mfma_f32_16x16x32_bf16 v[24:27], v[198:201], v[160:163], v[24:27]
	v_mfma_f32_16x16x32_bf16 v[20:23], v[202:205], v[160:163], v[20:23]
	v_mfma_f32_16x16x32_bf16 v[16:19], v[206:209], v[160:163], v[16:19]
	global_load_dwordx4 v[144:147], v[66:67], off
	s_waitcnt vmcnt(8)
	ds_write_b128 v109, v[84:87] offset:57344
	s_waitcnt lgkmcnt(7)
	v_mfma_f32_16x16x32_bf16 v[12:15], v[194:197], v[190:193], v[12:15]
	v_mfma_f32_16x16x32_bf16 v[8:11], v[198:201], v[190:193], v[8:11]
	v_mfma_f32_16x16x32_bf16 v[4:7], v[202:205], v[190:193], v[4:7]
	v_mfma_f32_16x16x32_bf16 v[0:3], v[206:209], v[190:193], v[0:3]
	global_load_dwordx4 v[148:151], v[64:65], off
	s_waitcnt vmcnt(8)
	ds_write_b128 v109, v[88:91] offset:61440
	s_waitcnt lgkmcnt(0)
	s_barrier
	ds_read_b128 v[80:83], v111 offset:49152
	ds_read_b128 v[84:87], v111 offset:51200
	ds_read_b128 v[88:91], v111 offset:53248
	ds_read_b128 v[92:95], v111 offset:55296
	ds_read_b128 v[64:67], v110 offset:32768
	ds_read_b128 v[68:71], v110 offset:34816
	s_min_u32 s25, s24, 60
	s_lshl_b32 s92, s25, 7
	ds_read_b128 v[72:75], v110 offset:36864
	v_lshl_add_u64 v[164:165], v[98:99], 0, s[92:93]
	ds_read_b128 v[76:79], v110 offset:38912
	ds_read_b128 v[152:155], v112 offset:32768
	ds_read_b128 v[156:159], v112 offset:34816
	ds_read_b128 v[160:163], v112 offset:36864
	ds_read_b128 v[190:193], v112 offset:38912
	ds_read_b128 v[194:197], v113 offset:49152
	ds_read_b128 v[198:201], v113 offset:51200
	ds_read_b128 v[202:205], v113 offset:53248
	ds_read_b128 v[206:209], v113 offset:55296
	s_waitcnt lgkmcnt(11)
	v_mfma_f32_16x16x32_bf16 v[210:213], v[80:83], v[64:67], v[60:63]
	v_mfma_f32_16x16x32_bf16 v[56:59], v[84:87], v[64:67], v[56:59]
	v_mfma_f32_16x16x32_bf16 v[52:55], v[88:91], v[64:67], v[52:55]
	v_mfma_f32_16x16x32_bf16 v[48:51], v[92:95], v[64:67], v[48:51]
	v_add_co_u32_e32 v64, vcc, s7, v164
	global_load_dwordx4 v[60:63], v[164:165], off offset:384
	s_nop 0
	v_addc_co_u32_e32 v65, vcc, 0, v165, vcc
	s_waitcnt vmcnt(8)
	ds_write_b128 v109, v[116:119]
	s_waitcnt lgkmcnt(11)
	v_mfma_f32_16x16x32_bf16 v[44:47], v[80:83], v[68:71], v[44:47]
	v_mfma_f32_16x16x32_bf16 v[40:43], v[84:87], v[68:71], v[40:43]
	v_mfma_f32_16x16x32_bf16 v[36:39], v[88:91], v[68:71], v[36:39]
	v_mfma_f32_16x16x32_bf16 v[32:35], v[92:95], v[68:71], v[32:35]
	v_add_co_u32_e32 v68, vcc, s52, v164
	global_load_dwordx4 v[64:67], v[64:65], off offset:384
	s_nop 0
	v_addc_co_u32_e32 v69, vcc, 0, v165, vcc
	s_waitcnt vmcnt(8)
	ds_write_b128 v109, v[120:123] offset:4096
	s_waitcnt lgkmcnt(11)
	v_mfma_f32_16x16x32_bf16 v[28:31], v[80:83], v[72:75], v[28:31]
	v_mfma_f32_16x16x32_bf16 v[24:27], v[84:87], v[72:75], v[24:27]
	v_mfma_f32_16x16x32_bf16 v[20:23], v[88:91], v[72:75], v[20:23]
	v_mfma_f32_16x16x32_bf16 v[16:19], v[92:95], v[72:75], v[16:19]
	v_add_co_u32_e32 v72, vcc, s34, v164
	global_load_dwordx4 v[68:71], v[68:69], off offset:384
	s_waitcnt vmcnt(8)
	ds_write_b128 v109, v[124:127] offset:8192
	s_waitcnt lgkmcnt(11)
	v_mfma_f32_16x16x32_bf16 v[4:7], v[88:91], v[76:79], v[4:7]
	v_addc_co_u32_e32 v73, vcc, 0, v165, vcc
	v_lshl_add_u64 v[88:89], v[100:101], 0, s[92:93]
	v_mfma_f32_16x16x32_bf16 v[12:15], v[80:83], v[76:79], v[12:15]
	v_add_co_u32_e32 v80, vcc, s7, v88
	v_mfma_f32_16x16x32_bf16 v[8:11], v[84:87], v[76:79], v[8:11]
	s_nop 0
	v_addc_co_u32_e32 v81, vcc, 0, v89, vcc
	v_add_co_u32_e32 v84, vcc, s52, v88
	v_mfma_f32_16x16x32_bf16 v[0:3], v[92:95], v[76:79], v[0:3]
	s_nop 0
	v_addc_co_u32_e32 v85, vcc, 0, v89, vcc
	global_load_dwordx4 v[76:79], v[72:73], off offset:384
	s_waitcnt vmcnt(8)
	ds_write_b128 v109, v[132:135] offset:12288
	s_waitcnt lgkmcnt(7)
	v_mfma_f32_16x16x32_bf16 v[92:95], v[194:197], v[152:155], v[210:213]
	s_waitcnt lgkmcnt(6)
	v_mfma_f32_16x16x32_bf16 v[56:59], v[198:201], v[152:155], v[56:59]
	s_waitcnt lgkmcnt(5)
	v_mfma_f32_16x16x32_bf16 v[52:55], v[202:205], v[152:155], v[52:55]
	s_waitcnt lgkmcnt(4)
	v_mfma_f32_16x16x32_bf16 v[48:51], v[206:209], v[152:155], v[48:51]
	global_load_dwordx4 v[72:75], v[88:89], off offset:384
	v_add_co_u32_e32 v88, vcc, s34, v88
	s_waitcnt vmcnt(8)
	ds_write_b128 v109, v[136:139] offset:16384
	v_addc_co_u32_e32 v89, vcc, 0, v89, vcc
	v_mfma_f32_16x16x32_bf16 v[44:47], v[194:197], v[156:159], v[44:47]
	v_mfma_f32_16x16x32_bf16 v[40:43], v[198:201], v[156:159], v[40:43]
	v_mfma_f32_16x16x32_bf16 v[36:39], v[202:205], v[156:159], v[36:39]
	v_mfma_f32_16x16x32_bf16 v[32:35], v[206:209], v[156:159], v[32:35]
	global_load_dwordx4 v[80:83], v[80:81], off offset:384
	s_waitcnt vmcnt(8)
	ds_write_b128 v109, v[140:143] offset:20480
	v_mfma_f32_16x16x32_bf16 v[28:31], v[194:197], v[160:163], v[28:31]
	v_mfma_f32_16x16x32_bf16 v[24:27], v[198:201], v[160:163], v[24:27]
	v_mfma_f32_16x16x32_bf16 v[20:23], v[202:205], v[160:163], v[20:23]
	v_mfma_f32_16x16x32_bf16 v[16:19], v[206:209], v[160:163], v[16:19]
	global_load_dwordx4 v[84:87], v[84:85], off offset:384
	s_waitcnt vmcnt(8)
	ds_write_b128 v109, v[144:147] offset:24576
	v_mfma_f32_16x16x32_bf16 v[12:15], v[194:197], v[190:193], v[12:15]
	v_mfma_f32_16x16x32_bf16 v[8:11], v[198:201], v[190:193], v[8:11]
	v_mfma_f32_16x16x32_bf16 v[4:7], v[202:205], v[190:193], v[4:7]
	v_mfma_f32_16x16x32_bf16 v[0:3], v[206:209], v[190:193], v[0:3]
	global_load_dwordx4 v[88:91], v[88:89], off offset:384
	s_waitcnt vmcnt(8)
	ds_write_b128 v109, v[148:151] offset:28672
	s_cmp_lt_u32 s24, 62
	s_mov_b32 s25, s24
	s_waitcnt lgkmcnt(0)
	s_barrier
	s_cbranch_scc1 .LBB0_236
	s_add_i32 s26, s69, 1
	v_readlane_b32 s16, v251, 5
	s_and_b64 s[24:25], s[8:9], exec
	s_mul_i32 s25, s69, 0x12000
	s_waitcnt vmcnt(2)
	v_add_u32_e32 v80, s16, v108
	v_readlane_b32 s28, v250, 25
	v_add_u32_e32 v60, 0xffffe000, v80
	s_cselect_b32 s24, 3, s26
	v_readlane_b32 s29, v250, 26
	s_add_u32 s25, s28, s25
	v_or_b32_e32 v70, v80, v107
	v_lshlrev_b32_e32 v114, 6, v102
	v_readlane_b32 s16, v251, 6
	v_lshrrev_b32_e32 v60, 10, v60
	s_movk_i32 s5, 0x1800
	s_addc_u32 s26, s29, 0
	v_or_b32_e32 v81, s16, v114
	v_lshlrev_b32_e32 v115, 2, v97
	v_mad_u32_u24 v60, v60, s5, s5
	v_cmp_lt_i32_e32 vcc, s13, v70
	s_add_u32 s40, s25, 0x5000
	v_or_b32_e32 v64, v81, v115
	v_cndmask_b32_e32 v76, 0, v60, vcc
	s_addc_u32 s41, s26, 0
	v_ashrrev_i32_e32 v77, 31, v76
	v_ashrrev_i32_e32 v65, 31, v64
	v_ashrrev_i32_e32 v71, 31, v70
	v_lshl_add_u64 v[60:61], v[76:77], 2, s[40:41]
	v_lshlrev_b64 v[66:67], 2, v[64:65]
	v_readlane_b32 s16, v250, 15
	v_lshl_add_u64 v[74:75], v[60:61], 0, v[66:67]
	v_lshlrev_b64 v[60:61], 12, v[70:71]
	v_readlane_b32 s17, v250, 16
	v_readlane_b32 s68, v250, 41
	s_mul_i32 s25, s24, 0x12000
	v_lshl_add_u64 v[60:61], s[16:17], 0, v[60:61]
	v_lshl_add_u64 v[72:73], v[60:61], 0, v[66:67]
	global_load_dwordx4 v[116:119], v[74:75], off
	global_load_dwordx4 v[120:123], v[74:75], off offset:64
	global_load_dwordx4 v[124:127], v[74:75], off offset:128
	global_load_dwordx4 v[132:135], v[74:75], off offset:192
	global_load_dwordx4 v[190:193], v[72:73], off
	global_load_dwordx4 v[194:197], v[72:73], off offset:64
	global_load_dwordx4 v[198:201], v[72:73], off offset:128
	global_load_dwordx4 v[202:205], v[72:73], off offset:192
	v_add_co_u32_e32 v164, vcc, 0x10000, v72
	s_nop 1
	v_addc_co_u32_e32 v165, vcc, 0, v73, vcc
	v_add_co_u32_e32 v222, vcc, 0x20000, v72
	s_nop 1
	v_addc_co_u32_e32 v223, vcc, 0, v73, vcc
	v_add_co_u32_e32 v224, vcc, 0x30000, v72
	s_nop 1
	v_addc_co_u32_e32 v225, vcc, 0, v73, vcc
	global_load_dwordx4 v[206:209], v[164:165], off
	global_load_dwordx4 v[210:213], v[164:165], off offset:64
	global_load_dwordx4 v[214:217], v[164:165], off offset:128
	global_load_dwordx4 v[218:221], v[164:165], off offset:192
	s_lshl_b32 s24, s24, 12
	v_readlane_b32 s70, v250, 43
	v_readlane_b32 s71, v250, 44
	s_add_u32 s26, s70, s24
	s_addc_u32 s27, s71, 0
	s_add_u32 s24, s28, s25
	s_addc_u32 s25, s29, 0
	s_add_u32 s42, s24, 0x1000
	v_cndmask_b32_e64 v68, 0, 1, s[2:3]
	s_addc_u32 s43, s25, 0
	s_andn2_b64 vcc, exec, s[2:3]
	v_readlane_b32 s2, v250, 21
	s_waitcnt vmcnt(3)
	v_lshlrev_b64 v[86:87], 10, v[70:71]
	v_readlane_b32 s3, v250, 22
	v_cmp_ne_u32_e64 s[36:37], 1, v68
	v_lshl_add_u64 v[68:69], s[26:27], 0, v[66:67]
	v_lshl_add_u64 v[78:79], v[76:77], 2, s[42:43]
	v_lshl_add_u64 v[76:77], v[86:87], 1, s[2:3]
	v_readlane_b32 s69, v250, 42
	v_readlane_b32 s72, v250, 45
	v_readlane_b32 s73, v250, 46
	v_readlane_b32 s74, v250, 47
	v_readlane_b32 s75, v250, 48
	v_readlane_b32 s76, v250, 49
	v_readlane_b32 s77, v250, 50
	v_readlane_b32 s78, v250, 51
	v_readlane_b32 s79, v250, 52
	v_readlane_b32 s80, v250, 53
	v_readlane_b32 s81, v250, 54
	v_readlane_b32 s82, v250, 55
	v_readlane_b32 s83, v250, 56
	s_waitcnt vmcnt(4)
	v_pk_fma_f32 v[62:63], v[94:95], v[118:119], v[192:193]
	v_pk_fma_f32 v[60:61], v[92:93], v[116:117], v[190:191]
	global_store_dwordx4 v[72:73], v[60:63], off
	s_cbranch_vccnz .LBB0_239
	v_lshl_add_u64 v[86:87], v[78:79], 0, v[66:67]
	global_load_dwordx4 v[136:139], v[68:69], off
	global_load_dwordx4 v[140:143], v[68:69], off offset:64
	global_load_dwordx4 v[144:147], v[68:69], off offset:128
	global_load_dwordx4 v[148:151], v[68:69], off offset:192
	s_waitcnt vmcnt(0)
	v_pk_mul_f32 v[84:85], v[62:63], v[138:139]
	global_load_dwordx4 v[152:155], v[86:87], off
	global_load_dwordx4 v[156:159], v[86:87], off offset:64
	global_load_dwordx4 v[160:163], v[86:87], off offset:128
	global_load_dwordx4 v[180:183], v[86:87], off offset:192
	v_pk_mul_f32 v[82:83], v[60:61], v[136:137]
	s_waitcnt vmcnt(0)
	v_pk_add_f32 v[88:89], v[154:155], 1.0 op_sel_hi:[1,0]
	v_pk_add_f32 v[86:87], v[152:153], 1.0 op_sel_hi:[1,0]
	v_pk_mul_f32 v[84:85], v[84:85], v[88:89]
	v_pk_mul_f32 v[82:83], v[82:83], v[86:87]
	v_and_b32_sdwa v88, v84, v170 dst_sel:DWORD dst_unused:UNUSED_PAD src0_sel:WORD_1 src1_sel:DWORD
	v_and_b32_sdwa v89, v82, v170 dst_sel:DWORD dst_unused:UNUSED_PAD src0_sel:WORD_1 src1_sel:DWORD
	v_add3_u32 v82, v82, v89, s56
	v_add3_u32 v84, v84, v88, s56
	v_and_b32_sdwa v88, v85, v170 dst_sel:DWORD dst_unused:UNUSED_PAD src0_sel:WORD_1 src1_sel:DWORD
	v_and_b32_sdwa v89, v83, v170 dst_sel:DWORD dst_unused:UNUSED_PAD src0_sel:WORD_1 src1_sel:DWORD
	v_add3_u32 v85, v85, v88, s56
	v_add3_u32 v83, v83, v89, s56
	v_and_b32_e32 v85, 0xffff0000, v85
	v_and_b32_e32 v88, 0xffff0000, v83
	v_lshl_add_u64 v[86:87], v[64:65], 1, v[76:77]
	v_or_b32_sdwa v83, v85, v84 dst_sel:DWORD dst_unused:UNUSED_PAD src0_sel:DWORD src1_sel:WORD_1
	v_or_b32_sdwa v82, v88, v82 dst_sel:DWORD dst_unused:UNUSED_PAD src0_sel:DWORD src1_sel:WORD_1
	global_store_dwordx2 v[86:87], v[82:83], off

.LBB0_282:
	s_add_i32 s25, s28, 2
	ds_read_b128 v[136:139], v111 offset:16384
	ds_read_b128 v[140:143], v111 offset:18432
	ds_read_b128 v[144:147], v111 offset:20480
	ds_read_b128 v[148:151], v111 offset:22528
	ds_read_b128 v[116:119], v110
	s_add_i32 s28, s28, 4
	ds_read_b128 v[120:123], v110 offset:2048
	s_min_u32 s28, s28, 63
	s_lshl_b32 s92, s28, 7
	ds_read_b128 v[124:127], v110 offset:4096
	ds_read_b128 v[194:197], v113 offset:16384
	ds_read_b128 v[198:201], v113 offset:18432
	ds_read_b128 v[202:205], v113 offset:20480
	ds_read_b128 v[206:209], v113 offset:22528
	v_lshl_add_u64 v[164:165], v[100:101], 0, s[92:93]
	ds_read_b128 v[132:135], v110 offset:6144
	ds_read_b128 v[152:155], v112
	ds_read_b128 v[156:159], v112 offset:2048
	ds_read_b128 v[160:163], v112 offset:4096
	ds_read_b128 v[190:193], v112 offset:6144
	s_waitcnt lgkmcnt(11)
	v_mfma_f32_16x16x32_bf16 v[92:95], v[136:139], v[116:119], v[92:95]
	v_mfma_f32_16x16x32_bf16 v[56:59], v[140:143], v[116:119], v[56:59]
	v_mfma_f32_16x16x32_bf16 v[52:55], v[144:147], v[116:119], v[52:55]
	v_mfma_f32_16x16x32_bf16 v[48:51], v[148:151], v[116:119], v[48:51]
	global_load_dwordx4 v[116:119], v[164:165], off
	s_waitcnt vmcnt(6)
	ds_write_b128 v109, v[60:63] offset:32768
	v_add_co_u32_e32 v60, vcc, s7, v164
	s_waitcnt lgkmcnt(11)
	v_mfma_f32_16x16x32_bf16 v[44:47], v[136:139], v[120:123], v[44:47]
	v_addc_co_u32_e32 v61, vcc, 0, v165, vcc
	v_mfma_f32_16x16x32_bf16 v[40:43], v[140:143], v[120:123], v[40:43]
	v_mfma_f32_16x16x32_bf16 v[36:39], v[144:147], v[120:123], v[36:39]
	v_mfma_f32_16x16x32_bf16 v[32:35], v[148:151], v[120:123], v[32:35]
	global_load_dwordx4 v[120:123], v[60:61], off
	v_add_co_u32_e32 v60, vcc, s52, v164
	ds_write_b128 v109, v[64:67] offset:36864
	s_nop 0
	v_addc_co_u32_e32 v61, vcc, 0, v165, vcc
	s_waitcnt lgkmcnt(11)
	v_mfma_f32_16x16x32_bf16 v[28:31], v[136:139], v[124:127], v[28:31]
	v_lshl_add_u64 v[64:65], v[102:103], 0, s[92:93]
	v_mfma_f32_16x16x32_bf16 v[24:27], v[140:143], v[124:127], v[24:27]
	v_mfma_f32_16x16x32_bf16 v[20:23], v[144:147], v[124:127], v[20:23]
	v_mfma_f32_16x16x32_bf16 v[16:19], v[148:151], v[124:127], v[16:19]
	global_load_dwordx4 v[124:127], v[60:61], off
	v_add_co_u32_e32 v60, vcc, s34, v164
	ds_write_b128 v109, v[68:71] offset:40960
	s_nop 0
	v_addc_co_u32_e32 v61, vcc, 0, v165, vcc
	v_add_co_u32_e32 v66, vcc, s7, v64
	s_waitcnt lgkmcnt(7)
	v_mfma_f32_16x16x32_bf16 v[12:15], v[136:139], v[132:135], v[12:15]
	v_addc_co_u32_e32 v67, vcc, 0, v65, vcc
	v_mfma_f32_16x16x32_bf16 v[8:11], v[140:143], v[132:135], v[8:11]
	v_mfma_f32_16x16x32_bf16 v[4:7], v[144:147], v[132:135], v[4:7]
	v_mfma_f32_16x16x32_bf16 v[0:3], v[148:151], v[132:135], v[0:3]
	global_load_dwordx4 v[132:135], v[60:61], off
	s_waitcnt vmcnt(7)
	ds_write_b128 v109, v[76:79] offset:45056
	s_waitcnt lgkmcnt(7)
	v_mfma_f32_16x16x32_bf16 v[60:63], v[194:197], v[152:155], v[92:95]
	v_mfma_f32_16x16x32_bf16 v[56:59], v[198:201], v[152:155], v[56:59]
	v_mfma_f32_16x16x32_bf16 v[52:55], v[202:205], v[152:155], v[52:55]
	v_mfma_f32_16x16x32_bf16 v[48:51], v[206:209], v[152:155], v[48:51]
	global_load_dwordx4 v[136:139], v[64:65], off
	ds_write_b128 v109, v[72:75] offset:49152
	s_waitcnt lgkmcnt(7)
	v_mfma_f32_16x16x32_bf16 v[44:47], v[194:197], v[156:159], v[44:47]
	v_mfma_f32_16x16x32_bf16 v[40:43], v[198:201], v[156:159], v[40:43]
	v_mfma_f32_16x16x32_bf16 v[36:39], v[202:205], v[156:159], v[36:39]
	v_mfma_f32_16x16x32_bf16 v[32:35], v[206:209], v[156:159], v[32:35]
	global_load_dwordx4 v[140:143], v[66:67], off
	v_add_co_u32_e32 v66, vcc, s52, v64
	s_waitcnt vmcnt(8)
	ds_write_b128 v109, v[80:83] offset:53248
	v_addc_co_u32_e32 v67, vcc, 0, v65, vcc
	v_add_co_u32_e32 v64, vcc, s34, v64
	s_waitcnt lgkmcnt(7)
	v_mfma_f32_16x16x32_bf16 v[28:31], v[194:197], v[160:163], v[28:31]
	v_addc_co_u32_e32 v65, vcc, 0, v65, vcc
	v_mfma_f32_16x16x32_bf16 v[24:27], v[198:201], v[160:163], v[24:27]
	v_mfma_f32_16x16x32_bf16 v[20:23], v[202:205], v[160:163], v[20:23]
	v_mfma_f32_16x16x32_bf16 v[16:19], v[206:209], v[160:163], v[16:19]
	global_load_dwordx4 v[144:147], v[66:67], off
	s_waitcnt vmcnt(8)
	ds_write_b128 v109, v[84:87] offset:57344
	s_waitcnt lgkmcnt(7)
	v_mfma_f32_16x16x32_bf16 v[12:15], v[194:197], v[190:193], v[12:15]
	v_mfma_f32_16x16x32_bf16 v[8:11], v[198:201], v[190:193], v[8:11]
	v_mfma_f32_16x16x32_bf16 v[4:7], v[202:205], v[190:193], v[4:7]
	v_mfma_f32_16x16x32_bf16 v[0:3], v[206:209], v[190:193], v[0:3]
	global_load_dwordx4 v[148:151], v[64:65], off
	s_waitcnt vmcnt(8)
	ds_write_b128 v109, v[88:91] offset:61440
	s_waitcnt lgkmcnt(0)
	s_barrier
	ds_read_b128 v[80:83], v111 offset:49152
	ds_read_b128 v[84:87], v111 offset:51200
	ds_read_b128 v[88:91], v111 offset:53248
	ds_read_b128 v[92:95], v111 offset:55296
	ds_read_b128 v[64:67], v110 offset:32768
	ds_read_b128 v[68:71], v110 offset:34816
	s_min_u32 s28, s25, 60
	s_lshl_b32 s92, s28, 7
	ds_read_b128 v[72:75], v110 offset:36864
	v_lshl_add_u64 v[164:165], v[100:101], 0, s[92:93]
	ds_read_b128 v[76:79], v110 offset:38912
	ds_read_b128 v[152:155], v112 offset:32768
	ds_read_b128 v[156:159], v112 offset:34816
	ds_read_b128 v[160:163], v112 offset:36864
	ds_read_b128 v[190:193], v112 offset:38912
	ds_read_b128 v[194:197], v113 offset:49152
	ds_read_b128 v[198:201], v113 offset:51200
	ds_read_b128 v[202:205], v113 offset:53248
	ds_read_b128 v[206:209], v113 offset:55296
	s_waitcnt lgkmcnt(11)
	v_mfma_f32_16x16x32_bf16 v[210:213], v[80:83], v[64:67], v[60:63]
	v_mfma_f32_16x16x32_bf16 v[56:59], v[84:87], v[64:67], v[56:59]
	v_mfma_f32_16x16x32_bf16 v[52:55], v[88:91], v[64:67], v[52:55]
	v_mfma_f32_16x16x32_bf16 v[48:51], v[92:95], v[64:67], v[48:51]
	v_add_co_u32_e32 v64, vcc, s7, v164
	global_load_dwordx4 v[60:63], v[164:165], off offset:384
	s_nop 0
	v_addc_co_u32_e32 v65, vcc, 0, v165, vcc
	s_waitcnt vmcnt(8)
	ds_write_b128 v109, v[116:119]
	s_waitcnt lgkmcnt(11)
	v_mfma_f32_16x16x32_bf16 v[44:47], v[80:83], v[68:71], v[44:47]
	v_mfma_f32_16x16x32_bf16 v[40:43], v[84:87], v[68:71], v[40:43]
	v_mfma_f32_16x16x32_bf16 v[36:39], v[88:91], v[68:71], v[36:39]
	v_mfma_f32_16x16x32_bf16 v[32:35], v[92:95], v[68:71], v[32:35]
	v_add_co_u32_e32 v68, vcc, s52, v164
	global_load_dwordx4 v[64:67], v[64:65], off offset:384
	s_nop 0
	v_addc_co_u32_e32 v69, vcc, 0, v165, vcc
	s_waitcnt vmcnt(8)
	ds_write_b128 v109, v[120:123] offset:4096
	s_waitcnt lgkmcnt(11)
	v_mfma_f32_16x16x32_bf16 v[28:31], v[80:83], v[72:75], v[28:31]
	v_mfma_f32_16x16x32_bf16 v[24:27], v[84:87], v[72:75], v[24:27]
	v_mfma_f32_16x16x32_bf16 v[20:23], v[88:91], v[72:75], v[20:23]
	v_mfma_f32_16x16x32_bf16 v[16:19], v[92:95], v[72:75], v[16:19]
	v_add_co_u32_e32 v72, vcc, s34, v164
	global_load_dwordx4 v[68:71], v[68:69], off offset:384
	s_waitcnt vmcnt(8)
	ds_write_b128 v109, v[124:127] offset:8192
	s_waitcnt lgkmcnt(11)
	v_mfma_f32_16x16x32_bf16 v[4:7], v[88:91], v[76:79], v[4:7]
	v_addc_co_u32_e32 v73, vcc, 0, v165, vcc
	v_lshl_add_u64 v[88:89], v[102:103], 0, s[92:93]
	v_mfma_f32_16x16x32_bf16 v[12:15], v[80:83], v[76:79], v[12:15]
	v_add_co_u32_e32 v80, vcc, s7, v88
	v_mfma_f32_16x16x32_bf16 v[8:11], v[84:87], v[76:79], v[8:11]
	s_nop 0
	v_addc_co_u32_e32 v81, vcc, 0, v89, vcc
	v_add_co_u32_e32 v84, vcc, s52, v88
	v_mfma_f32_16x16x32_bf16 v[0:3], v[92:95], v[76:79], v[0:3]
	s_nop 0
	v_addc_co_u32_e32 v85, vcc, 0, v89, vcc
	global_load_dwordx4 v[76:79], v[72:73], off offset:384
	s_waitcnt vmcnt(8)
	ds_write_b128 v109, v[132:135] offset:12288
	s_waitcnt lgkmcnt(7)
	v_mfma_f32_16x16x32_bf16 v[92:95], v[194:197], v[152:155], v[210:213]
	s_waitcnt lgkmcnt(6)
	v_mfma_f32_16x16x32_bf16 v[56:59], v[198:201], v[152:155], v[56:59]
	s_waitcnt lgkmcnt(5)
	v_mfma_f32_16x16x32_bf16 v[52:55], v[202:205], v[152:155], v[52:55]
	s_waitcnt lgkmcnt(4)
	v_mfma_f32_16x16x32_bf16 v[48:51], v[206:209], v[152:155], v[48:51]
	global_load_dwordx4 v[72:75], v[88:89], off offset:384
	v_add_co_u32_e32 v88, vcc, s34, v88
	s_waitcnt vmcnt(8)
	ds_write_b128 v109, v[136:139] offset:16384
	v_addc_co_u32_e32 v89, vcc, 0, v89, vcc
	v_mfma_f32_16x16x32_bf16 v[44:47], v[194:197], v[156:159], v[44:47]
	v_mfma_f32_16x16x32_bf16 v[40:43], v[198:201], v[156:159], v[40:43]
	v_mfma_f32_16x16x32_bf16 v[36:39], v[202:205], v[156:159], v[36:39]
	v_mfma_f32_16x16x32_bf16 v[32:35], v[206:209], v[156:159], v[32:35]
	global_load_dwordx4 v[80:83], v[80:81], off offset:384
	s_waitcnt vmcnt(8)
	ds_write_b128 v109, v[140:143] offset:20480
	v_mfma_f32_16x16x32_bf16 v[28:31], v[194:197], v[160:163], v[28:31]
	v_mfma_f32_16x16x32_bf16 v[24:27], v[198:201], v[160:163], v[24:27]
	v_mfma_f32_16x16x32_bf16 v[20:23], v[202:205], v[160:163], v[20:23]
	v_mfma_f32_16x16x32_bf16 v[16:19], v[206:209], v[160:163], v[16:19]
	global_load_dwordx4 v[84:87], v[84:85], off offset:384
	s_waitcnt vmcnt(8)
	ds_write_b128 v109, v[144:147] offset:24576
	v_mfma_f32_16x16x32_bf16 v[12:15], v[194:197], v[190:193], v[12:15]
	v_mfma_f32_16x16x32_bf16 v[8:11], v[198:201], v[190:193], v[8:11]
	v_mfma_f32_16x16x32_bf16 v[4:7], v[202:205], v[190:193], v[4:7]
	v_mfma_f32_16x16x32_bf16 v[0:3], v[206:209], v[190:193], v[0:3]
	global_load_dwordx4 v[88:91], v[88:89], off offset:384
	s_waitcnt vmcnt(8)
	ds_write_b128 v109, v[148:151] offset:28672
	s_cmp_lt_u32 s25, 62
	s_mov_b32 s28, s25
	s_waitcnt lgkmcnt(0)
	s_barrier
	s_cbranch_scc1 .LBB0_282
	s_waitcnt vmcnt(2)
	v_add_u32_e32 v80, s2, v108
	v_add_u32_e32 v60, 0xffffe000, v80
	v_or_b32_e32 v70, v80, v107
	v_lshrrev_b32_e32 v60, 10, v60
	s_movk_i32 s2, 0x1800
	v_or_b32_e32 v81, s3, v114
	v_mad_u32_u24 v60, v60, s2, s2
	v_cmp_lt_i32_e32 vcc, s13, v70
	v_or_b32_e32 v64, v81, v115
	v_ashrrev_i32_e32 v71, 31, v70
	v_cndmask_b32_e32 v82, 0, v60, vcc
	v_readlane_b32 s2, v250, 15
	v_ashrrev_i32_e32 v83, 31, v82
	v_ashrrev_i32_e32 v65, 31, v64
	v_lshlrev_b64 v[68:69], 12, v[70:71]
	v_readlane_b32 s3, v250, 16
	v_lshl_add_u64 v[60:61], v[82:83], 2, s[40:41]
	v_lshlrev_b64 v[66:67], 2, v[64:65]
	v_lshl_add_u64 v[68:69], s[2:3], 0, v[68:69]
	v_lshl_add_u64 v[74:75], v[60:61], 0, v[66:67]
	v_lshl_add_u64 v[72:73], v[68:69], 0, v[66:67]
	global_load_dwordx4 v[60:63], v[74:75], off
	global_load_dwordx4 v[76:79], v[72:73], off
	v_readlane_b32 s2, v250, 21
	s_waitcnt vmcnt(3)
	v_lshlrev_b64 v[84:85], 10, v[70:71]
	v_readlane_b32 s3, v250, 22
	s_and_b64 vcc, exec, s[36:37]
	v_lshl_add_u64 v[68:69], s[26:27], 0, v[66:67]
	s_waitcnt vmcnt(0)
	v_pk_fma_f32 v[62:63], v[94:95], v[62:63], v[78:79]
	v_pk_fma_f32 v[60:61], v[92:93], v[60:61], v[76:77]
	v_lshl_add_u64 v[76:77], v[82:83], 2, s[42:43]
	v_lshl_add_u64 v[78:79], v[84:85], 1, s[2:3]
	global_store_dwordx4 v[72:73], v[60:63], off
	s_cbranch_vccnz .LBB0_285
	v_lshl_add_u64 v[86:87], v[76:77], 0, v[66:67]
	global_load_dwordx4 v[82:85], v[68:69], off
	s_waitcnt vmcnt(0)
	v_pk_mul_f32 v[84:85], v[62:63], v[84:85]
	global_load_dwordx4 v[86:89], v[86:87], off
	v_pk_mul_f32 v[82:83], v[60:61], v[82:83]
	s_waitcnt vmcnt(0)
	v_pk_add_f32 v[88:89], v[88:89], 1.0 op_sel_hi:[1,0]
	v_pk_add_f32 v[86:87], v[86:87], 1.0 op_sel_hi:[1,0]
	v_pk_mul_f32 v[84:85], v[84:85], v[88:89]
	v_pk_mul_f32 v[82:83], v[82:83], v[86:87]
	v_and_b32_sdwa v88, v84, v170 dst_sel:DWORD dst_unused:UNUSED_PAD src0_sel:WORD_1 src1_sel:DWORD
	v_and_b32_sdwa v89, v82, v170 dst_sel:DWORD dst_unused:UNUSED_PAD src0_sel:WORD_1 src1_sel:DWORD
	v_add3_u32 v82, v82, v89, s56
	v_add3_u32 v84, v84, v88, s56
	v_and_b32_sdwa v88, v85, v170 dst_sel:DWORD dst_unused:UNUSED_PAD src0_sel:WORD_1 src1_sel:DWORD
	v_and_b32_sdwa v89, v83, v170 dst_sel:DWORD dst_unused:UNUSED_PAD src0_sel:WORD_1 src1_sel:DWORD
	v_add3_u32 v85, v85, v88, s56
	v_add3_u32 v83, v83, v89, s56
	v_and_b32_e32 v85, 0xffff0000, v85
	v_and_b32_e32 v88, 0xffff0000, v83
	v_lshl_add_u64 v[86:87], v[64:65], 1, v[78:79]
	v_or_b32_sdwa v83, v85, v84 dst_sel:DWORD dst_unused:UNUSED_PAD src0_sel:DWORD src1_sel:WORD_1
	v_or_b32_sdwa v82, v88, v82 dst_sel:DWORD dst_unused:UNUSED_PAD src0_sel:DWORD src1_sel:WORD_1
	global_store_dwordx2 v[86:87], v[82:83], off

.LBB0_327:
	s_add_i32 s0, s1, 2
	v_add_u32_e32 v127, v89, v90
	ds_read_b128 v[100:103], v127 offset:16384
	ds_read_b128 v[106:109], v127 offset:18432
	ds_read_b128 v[110:113], v127 offset:20480
	ds_read_b128 v[114:117], v127 offset:22528
	v_add_u32_e32 v126, v88, v90
	ds_read_b128 v[92:95], v126
	ds_read_b128 v[96:99], v126 offset:2048
	s_add_i32 s1, s1, 4
	s_min_u32 s1, s1, 63
	v_add_u32_e32 v128, v88, v91
	v_add_u32_e32 v130, v89, v91
	s_lshl_b32 s92, s1, 7
	ds_read_b128 v[118:121], v130 offset:18432
	ds_read_b128 v[122:125], v130 offset:20480
	ds_read_b128 v[132:135], v130 offset:22528
	s_waitcnt lgkmcnt(4)
	v_mfma_f32_16x16x32_bf16 v[76:79], v[100:103], v[92:95], v[76:79]
	v_lshl_add_u64 v[48:49], v[80:81], 0, s[92:93]
	v_add_co_u32_e32 v50, vcc, s7, v48
	v_mfma_f32_16x16x32_bf16 v[56:59], v[106:109], v[92:95], v[56:59]
	s_nop 0
	v_addc_co_u32_e32 v51, vcc, 0, v49, vcc
	v_mfma_f32_16x16x32_bf16 v[44:47], v[110:113], v[92:95], v[44:47]
	v_mfma_f32_16x16x32_bf16 v[24:27], v[114:117], v[92:95], v[24:27]
	s_waitcnt lgkmcnt(3)
	v_mfma_f32_16x16x32_bf16 v[92:95], v[100:103], v[96:99], v[12:15]
	s_nop 2
	ds_read_b128 v[12:15], v128
	v_mfma_f32_16x16x32_bf16 v[100:103], v[106:109], v[96:99], v[8:11]
	v_mfma_f32_16x16x32_bf16 v[106:109], v[110:113], v[96:99], v[4:7]
	ds_read_b128 v[110:113], v128 offset:2048
	v_mfma_f32_16x16x32_bf16 v[96:99], v[114:117], v[96:99], v[0:3]
	ds_read_b128 v[114:117], v130 offset:16384
	global_load_dwordx4 v[72:75], v[48:49], off
	s_waitcnt vmcnt(1)
	ds_write_b128 v87, v[16:19] offset:53248
	global_load_dwordx4 v[68:71], v[50:51], off
	v_add_co_u32_e32 v50, vcc, s52, v48
	ds_write_b128 v87, v[20:23] offset:49152
	s_nop 0
	v_addc_co_u32_e32 v51, vcc, 0, v49, vcc
	v_add_co_u32_e32 v48, vcc, s34, v48
	global_load_dwordx4 v[64:67], v[50:51], off
	s_nop 0
	v_addc_co_u32_e32 v49, vcc, 0, v49, vcc
	ds_write_b128 v87, v[28:31] offset:45056
	global_load_dwordx4 v[60:63], v[48:49], off
	v_lshl_add_u64 v[48:49], v[82:83], 0, s[92:93]
	ds_write_b128 v87, v[36:39] offset:32768
	s_waitcnt lgkmcnt(4)
	v_mfma_f32_16x16x32_bf16 v[0:3], v[114:117], v[12:15], v[76:79]
	v_mfma_f32_16x16x32_bf16 v[4:7], v[118:121], v[12:15], v[56:59]
	global_load_dwordx4 v[52:55], v[48:49], off
	v_add_co_u32_e32 v48, vcc, s7, v48
	ds_write_b128 v87, v[40:43] offset:36864
	s_nop 0
	v_addc_co_u32_e32 v49, vcc, 0, v49, vcc
	v_mfma_f32_16x16x32_bf16 v[8:11], v[122:125], v[12:15], v[44:47]
	v_mfma_f32_16x16x32_bf16 v[12:15], v[132:135], v[12:15], v[24:27]
	global_load_dwordx4 v[48:51], v[48:49], off
	ds_write_b128 v87, v[32:35] offset:40960
	v_mfma_f32_16x16x32_bf16 v[24:27], v[114:117], v[110:113], v[92:95]
	v_mfma_f32_16x16x32_bf16 v[44:47], v[118:121], v[110:113], v[100:103]
	v_mfma_f32_16x16x32_bf16 v[56:59], v[122:125], v[110:113], v[106:109]
	v_mfma_f32_16x16x32_bf16 v[76:79], v[132:135], v[110:113], v[96:99]
	s_waitcnt lgkmcnt(0)
	s_barrier
	ds_read_b128 v[100:103], v127 offset:49152
	ds_read_b128 v[106:109], v127 offset:51200
	ds_read_b128 v[110:113], v127 offset:53248
	ds_read_b128 v[114:117], v127 offset:55296
	ds_read_b128 v[92:95], v126 offset:32768
	ds_read_b128 v[96:99], v126 offset:34816
	s_min_u32 s1, s0, 60
	s_lshl_b32 s92, s1, 7
	ds_read_b128 v[118:121], v130 offset:51200
	ds_read_b128 v[122:125], v130 offset:53248
	ds_read_b128 v[132:135], v130 offset:55296
	s_waitcnt lgkmcnt(4)
	v_mfma_f32_16x16x32_bf16 v[0:3], v[100:103], v[92:95], v[0:3]
	v_lshl_add_u64 v[16:17], v[80:81], 0, s[92:93]
	v_add_co_u32_e32 v18, vcc, s7, v16
	v_mfma_f32_16x16x32_bf16 v[4:7], v[106:109], v[92:95], v[4:7]
	s_nop 0
	v_addc_co_u32_e32 v19, vcc, 0, v17, vcc
	v_mfma_f32_16x16x32_bf16 v[8:11], v[110:113], v[92:95], v[8:11]
	v_mfma_f32_16x16x32_bf16 v[12:15], v[114:117], v[92:95], v[12:15]
	s_waitcnt lgkmcnt(3)
	v_mfma_f32_16x16x32_bf16 v[92:95], v[100:103], v[96:99], v[24:27]
	s_nop 2
	ds_read_b128 v[24:27], v128 offset:32768
	v_mfma_f32_16x16x32_bf16 v[100:103], v[106:109], v[96:99], v[44:47]
	v_mfma_f32_16x16x32_bf16 v[106:109], v[110:113], v[96:99], v[56:59]
	ds_read_b128 v[110:113], v128 offset:34816
	v_mfma_f32_16x16x32_bf16 v[96:99], v[114:117], v[96:99], v[76:79]
	ds_read_b128 v[114:117], v130 offset:49152
	global_load_dwordx4 v[36:39], v[16:17], off offset:384
	s_waitcnt vmcnt(1)
	ds_write_b128 v87, v[48:51] offset:20480
	global_load_dwordx4 v[40:43], v[18:19], off offset:384
	v_add_co_u32_e32 v18, vcc, s52, v16
	ds_write_b128 v87, v[52:55] offset:16384
	s_nop 0
	v_addc_co_u32_e32 v19, vcc, 0, v17, vcc
	v_add_co_u32_e32 v16, vcc, s34, v16
	global_load_dwordx4 v[32:35], v[18:19], off offset:384
	s_nop 0
	v_addc_co_u32_e32 v17, vcc, 0, v17, vcc
	ds_write_b128 v87, v[60:63] offset:12288
	global_load_dwordx4 v[28:31], v[16:17], off offset:384
	v_lshl_add_u64 v[16:17], v[82:83], 0, s[92:93]
	ds_write_b128 v87, v[72:75]
	s_waitcnt lgkmcnt(4)
	v_mfma_f32_16x16x32_bf16 v[76:79], v[114:117], v[24:27], v[0:3]
	v_mfma_f32_16x16x32_bf16 v[56:59], v[118:121], v[24:27], v[4:7]
	global_load_dwordx4 v[20:23], v[16:17], off offset:384
	v_add_co_u32_e32 v16, vcc, s7, v16
	ds_write_b128 v87, v[68:71] offset:4096
	s_nop 0
	v_addc_co_u32_e32 v17, vcc, 0, v17, vcc
	v_mfma_f32_16x16x32_bf16 v[44:47], v[122:125], v[24:27], v[8:11]
	v_mfma_f32_16x16x32_bf16 v[24:27], v[132:135], v[24:27], v[12:15]
	global_load_dwordx4 v[16:19], v[16:17], off offset:384
	ds_write_b128 v87, v[64:67] offset:8192
	v_mfma_f32_16x16x32_bf16 v[12:15], v[114:117], v[110:113], v[92:95]
	v_mfma_f32_16x16x32_bf16 v[8:11], v[118:121], v[110:113], v[100:103]
	v_mfma_f32_16x16x32_bf16 v[4:7], v[122:125], v[110:113], v[106:109]
	v_mfma_f32_16x16x32_bf16 v[0:3], v[132:135], v[110:113], v[96:99]
	s_cmp_lt_u32 s0, 62
	s_mov_b32 s1, s0
	s_waitcnt lgkmcnt(0)
	s_barrier
	s_cbranch_scc1 .LBB0_327
	v_readlane_b32 s0, v251, 18
	s_nop 1
	v_add_u32_e32 v48, s0, v86
	v_readlane_b32 s0, v251, 19
	s_waitcnt vmcnt(0)
	v_add_u32_e32 v16, 0xffffe000, v48
	v_or_b32_e32 v34, v48, v85
	v_lshl_or_b32 v32, v84, 2, s0
	v_lshrrev_b32_e32 v16, 10, v16
	s_movk_i32 s0, 0x1800
	v_mad_u32_u24 v16, v16, s0, s0
	v_cmp_lt_i32_e32 vcc, s13, v34
	v_ashrrev_i32_e32 v35, 31, v34
	v_lshlrev_b32_e32 v128, 2, v32
	v_cndmask_b32_e32 v28, 0, v16, vcc
	v_ashrrev_i32_e32 v29, 31, v28
	v_lshl_add_u64 v[16:17], v[28:29], 2, s[40:41]
	v_readlane_b32 s0, v250, 15
	v_lshl_add_u64 v[40:41], v[16:17], 0, v[128:129]
	v_lshlrev_b64 v[16:17], 12, v[34:35]
	v_readlane_b32 s1, v250, 16
	v_lshlrev_b64 v[30:31], 10, v[34:35]
	s_and_b64 vcc, exec, s[36:37]
	v_lshl_add_u64 v[16:17], s[0:1], 0, v[16:17]
	v_lshl_add_u64 v[38:39], v[16:17], 0, v[128:129]
	global_load_dwordx4 v[60:63], v[40:41], off
	global_load_dwordx4 v[72:75], v[40:41], off offset:64
	global_load_dwordx4 v[80:83], v[40:41], off offset:128
	global_load_dwordx4 v[88:91], v[40:41], off offset:192
	global_load_dwordx4 v[190:193], v[38:39], off
	global_load_dwordx4 v[194:197], v[38:39], off offset:64
	global_load_dwordx4 v[198:201], v[38:39], off offset:128
	global_load_dwordx4 v[202:205], v[38:39], off offset:192
	v_add_co_u32_e32 v54, vcc, 0x10000, v38
	s_nop 1
	v_addc_co_u32_e32 v55, vcc, 0, v39, vcc
	global_load_dwordx4 v[206:209], v[54:55], off
	global_load_dwordx4 v[210:213], v[54:55], off offset:64
	global_load_dwordx4 v[214:217], v[54:55], off offset:128
	global_load_dwordx4 v[218:221], v[54:55], off offset:192
	v_readlane_b32 s0, v250, 21
	v_readlane_b32 s1, v250, 22
	v_lshl_add_u64 v[42:43], v[28:29], 2, s[42:43]
	v_lshlrev_b32_e32 v32, 1, v32
	v_lshl_add_u64 v[36:37], v[30:31], 1, s[0:1]
	s_waitcnt vmcnt(4)
	v_pk_fma_f32 v[18:19], v[78:79], v[62:63], v[192:193]
	v_pk_fma_f32 v[16:17], v[76:77], v[60:61], v[190:191]
	global_store_dwordx4 v[38:39], v[16:19], off
	s_cbranch_vccnz .LBB0_330
	v_lshl_add_u64 v[28:29], v[42:43], 0, v[128:129]
	global_load_dwordx4 v[136:139], v128, s[26:27]
	global_load_dwordx4 v[140:143], v128, s[26:27] offset:64
	global_load_dwordx4 v[144:147], v128, s[26:27] offset:128
	global_load_dwordx4 v[148:151], v128, s[26:27] offset:192
	v_mov_b32_e32 v33, v129
	global_load_dwordx4 v[152:155], v[28:29], off
	global_load_dwordx4 v[156:159], v[28:29], off offset:64
	global_load_dwordx4 v[160:163], v[28:29], off offset:128
	global_load_dwordx4 v[180:183], v[28:29], off offset:192
	s_waitcnt vmcnt(0)
	v_pk_mul_f32 v[22:23], v[18:19], v[138:139]
	v_pk_mul_f32 v[20:21], v[16:17], v[136:137]
	s_waitcnt vmcnt(0)
	v_pk_add_f32 v[30:31], v[154:155], 1.0 op_sel_hi:[1,0]
	v_pk_add_f32 v[28:29], v[152:153], 1.0 op_sel_hi:[1,0]
	v_pk_mul_f32 v[22:23], v[22:23], v[30:31]
	v_pk_mul_f32 v[20:21], v[20:21], v[28:29]
	v_and_b32_sdwa v30, v22, v170 dst_sel:DWORD dst_unused:UNUSED_PAD src0_sel:WORD_1 src1_sel:DWORD
	v_and_b32_sdwa v31, v20, v170 dst_sel:DWORD dst_unused:UNUSED_PAD src0_sel:WORD_1 src1_sel:DWORD
	v_add3_u32 v20, v20, v31, s56
	v_add3_u32 v22, v22, v30, s56
	v_and_b32_sdwa v30, v23, v170 dst_sel:DWORD dst_unused:UNUSED_PAD src0_sel:WORD_1 src1_sel:DWORD
	v_and_b32_sdwa v31, v21, v170 dst_sel:DWORD dst_unused:UNUSED_PAD src0_sel:WORD_1 src1_sel:DWORD
	v_add3_u32 v23, v23, v30, s56
	v_add3_u32 v21, v21, v31, s56
	v_and_b32_e32 v23, 0xffff0000, v23
	v_and_b32_e32 v30, 0xffff0000, v21
	v_lshl_add_u64 v[28:29], v[36:37], 0, v[32:33]
	v_or_b32_sdwa v21, v23, v22 dst_sel:DWORD dst_unused:UNUSED_PAD src0_sel:DWORD src1_sel:WORD_1
	v_or_b32_sdwa v20, v30, v20 dst_sel:DWORD dst_unused:UNUSED_PAD src0_sel:DWORD src1_sel:WORD_1
	global_store_dwordx2 v[28:29], v[20:21], off

.LBB0_392:
	s_add_i32 s0, s1, 2
	v_add_u32_e32 v111, v104, v105
	ds_read_b128 v[136:139], v111 offset:16384
	ds_read_b128 v[140:143], v111 offset:18432
	ds_read_b128 v[144:147], v111 offset:20480
	ds_read_b128 v[148:151], v111 offset:22528
	v_add_u32_e32 v110, v103, v105
	ds_read_b128 v[116:119], v110
	s_add_i32 s1, s1, 4
	ds_read_b128 v[120:123], v110 offset:2048
	s_min_u32 s1, s1, 15
	v_add_u32_e32 v113, v104, v114
	s_lshl_b32 s92, s1, 7
	ds_read_b128 v[124:127], v110 offset:4096
	v_add_u32_e32 v112, v103, v114
	ds_read_b128 v[194:197], v113 offset:16384
	ds_read_b128 v[198:201], v113 offset:18432
	ds_read_b128 v[202:205], v113 offset:20480
	ds_read_b128 v[206:209], v113 offset:22528
	v_lshl_add_u64 v[164:165], v[98:99], 0, s[92:93]
	ds_read_b128 v[132:135], v110 offset:6144
	ds_read_b128 v[152:155], v112
	ds_read_b128 v[156:159], v112 offset:2048
	ds_read_b128 v[160:163], v112 offset:4096
	ds_read_b128 v[190:193], v112 offset:6144
	s_waitcnt lgkmcnt(11)
	v_mfma_f32_16x16x32_bf16 v[92:95], v[136:139], v[116:119], v[92:95]
	v_mfma_f32_16x16x32_bf16 v[88:91], v[140:143], v[116:119], v[88:91]
	v_mfma_f32_16x16x32_bf16 v[52:55], v[144:147], v[116:119], v[52:55]
	v_mfma_f32_16x16x32_bf16 v[48:51], v[148:151], v[116:119], v[48:51]
	global_load_dwordx4 v[116:119], v[164:165], off
	s_waitcnt vmcnt(6)
	ds_write_b128 v109, v[56:59] offset:32768
	v_add_co_u32_e32 v56, vcc, s11, v164
	s_waitcnt lgkmcnt(11)
	v_mfma_f32_16x16x32_bf16 v[44:47], v[136:139], v[120:123], v[44:47]
	v_addc_co_u32_e32 v57, vcc, 0, v165, vcc
	v_mfma_f32_16x16x32_bf16 v[40:43], v[140:143], v[120:123], v[40:43]
	v_mfma_f32_16x16x32_bf16 v[36:39], v[144:147], v[120:123], v[36:39]
	v_mfma_f32_16x16x32_bf16 v[32:35], v[148:151], v[120:123], v[32:35]
	global_load_dwordx4 v[120:123], v[56:57], off
	v_add_co_u32_e32 v56, vcc, s33, v164
	ds_write_b128 v109, v[60:63] offset:36864
	s_nop 0
	v_addc_co_u32_e32 v57, vcc, 0, v165, vcc
	s_waitcnt lgkmcnt(11)
	v_mfma_f32_16x16x32_bf16 v[28:31], v[136:139], v[124:127], v[28:31]
	v_mfma_f32_16x16x32_bf16 v[24:27], v[140:143], v[124:127], v[24:27]
	v_mfma_f32_16x16x32_bf16 v[20:23], v[144:147], v[124:127], v[20:23]
	v_mfma_f32_16x16x32_bf16 v[16:19], v[148:151], v[124:127], v[16:19]
	global_load_dwordx4 v[124:127], v[56:57], off
	v_add_co_u32_e32 v56, vcc, s59, v164
	ds_write_b128 v109, v[64:67] offset:40960
	s_nop 0
	v_addc_co_u32_e32 v57, vcc, 0, v165, vcc
	v_lshl_add_u64 v[64:65], v[100:101], 0, s[92:93]
	v_add_co_u32_e32 v66, vcc, s11, v64
	s_waitcnt lgkmcnt(7)
	v_mfma_f32_16x16x32_bf16 v[12:15], v[136:139], v[132:135], v[12:15]
	v_addc_co_u32_e32 v67, vcc, 0, v65, vcc
	v_mfma_f32_16x16x32_bf16 v[8:11], v[140:143], v[132:135], v[8:11]
	v_mfma_f32_16x16x32_bf16 v[4:7], v[144:147], v[132:135], v[4:7]
	v_mfma_f32_16x16x32_bf16 v[0:3], v[148:151], v[132:135], v[0:3]
	global_load_dwordx4 v[132:135], v[56:57], off
	s_waitcnt vmcnt(7)
	ds_write_b128 v109, v[72:75] offset:45056
	s_waitcnt lgkmcnt(7)
	v_mfma_f32_16x16x32_bf16 v[56:59], v[194:197], v[152:155], v[92:95]
	v_mfma_f32_16x16x32_bf16 v[60:63], v[198:201], v[152:155], v[88:91]
	v_mfma_f32_16x16x32_bf16 v[52:55], v[202:205], v[152:155], v[52:55]
	v_mfma_f32_16x16x32_bf16 v[48:51], v[206:209], v[152:155], v[48:51]
	global_load_dwordx4 v[136:139], v[64:65], off
	ds_write_b128 v109, v[68:71] offset:49152
	s_waitcnt lgkmcnt(7)
	v_mfma_f32_16x16x32_bf16 v[44:47], v[194:197], v[156:159], v[44:47]
	v_mfma_f32_16x16x32_bf16 v[40:43], v[198:201], v[156:159], v[40:43]
	v_mfma_f32_16x16x32_bf16 v[36:39], v[202:205], v[156:159], v[36:39]
	v_mfma_f32_16x16x32_bf16 v[32:35], v[206:209], v[156:159], v[32:35]
	global_load_dwordx4 v[140:143], v[66:67], off
	v_add_co_u32_e32 v66, vcc, s33, v64
	s_waitcnt vmcnt(8)
	ds_write_b128 v109, v[76:79] offset:53248
	v_addc_co_u32_e32 v67, vcc, 0, v65, vcc
	v_add_co_u32_e32 v64, vcc, s59, v64
	s_waitcnt lgkmcnt(7)
	v_mfma_f32_16x16x32_bf16 v[28:31], v[194:197], v[160:163], v[28:31]
	v_addc_co_u32_e32 v65, vcc, 0, v65, vcc
	v_mfma_f32_16x16x32_bf16 v[24:27], v[198:201], v[160:163], v[24:27]
	v_mfma_f32_16x16x32_bf16 v[20:23], v[202:205], v[160:163], v[20:23]
	v_mfma_f32_16x16x32_bf16 v[16:19], v[206:209], v[160:163], v[16:19]
	global_load_dwordx4 v[144:147], v[66:67], off
	s_waitcnt vmcnt(8)
	ds_write_b128 v109, v[80:83] offset:57344
	s_waitcnt lgkmcnt(7)
	v_mfma_f32_16x16x32_bf16 v[12:15], v[194:197], v[190:193], v[12:15]
	v_mfma_f32_16x16x32_bf16 v[8:11], v[198:201], v[190:193], v[8:11]
	v_mfma_f32_16x16x32_bf16 v[4:7], v[202:205], v[190:193], v[4:7]
	v_mfma_f32_16x16x32_bf16 v[0:3], v[206:209], v[190:193], v[0:3]
	global_load_dwordx4 v[148:151], v[64:65], off
	s_waitcnt vmcnt(8)
	ds_write_b128 v109, v[84:87] offset:61440
	s_waitcnt lgkmcnt(0)
	s_barrier
	ds_read_b128 v[84:87], v111 offset:51200
	ds_read_b128 v[80:83], v111 offset:49152
	ds_read_b128 v[88:91], v111 offset:53248
	ds_read_b128 v[92:95], v111 offset:55296
	ds_read_b128 v[64:67], v110 offset:32768
	s_min_u32 s1, s0, 12
	s_lshl_b32 s92, s1, 7
	ds_read_b128 v[68:71], v110 offset:34816
	v_lshl_add_u64 v[164:165], v[98:99], 0, s[92:93]
	ds_read_b128 v[72:75], v110 offset:36864
	ds_read_b128 v[76:79], v110 offset:38912
	ds_read_b128 v[152:155], v112 offset:32768
	ds_read_b128 v[156:159], v112 offset:34816
	ds_read_b128 v[160:163], v112 offset:36864
	ds_read_b128 v[190:193], v112 offset:38912
	ds_read_b128 v[194:197], v113 offset:49152
	ds_read_b128 v[198:201], v113 offset:51200
	ds_read_b128 v[202:205], v113 offset:53248
	ds_read_b128 v[206:209], v113 offset:55296
	s_waitcnt lgkmcnt(11)
	v_mfma_f32_16x16x32_bf16 v[214:217], v[84:87], v[64:67], v[60:63]
	v_mfma_f32_16x16x32_bf16 v[210:213], v[80:83], v[64:67], v[56:59]
	s_nop 1
	v_add_co_u32_e32 v60, vcc, s11, v164
	s_nop 1
	v_addc_co_u32_e32 v61, vcc, 0, v165, vcc
	v_mfma_f32_16x16x32_bf16 v[52:55], v[88:91], v[64:67], v[52:55]
	v_mfma_f32_16x16x32_bf16 v[48:51], v[92:95], v[64:67], v[48:51]
	v_add_co_u32_e32 v64, vcc, s33, v164
	global_load_dwordx4 v[56:59], v[164:165], off offset:384
	s_nop 0
	v_addc_co_u32_e32 v65, vcc, 0, v165, vcc
	s_waitcnt vmcnt(8)
	ds_write_b128 v109, v[116:119]
	s_waitcnt lgkmcnt(11)
	v_mfma_f32_16x16x32_bf16 v[44:47], v[80:83], v[68:71], v[44:47]
	v_mfma_f32_16x16x32_bf16 v[40:43], v[84:87], v[68:71], v[40:43]
	v_mfma_f32_16x16x32_bf16 v[36:39], v[88:91], v[68:71], v[36:39]
	v_mfma_f32_16x16x32_bf16 v[32:35], v[92:95], v[68:71], v[32:35]
	v_add_co_u32_e32 v68, vcc, s59, v164
	global_load_dwordx4 v[60:63], v[60:61], off offset:384
	s_waitcnt vmcnt(8)
	ds_write_b128 v109, v[120:123] offset:4096
	s_waitcnt lgkmcnt(11)
	v_mfma_f32_16x16x32_bf16 v[28:31], v[80:83], v[72:75], v[28:31]
	v_addc_co_u32_e32 v69, vcc, 0, v165, vcc
	v_mfma_f32_16x16x32_bf16 v[24:27], v[84:87], v[72:75], v[24:27]
	v_mfma_f32_16x16x32_bf16 v[20:23], v[88:91], v[72:75], v[20:23]
	v_mfma_f32_16x16x32_bf16 v[16:19], v[92:95], v[72:75], v[16:19]
	global_load_dwordx4 v[64:67], v[64:65], off offset:384
	s_waitcnt vmcnt(8)
	ds_write_b128 v109, v[124:127] offset:8192
	s_waitcnt lgkmcnt(11)
	v_mfma_f32_16x16x32_bf16 v[8:11], v[84:87], v[76:79], v[8:11]
	v_lshl_add_u64 v[84:85], v[100:101], 0, s[92:93]
	v_mfma_f32_16x16x32_bf16 v[12:15], v[80:83], v[76:79], v[12:15]
	v_mfma_f32_16x16x32_bf16 v[4:7], v[88:91], v[76:79], v[4:7]
	v_mfma_f32_16x16x32_bf16 v[0:3], v[92:95], v[76:79], v[0:3]
	v_add_co_u32_e32 v76, vcc, s11, v84
	global_load_dwordx4 v[72:75], v[68:69], off offset:384
	s_nop 0
	v_addc_co_u32_e32 v77, vcc, 0, v85, vcc
	v_add_co_u32_e32 v80, vcc, s33, v84
	s_waitcnt vmcnt(8)
	ds_write_b128 v109, v[132:135] offset:12288
	v_addc_co_u32_e32 v81, vcc, 0, v85, vcc
	s_waitcnt lgkmcnt(7)
	v_mfma_f32_16x16x32_bf16 v[92:95], v[194:197], v[152:155], v[210:213]
	s_waitcnt lgkmcnt(6)
	v_mfma_f32_16x16x32_bf16 v[88:91], v[198:201], v[152:155], v[214:217]
	s_waitcnt lgkmcnt(5)
	v_mfma_f32_16x16x32_bf16 v[52:55], v[202:205], v[152:155], v[52:55]
	s_waitcnt lgkmcnt(4)
	v_mfma_f32_16x16x32_bf16 v[48:51], v[206:209], v[152:155], v[48:51]
	global_load_dwordx4 v[68:71], v[84:85], off offset:384
	v_add_co_u32_e32 v84, vcc, s59, v84
	s_waitcnt vmcnt(8)
	ds_write_b128 v109, v[136:139] offset:16384
	v_addc_co_u32_e32 v85, vcc, 0, v85, vcc
	v_mfma_f32_16x16x32_bf16 v[44:47], v[194:197], v[156:159], v[44:47]
	v_mfma_f32_16x16x32_bf16 v[40:43], v[198:201], v[156:159], v[40:43]
	v_mfma_f32_16x16x32_bf16 v[36:39], v[202:205], v[156:159], v[36:39]
	v_mfma_f32_16x16x32_bf16 v[32:35], v[206:209], v[156:159], v[32:35]
	global_load_dwordx4 v[76:79], v[76:77], off offset:384
	s_waitcnt vmcnt(8)
	ds_write_b128 v109, v[140:143] offset:20480
	v_mfma_f32_16x16x32_bf16 v[28:31], v[194:197], v[160:163], v[28:31]
	v_mfma_f32_16x16x32_bf16 v[24:27], v[198:201], v[160:163], v[24:27]
	v_mfma_f32_16x16x32_bf16 v[20:23], v[202:205], v[160:163], v[20:23]
	v_mfma_f32_16x16x32_bf16 v[16:19], v[206:209], v[160:163], v[16:19]
	global_load_dwordx4 v[80:83], v[80:81], off offset:384
	s_waitcnt vmcnt(8)
	ds_write_b128 v109, v[144:147] offset:24576
	v_mfma_f32_16x16x32_bf16 v[12:15], v[194:197], v[190:193], v[12:15]
	v_mfma_f32_16x16x32_bf16 v[8:11], v[198:201], v[190:193], v[8:11]
	v_mfma_f32_16x16x32_bf16 v[4:7], v[202:205], v[190:193], v[4:7]
	v_mfma_f32_16x16x32_bf16 v[0:3], v[206:209], v[190:193], v[0:3]
	global_load_dwordx4 v[84:87], v[84:85], off offset:384
	s_waitcnt vmcnt(8)
	ds_write_b128 v109, v[148:151] offset:28672
	s_cmp_lt_u32 s0, 14
	s_mov_b32 s1, s0
	s_waitcnt lgkmcnt(0)
	s_barrier
	s_cbranch_scc1 .LBB0_392
	s_mul_i32 s0, s69, 0x12000
	v_readlane_b32 s16, v250, 25
	s_add_u32 s24, s16, s0
	v_readlane_b32 s0, v251, 5
	v_lshlrev_b32_e32 v114, 6, v102
	v_readlane_b32 s17, v250, 26
	s_waitcnt vmcnt(5)
	v_add_u32_e32 v64, s0, v108
	v_readlane_b32 s0, v251, 6
	v_add_u32_e32 v56, 0xffffe000, v64
	v_or_b32_e32 v62, v64, v107
	v_or_b32_e32 v65, s0, v114
	v_lshrrev_b32_e32 v56, 10, v56
	s_movk_i32 s0, 0x1800
	v_mad_u32_u24 v56, v56, s0, s0
	v_cmp_lt_i32_e32 vcc, s13, v62
	s_addc_u32 s25, s17, 0
	v_lshlrev_b32_e32 v115, 2, v97
	v_cndmask_b32_e32 v56, 0, v56, vcc
	s_add_u32 s40, s24, 0x2000
	v_or_b32_e32 v58, v65, v115
	v_ashrrev_i32_e32 v57, 31, v56
	s_addc_u32 s41, s25, 0
	s_waitcnt vmcnt(4)
	v_lshlrev_b64 v[74:75], 2, v[56:57]
	v_ashrrev_i32_e32 v59, 31, v58
	v_ashrrev_i32_e32 v63, 31, v62
	v_lshl_add_u64 v[56:57], s[40:41], 0, v[74:75]
	v_lshlrev_b64 v[60:61], 2, v[58:59]
	v_readlane_b32 s0, v250, 15
	s_waitcnt vmcnt(1)
	v_lshl_add_u64 v[82:83], v[56:57], 0, v[60:61]
	v_lshlrev_b64 v[56:57], 12, v[62:63]
	v_readlane_b32 s1, v250, 16
	v_readlane_b32 s16, v250, 21
	v_lshlrev_b64 v[78:79], 11, v[62:63]
	v_lshl_add_u64 v[56:57], s[0:1], 0, v[56:57]
	s_waitcnt vmcnt(0)
	v_lshl_add_u64 v[84:85], v[56:57], 0, v[60:61]
	global_load_dwordx4 v[116:119], v[82:83], off
	global_load_dwordx4 v[120:123], v[82:83], off offset:64
	global_load_dwordx4 v[124:127], v[82:83], off offset:128
	global_load_dwordx4 v[132:135], v[82:83], off offset:192
	global_load_dwordx4 v[190:193], v[84:85], off
	global_load_dwordx4 v[194:197], v[84:85], off offset:64
	global_load_dwordx4 v[198:201], v[84:85], off offset:128
	global_load_dwordx4 v[202:205], v[84:85], off offset:192
	v_add_co_u32_e32 v164, vcc, 0x10000, v84
	s_nop 1
	v_addc_co_u32_e32 v165, vcc, 0, v85, vcc
	v_add_co_u32_e32 v222, vcc, 0x20000, v84
	s_nop 1
	v_addc_co_u32_e32 v223, vcc, 0, v85, vcc
	v_add_co_u32_e32 v224, vcc, 0x30000, v84
	s_nop 1
	v_addc_co_u32_e32 v225, vcc, 0, v85, vcc
	global_load_dwordx4 v[206:209], v[164:165], off
	global_load_dwordx4 v[210:213], v[164:165], off offset:64
	global_load_dwordx4 v[214:217], v[164:165], off offset:128
	global_load_dwordx4 v[218:221], v[164:165], off offset:192
	s_lshl_b32 s0, s69, 12
	v_readlane_b32 s68, v250, 41
	v_readlane_b32 s72, v250, 45
	v_readlane_b32 s73, v250, 46
	s_add_u32 s0, s72, s0
	s_addc_u32 s1, s73, 0
	s_add_u32 s42, s24, 0x4000
	s_addc_u32 s43, s25, 0
	v_lshl_add_u64 v[74:75], s[42:43], 0, v[74:75]
	v_lshl_add_u64 v[56:57], s[0:1], 0, v[60:61]
	v_lshl_add_u64 v[86:87], v[74:75], 0, v[60:61]
	v_readlane_b32 s17, v250, 22
	v_readlane_b32 s69, v250, 42
	v_readlane_b32 s69, v254, 49
	v_lshl_add_u64 v[78:79], s[16:17], 0, v[78:79]
	s_mul_i32 s24, s69, 0x140000
	s_add_u32 s24, s86, s24
	v_lshrrev_b32_e32 v65, 6, v65
	s_mov_b32 s16, 0xa000
	s_addc_u32 s25, s87, 0
	s_add_u32 s38, s24, 0xaf1a000
	s_addc_u32 s39, s25, 0
	v_cmp_eq_u32_e64 s[36:37], 0, v97
	v_readlane_b32 s70, v250, 43
	v_readlane_b32 s71, v250, 44
	v_readlane_b32 s74, v250, 47
	v_readlane_b32 s75, v250, 48
	v_readlane_b32 s76, v250, 49
	v_readlane_b32 s77, v250, 50
	v_readlane_b32 s78, v250, 51
	v_readlane_b32 s79, v250, 52
	v_readlane_b32 s80, v250, 53
	v_readlane_b32 s81, v250, 54
	v_readlane_b32 s82, v250, 55
	v_readlane_b32 s83, v250, 56
	s_waitcnt vmcnt(4)
	v_pk_fma_f32 v[68:69], v[94:95], v[118:119], v[192:193]
	v_pk_fma_f32 v[66:67], v[92:93], v[116:117], v[190:191]
	global_store_dwordx4 v[84:85], v[66:69], off
	global_load_dwordx4 v[136:139], v[56:57], off
	global_load_dwordx4 v[140:143], v[56:57], off offset:64
	global_load_dwordx4 v[144:147], v[56:57], off offset:128
	global_load_dwordx4 v[148:151], v[56:57], off offset:192
	global_load_dwordx4 v[152:155], v[86:87], off
	global_load_dwordx4 v[156:159], v[86:87], off offset:64
	global_load_dwordx4 v[160:163], v[86:87], off offset:128
	global_load_dwordx4 v[180:183], v[86:87], off offset:192
	v_lshl_add_u64 v[92:93], v[58:59], 1, v[78:79]
	s_waitcnt vmcnt(0)
	v_pk_mul_f32 v[72:73], v[68:69], v[138:139]
	v_pk_mul_f32 v[70:71], v[66:67], v[136:137]
	s_waitcnt vmcnt(0)
	v_pk_add_f32 v[76:77], v[154:155], 1.0 op_sel_hi:[1,0]
	v_pk_add_f32 v[74:75], v[152:153], 1.0 op_sel_hi:[1,0]
	v_pk_mul_f32 v[72:73], v[72:73], v[76:77]
	v_pk_mul_f32 v[70:71], v[70:71], v[74:75]
	v_and_b32_sdwa v76, v73, v170 dst_sel:DWORD dst_unused:UNUSED_PAD src0_sel:WORD_1 src1_sel:DWORD
	v_and_b32_sdwa v77, v71, v170 dst_sel:DWORD dst_unused:UNUSED_PAD src0_sel:WORD_1 src1_sel:DWORD
	v_and_b32_sdwa v74, v72, v170 dst_sel:DWORD dst_unused:UNUSED_PAD src0_sel:WORD_1 src1_sel:DWORD
	v_and_b32_sdwa v75, v70, v170 dst_sel:DWORD dst_unused:UNUSED_PAD src0_sel:WORD_1 src1_sel:DWORD
	v_add3_u32 v73, v73, v76, s56
	v_add3_u32 v71, v71, v77, s56
	v_add3_u32 v70, v70, v75, s56
	v_add3_u32 v72, v72, v74, s56
	v_and_b32_e32 v73, 0xffff0000, v73
	v_and_b32_e32 v74, 0xffff0000, v71
	v_or_b32_sdwa v71, v73, v72 dst_sel:DWORD dst_unused:UNUSED_PAD src0_sel:DWORD src1_sel:WORD_1
	v_or_b32_sdwa v70, v74, v70 dst_sel:DWORD dst_unused:UNUSED_PAD src0_sel:DWORD src1_sel:WORD_1
	global_store_dwordx2 v[92:93], v[70:71], off
	s_nop 0
	s_waitcnt vmcnt(0)
	v_pk_fma_f32 v[72:73], v[90:91], v[122:123], v[196:197]
	v_pk_fma_f32 v[70:71], v[88:89], v[120:121], v[194:195]
	global_store_dwordx4 v[84:85], v[70:73], off offset:64
	v_pk_mul_f32 v[76:77], v[72:73], v[142:143]
	v_pk_mul_f32 v[74:75], v[70:71], v[140:141]
	v_pk_add_f32 v[80:81], v[158:159], 1.0 op_sel_hi:[1,0]
	v_pk_add_f32 v[78:79], v[156:157], 1.0 op_sel_hi:[1,0]
	v_pk_mul_f32 v[76:77], v[76:77], v[80:81]
	v_pk_mul_f32 v[74:75], v[74:75], v[78:79]
	v_and_b32_sdwa v80, v77, v170 dst_sel:DWORD dst_unused:UNUSED_PAD src0_sel:WORD_1 src1_sel:DWORD
	v_and_b32_sdwa v81, v75, v170 dst_sel:DWORD dst_unused:UNUSED_PAD src0_sel:WORD_1 src1_sel:DWORD
	v_and_b32_sdwa v78, v76, v170 dst_sel:DWORD dst_unused:UNUSED_PAD src0_sel:WORD_1 src1_sel:DWORD
	v_and_b32_sdwa v79, v74, v170 dst_sel:DWORD dst_unused:UNUSED_PAD src0_sel:WORD_1 src1_sel:DWORD
	v_add3_u32 v77, v77, v80, s56
	v_add3_u32 v75, v75, v81, s56
	v_add3_u32 v74, v74, v79, s56
	v_add3_u32 v76, v76, v78, s56
	v_and_b32_e32 v77, 0xffff0000, v77
	v_and_b32_e32 v78, 0xffff0000, v75
	v_or_b32_sdwa v75, v77, v76 dst_sel:DWORD dst_unused:UNUSED_PAD src0_sel:DWORD src1_sel:WORD_1
	v_or_b32_sdwa v74, v78, v74 dst_sel:DWORD dst_unused:UNUSED_PAD src0_sel:DWORD src1_sel:WORD_1
	global_store_dwordx2 v[92:93], v[74:75], off offset:32
	s_nop 0
	v_pk_fma_f32 v[54:55], v[54:55], v[126:127], v[200:201]
	v_pk_fma_f32 v[52:53], v[52:53], v[124:125], v[198:199]
	global_store_dwordx4 v[84:85], v[52:55], off offset:128
	v_pk_mul_f32 v[76:77], v[54:55], v[146:147]
	v_pk_mul_f32 v[74:75], v[52:53], v[144:145]
	v_pk_add_f32 v[80:81], v[162:163], 1.0 op_sel_hi:[1,0]
	v_pk_add_f32 v[78:79], v[160:161], 1.0 op_sel_hi:[1,0]
	v_pk_mul_f32 v[76:77], v[76:77], v[80:81]
	v_pk_mul_f32 v[74:75], v[74:75], v[78:79]
	v_and_b32_sdwa v80, v77, v170 dst_sel:DWORD dst_unused:UNUSED_PAD src0_sel:WORD_1 src1_sel:DWORD
	v_and_b32_sdwa v81, v75, v170 dst_sel:DWORD dst_unused:UNUSED_PAD src0_sel:WORD_1 src1_sel:DWORD
	v_and_b32_sdwa v78, v76, v170 dst_sel:DWORD dst_unused:UNUSED_PAD src0_sel:WORD_1 src1_sel:DWORD
	v_and_b32_sdwa v79, v74, v170 dst_sel:DWORD dst_unused:UNUSED_PAD src0_sel:WORD_1 src1_sel:DWORD
	v_add3_u32 v77, v77, v80, s56
	v_add3_u32 v75, v75, v81, s56
	v_add3_u32 v74, v74, v79, s56
	v_add3_u32 v76, v76, v78, s56
	v_and_b32_e32 v77, 0xffff0000, v77
	v_and_b32_e32 v78, 0xffff0000, v75
	v_or_b32_sdwa v75, v77, v76 dst_sel:DWORD dst_unused:UNUSED_PAD src0_sel:DWORD src1_sel:WORD_1
	v_or_b32_sdwa v74, v78, v74 dst_sel:DWORD dst_unused:UNUSED_PAD src0_sel:DWORD src1_sel:WORD_1
	global_store_dwordx2 v[92:93], v[74:75], off offset:64
	s_nop 0
	v_pk_fma_f32 v[76:77], v[50:51], v[134:135], v[204:205]
	v_pk_fma_f32 v[74:75], v[48:49], v[132:133], v[202:203]
	global_store_dwordx4 v[84:85], v[74:77], off offset:192
	s_nop 0
	v_mbcnt_lo_u32_b32 v48, -1, 0
	v_mbcnt_hi_u32_b32 v48, -1, v48
	v_and_b32_e32 v50, 64, v48
	v_xor_b32_e32 v49, 16, v48
	v_add_u32_e32 v50, 64, v50
	v_xor_b32_e32 v51, 32, v48
	v_cmp_lt_i32_e32 vcc, v49, v50
	s_nop 1
	v_cndmask_b32_e32 v49, v48, v49, vcc
	v_cmp_lt_i32_e32 vcc, v51, v50
	v_lshlrev_b32_e32 v105, 2, v49
	s_nop 0
	v_cndmask_b32_e32 v50, v48, v51, vcc
	v_lshlrev_b32_e32 v104, 2, v50
	v_mul_f32_e32 v50, v67, v67
	v_mul_f32_e32 v51, v71, v71
	v_fmac_f32_e32 v50, v66, v66
	v_fmac_f32_e32 v51, v70, v70
	v_fmac_f32_e32 v50, v68, v68
	v_fmac_f32_e32 v51, v72, v72
	v_fmac_f32_e32 v50, v69, v69
	v_fmac_f32_e32 v51, v73, v73
	v_add_f32_e32 v50, v50, v51
	v_mul_f32_e32 v51, v53, v53
	v_fmac_f32_e32 v51, v52, v52
	v_fmac_f32_e32 v51, v54, v54
	v_fmac_f32_e32 v51, v55, v55
	v_add_f32_e32 v50, v50, v51
	v_mul_f32_e32 v51, v75, v75
	v_fmac_f32_e32 v51, v74, v74
	v_fmac_f32_e32 v51, v76, v76
	v_fmac_f32_e32 v51, v77, v77
	v_add_f32_e32 v50, v50, v51
	ds_bpermute_b32 v51, v105, v50
	v_mul_lo_u32 v48, v65, s16
	v_ashrrev_i32_e32 v49, 31, v48
	v_lshl_add_u64 v[48:49], s[38:39], 0, v[48:49]
	v_lshl_add_u64 v[48:49], v[62:63], 2, v[48:49]
	s_waitcnt lgkmcnt(0)
	v_add_f32_e32 v50, v50, v51
	ds_bpermute_b32 v51, v104, v50
	v_pk_mul_f32 v[52:53], v[76:77], v[150:151]
	v_pk_mul_f32 v[54:55], v[74:75], v[148:149]
	v_pk_add_f32 v[66:67], v[182:183], 1.0 op_sel_hi:[1,0]
	v_pk_add_f32 v[68:69], v[180:181], 1.0 op_sel_hi:[1,0]
	v_pk_mul_f32 v[52:53], v[52:53], v[66:67]
	v_pk_mul_f32 v[54:55], v[54:55], v[68:69]
	v_and_b32_sdwa v67, v53, v170 dst_sel:DWORD dst_unused:UNUSED_PAD src0_sel:WORD_1 src1_sel:DWORD
	v_and_b32_sdwa v68, v55, v170 dst_sel:DWORD dst_unused:UNUSED_PAD src0_sel:WORD_1 src1_sel:DWORD
	v_and_b32_sdwa v65, v52, v170 dst_sel:DWORD dst_unused:UNUSED_PAD src0_sel:WORD_1 src1_sel:DWORD
	v_and_b32_sdwa v66, v54, v170 dst_sel:DWORD dst_unused:UNUSED_PAD src0_sel:WORD_1 src1_sel:DWORD
	v_add3_u32 v53, v53, v67, s56
	v_add3_u32 v55, v55, v68, s56
	v_add3_u32 v54, v54, v66, s56
	v_add3_u32 v52, v52, v65, s56
	v_and_b32_e32 v53, 0xffff0000, v53
	v_and_b32_e32 v55, 0xffff0000, v55
	v_or_b32_sdwa v53, v53, v52 dst_sel:DWORD dst_unused:UNUSED_PAD src0_sel:DWORD src1_sel:WORD_1
	v_or_b32_sdwa v52, v55, v54 dst_sel:DWORD dst_unused:UNUSED_PAD src0_sel:DWORD src1_sel:WORD_1
	global_store_dwordx2 v[92:93], v[52:53], off offset:96
	s_and_saveexec_b64 s[24:25], s[36:37]
	s_cbranch_execz .LBB0_395
	s_waitcnt lgkmcnt(0)
	v_add_f32_e32 v50, v50, v51
	global_store_dword v[48:49], v50, off

.LBB0_406:
	s_add_i32 s29, s44, 2
	ds_read_b128 v[136:139], v111 offset:16384
	ds_read_b128 v[140:143], v111 offset:18432
	ds_read_b128 v[144:147], v111 offset:20480
	ds_read_b128 v[148:151], v111 offset:22528
	ds_read_b128 v[116:119], v110
	s_add_i32 s44, s44, 4
	ds_read_b128 v[120:123], v110 offset:2048
	s_min_u32 s44, s44, 15
	s_lshl_b32 s92, s44, 7
	ds_read_b128 v[124:127], v110 offset:4096
	ds_read_b128 v[194:197], v113 offset:16384
	ds_read_b128 v[198:201], v113 offset:18432
	ds_read_b128 v[202:205], v113 offset:20480
	ds_read_b128 v[206:209], v113 offset:22528
	v_lshl_add_u64 v[164:165], v[100:101], 0, s[92:93]
	ds_read_b128 v[132:135], v110 offset:6144
	ds_read_b128 v[152:155], v112
	ds_read_b128 v[156:159], v112 offset:2048
	ds_read_b128 v[160:163], v112 offset:4096
	ds_read_b128 v[190:193], v112 offset:6144
	s_waitcnt lgkmcnt(11)
	v_mfma_f32_16x16x32_bf16 v[92:95], v[136:139], v[116:119], v[92:95]
	v_mfma_f32_16x16x32_bf16 v[88:91], v[140:143], v[116:119], v[88:91]
	v_mfma_f32_16x16x32_bf16 v[56:59], v[144:147], v[116:119], v[56:59]
	v_mfma_f32_16x16x32_bf16 v[48:51], v[148:151], v[116:119], v[48:51]
	global_load_dwordx4 v[116:119], v[164:165], off
	s_waitcnt vmcnt(6)
	ds_write_b128 v109, v[52:55] offset:32768
	v_add_co_u32_e32 v52, vcc, s11, v164
	s_waitcnt lgkmcnt(11)
	v_mfma_f32_16x16x32_bf16 v[44:47], v[136:139], v[120:123], v[44:47]
	v_addc_co_u32_e32 v53, vcc, 0, v165, vcc
	v_mfma_f32_16x16x32_bf16 v[40:43], v[140:143], v[120:123], v[40:43]
	v_mfma_f32_16x16x32_bf16 v[36:39], v[144:147], v[120:123], v[36:39]
	v_mfma_f32_16x16x32_bf16 v[32:35], v[148:151], v[120:123], v[32:35]
	global_load_dwordx4 v[120:123], v[52:53], off
	v_add_co_u32_e32 v52, vcc, s33, v164
	ds_write_b128 v109, v[60:63] offset:36864
	s_nop 0
	v_addc_co_u32_e32 v53, vcc, 0, v165, vcc
	s_waitcnt lgkmcnt(11)
	v_mfma_f32_16x16x32_bf16 v[28:31], v[136:139], v[124:127], v[28:31]
	v_mfma_f32_16x16x32_bf16 v[24:27], v[140:143], v[124:127], v[24:27]
	v_mfma_f32_16x16x32_bf16 v[20:23], v[144:147], v[124:127], v[20:23]
	v_mfma_f32_16x16x32_bf16 v[16:19], v[148:151], v[124:127], v[16:19]
	global_load_dwordx4 v[124:127], v[52:53], off
	v_add_co_u32_e32 v52, vcc, s59, v164
	ds_write_b128 v109, v[64:67] offset:40960
	s_nop 0
	v_addc_co_u32_e32 v53, vcc, 0, v165, vcc
	v_lshl_add_u64 v[64:65], v[102:103], 0, s[92:93]
	v_add_co_u32_e32 v66, vcc, s11, v64
	s_waitcnt lgkmcnt(7)
	v_mfma_f32_16x16x32_bf16 v[12:15], v[136:139], v[132:135], v[12:15]
	v_addc_co_u32_e32 v67, vcc, 0, v65, vcc
	v_mfma_f32_16x16x32_bf16 v[8:11], v[140:143], v[132:135], v[8:11]
	v_mfma_f32_16x16x32_bf16 v[4:7], v[144:147], v[132:135], v[4:7]
	v_mfma_f32_16x16x32_bf16 v[0:3], v[148:151], v[132:135], v[0:3]
	global_load_dwordx4 v[132:135], v[52:53], off
	s_waitcnt vmcnt(7)
	ds_write_b128 v109, v[72:75] offset:45056
	s_waitcnt lgkmcnt(7)
	v_mfma_f32_16x16x32_bf16 v[52:55], v[194:197], v[152:155], v[92:95]
	v_mfma_f32_16x16x32_bf16 v[60:63], v[198:201], v[152:155], v[88:91]
	v_mfma_f32_16x16x32_bf16 v[56:59], v[202:205], v[152:155], v[56:59]
	v_mfma_f32_16x16x32_bf16 v[48:51], v[206:209], v[152:155], v[48:51]
	global_load_dwordx4 v[136:139], v[64:65], off
	ds_write_b128 v109, v[68:71] offset:49152
	s_waitcnt lgkmcnt(7)
	v_mfma_f32_16x16x32_bf16 v[44:47], v[194:197], v[156:159], v[44:47]
	v_mfma_f32_16x16x32_bf16 v[40:43], v[198:201], v[156:159], v[40:43]
	v_mfma_f32_16x16x32_bf16 v[36:39], v[202:205], v[156:159], v[36:39]
	v_mfma_f32_16x16x32_bf16 v[32:35], v[206:209], v[156:159], v[32:35]
	global_load_dwordx4 v[140:143], v[66:67], off
	v_add_co_u32_e32 v66, vcc, s33, v64
	s_waitcnt vmcnt(8)
	ds_write_b128 v109, v[76:79] offset:53248
	v_addc_co_u32_e32 v67, vcc, 0, v65, vcc
	v_add_co_u32_e32 v64, vcc, s59, v64
	s_waitcnt lgkmcnt(7)
	v_mfma_f32_16x16x32_bf16 v[28:31], v[194:197], v[160:163], v[28:31]
	v_addc_co_u32_e32 v65, vcc, 0, v65, vcc
	v_mfma_f32_16x16x32_bf16 v[24:27], v[198:201], v[160:163], v[24:27]
	v_mfma_f32_16x16x32_bf16 v[20:23], v[202:205], v[160:163], v[20:23]
	v_mfma_f32_16x16x32_bf16 v[16:19], v[206:209], v[160:163], v[16:19]
	global_load_dwordx4 v[144:147], v[66:67], off
	s_waitcnt vmcnt(8)
	ds_write_b128 v109, v[80:83] offset:57344
	s_waitcnt lgkmcnt(7)
	v_mfma_f32_16x16x32_bf16 v[12:15], v[194:197], v[190:193], v[12:15]
	v_mfma_f32_16x16x32_bf16 v[8:11], v[198:201], v[190:193], v[8:11]
	v_mfma_f32_16x16x32_bf16 v[4:7], v[202:205], v[190:193], v[4:7]
	v_mfma_f32_16x16x32_bf16 v[0:3], v[206:209], v[190:193], v[0:3]
	global_load_dwordx4 v[148:151], v[64:65], off
	s_waitcnt vmcnt(8)
	ds_write_b128 v109, v[84:87] offset:61440
	s_waitcnt lgkmcnt(0)
	s_barrier
	ds_read_b128 v[84:87], v111 offset:51200
	ds_read_b128 v[80:83], v111 offset:49152
	ds_read_b128 v[88:91], v111 offset:53248
	ds_read_b128 v[92:95], v111 offset:55296
	ds_read_b128 v[64:67], v110 offset:32768
	s_min_u32 s44, s29, 12
	s_lshl_b32 s92, s44, 7
	ds_read_b128 v[68:71], v110 offset:34816
	v_lshl_add_u64 v[164:165], v[100:101], 0, s[92:93]
	ds_read_b128 v[72:75], v110 offset:36864
	ds_read_b128 v[76:79], v110 offset:38912
	ds_read_b128 v[152:155], v112 offset:32768
	ds_read_b128 v[156:159], v112 offset:34816
	ds_read_b128 v[160:163], v112 offset:36864
	ds_read_b128 v[190:193], v112 offset:38912
	ds_read_b128 v[194:197], v113 offset:49152
	ds_read_b128 v[198:201], v113 offset:51200
	ds_read_b128 v[202:205], v113 offset:53248
	ds_read_b128 v[206:209], v113 offset:55296
	s_waitcnt lgkmcnt(11)
	v_mfma_f32_16x16x32_bf16 v[214:217], v[84:87], v[64:67], v[60:63]
	v_mfma_f32_16x16x32_bf16 v[210:213], v[80:83], v[64:67], v[52:55]
	s_nop 1
	v_add_co_u32_e32 v60, vcc, s11, v164
	s_nop 1
	v_addc_co_u32_e32 v61, vcc, 0, v165, vcc
	v_mfma_f32_16x16x32_bf16 v[56:59], v[88:91], v[64:67], v[56:59]
	v_mfma_f32_16x16x32_bf16 v[48:51], v[92:95], v[64:67], v[48:51]
	v_add_co_u32_e32 v64, vcc, s33, v164
	global_load_dwordx4 v[52:55], v[164:165], off offset:384
	s_nop 0
	v_addc_co_u32_e32 v65, vcc, 0, v165, vcc
	s_waitcnt vmcnt(8)
	ds_write_b128 v109, v[116:119]
	s_waitcnt lgkmcnt(11)
	v_mfma_f32_16x16x32_bf16 v[44:47], v[80:83], v[68:71], v[44:47]
	v_mfma_f32_16x16x32_bf16 v[40:43], v[84:87], v[68:71], v[40:43]
	v_mfma_f32_16x16x32_bf16 v[36:39], v[88:91], v[68:71], v[36:39]
	v_mfma_f32_16x16x32_bf16 v[32:35], v[92:95], v[68:71], v[32:35]
	v_add_co_u32_e32 v68, vcc, s59, v164
	global_load_dwordx4 v[60:63], v[60:61], off offset:384
	s_waitcnt vmcnt(8)
	ds_write_b128 v109, v[120:123] offset:4096
	s_waitcnt lgkmcnt(11)
	v_mfma_f32_16x16x32_bf16 v[28:31], v[80:83], v[72:75], v[28:31]
	v_addc_co_u32_e32 v69, vcc, 0, v165, vcc
	v_mfma_f32_16x16x32_bf16 v[24:27], v[84:87], v[72:75], v[24:27]
	v_mfma_f32_16x16x32_bf16 v[20:23], v[88:91], v[72:75], v[20:23]
	v_mfma_f32_16x16x32_bf16 v[16:19], v[92:95], v[72:75], v[16:19]
	global_load_dwordx4 v[64:67], v[64:65], off offset:384
	s_waitcnt vmcnt(8)
	ds_write_b128 v109, v[124:127] offset:8192
	s_waitcnt lgkmcnt(11)
	v_mfma_f32_16x16x32_bf16 v[8:11], v[84:87], v[76:79], v[8:11]
	v_lshl_add_u64 v[84:85], v[102:103], 0, s[92:93]
	v_mfma_f32_16x16x32_bf16 v[12:15], v[80:83], v[76:79], v[12:15]
	v_mfma_f32_16x16x32_bf16 v[4:7], v[88:91], v[76:79], v[4:7]
	v_mfma_f32_16x16x32_bf16 v[0:3], v[92:95], v[76:79], v[0:3]
	v_add_co_u32_e32 v76, vcc, s11, v84
	global_load_dwordx4 v[72:75], v[68:69], off offset:384
	s_nop 0
	v_addc_co_u32_e32 v77, vcc, 0, v85, vcc
	v_add_co_u32_e32 v80, vcc, s33, v84
	s_waitcnt vmcnt(8)
	ds_write_b128 v109, v[132:135] offset:12288
	v_addc_co_u32_e32 v81, vcc, 0, v85, vcc
	s_waitcnt lgkmcnt(7)
	v_mfma_f32_16x16x32_bf16 v[92:95], v[194:197], v[152:155], v[210:213]
	s_waitcnt lgkmcnt(6)
	v_mfma_f32_16x16x32_bf16 v[88:91], v[198:201], v[152:155], v[214:217]
	s_waitcnt lgkmcnt(5)
	v_mfma_f32_16x16x32_bf16 v[56:59], v[202:205], v[152:155], v[56:59]
	s_waitcnt lgkmcnt(4)
	v_mfma_f32_16x16x32_bf16 v[48:51], v[206:209], v[152:155], v[48:51]
	global_load_dwordx4 v[68:71], v[84:85], off offset:384
	v_add_co_u32_e32 v84, vcc, s59, v84
	s_waitcnt vmcnt(8)
	ds_write_b128 v109, v[136:139] offset:16384
	v_addc_co_u32_e32 v85, vcc, 0, v85, vcc
	v_mfma_f32_16x16x32_bf16 v[44:47], v[194:197], v[156:159], v[44:47]
	v_mfma_f32_16x16x32_bf16 v[40:43], v[198:201], v[156:159], v[40:43]
	v_mfma_f32_16x16x32_bf16 v[36:39], v[202:205], v[156:159], v[36:39]
	v_mfma_f32_16x16x32_bf16 v[32:35], v[206:209], v[156:159], v[32:35]
	global_load_dwordx4 v[76:79], v[76:77], off offset:384
	s_waitcnt vmcnt(8)
	ds_write_b128 v109, v[140:143] offset:20480
	v_mfma_f32_16x16x32_bf16 v[28:31], v[194:197], v[160:163], v[28:31]
	v_mfma_f32_16x16x32_bf16 v[24:27], v[198:201], v[160:163], v[24:27]
	v_mfma_f32_16x16x32_bf16 v[20:23], v[202:205], v[160:163], v[20:23]
	v_mfma_f32_16x16x32_bf16 v[16:19], v[206:209], v[160:163], v[16:19]
	global_load_dwordx4 v[80:83], v[80:81], off offset:384
	s_waitcnt vmcnt(8)
	ds_write_b128 v109, v[144:147] offset:24576
	v_mfma_f32_16x16x32_bf16 v[12:15], v[194:197], v[190:193], v[12:15]
	v_mfma_f32_16x16x32_bf16 v[8:11], v[198:201], v[190:193], v[8:11]
	v_mfma_f32_16x16x32_bf16 v[4:7], v[202:205], v[190:193], v[4:7]
	v_mfma_f32_16x16x32_bf16 v[0:3], v[206:209], v[190:193], v[0:3]
	global_load_dwordx4 v[84:87], v[84:85], off offset:384
	s_waitcnt vmcnt(8)
	ds_write_b128 v109, v[148:151] offset:28672
	s_cmp_lt_u32 s29, 14
	s_mov_b32 s44, s29
	s_waitcnt lgkmcnt(0)
	s_barrier
	s_cbranch_scc1 .LBB0_406
	s_waitcnt vmcnt(5)
	v_add_u32_e32 v64, s24, v108
	v_add_u32_e32 v52, 0xffffe000, v64
	v_or_b32_e32 v62, v64, v107
	v_lshrrev_b32_e32 v52, 10, v52
	s_movk_i32 s16, 0x1800
	v_mad_u32_u24 v52, v52, s16, s16
	v_cmp_lt_i32_e32 vcc, s13, v62
	v_or_b32_e32 v65, s25, v114
	v_or_b32_e32 v54, v65, v115
	v_cndmask_b32_e32 v52, 0, v52, vcc
	v_ashrrev_i32_e32 v53, 31, v52
	s_waitcnt vmcnt(4)
	v_lshlrev_b64 v[74:75], 2, v[52:53]
	v_ashrrev_i32_e32 v55, 31, v54
	v_ashrrev_i32_e32 v63, 31, v62
	v_lshl_add_u64 v[52:53], s[40:41], 0, v[74:75]
	v_lshlrev_b64 v[60:61], 2, v[54:55]
	v_readlane_b32 s16, v250, 15
	s_waitcnt vmcnt(1)
	v_lshl_add_u64 v[82:83], v[52:53], 0, v[60:61]
	v_lshlrev_b64 v[52:53], 12, v[62:63]
	v_readlane_b32 s17, v250, 16
	v_lshl_add_u64 v[74:75], s[42:43], 0, v[74:75]
	s_waitcnt vmcnt(0)
	v_lshl_add_u64 v[86:87], v[74:75], 0, v[60:61]
	v_lshl_add_u64 v[52:53], s[16:17], 0, v[52:53]
	v_lshl_add_u64 v[84:85], v[52:53], 0, v[60:61]
	global_load_dwordx4 v[66:69], v[82:83], off
	global_load_dwordx4 v[70:73], v[84:85], off
	v_lshl_add_u64 v[52:53], s[0:1], 0, v[60:61]
	v_readlane_b32 s16, v250, 21
	v_lshlrev_b64 v[78:79], 11, v[62:63]
	v_readlane_b32 s17, v250, 22
	s_waitcnt vmcnt(0)
	v_pk_fma_f32 v[68:69], v[94:95], v[68:69], v[72:73]
	v_pk_fma_f32 v[66:67], v[92:93], v[66:67], v[70:71]
	global_store_dwordx4 v[84:85], v[66:69], off
	global_load_dwordx4 v[70:73], v[52:53], off
	global_load_dwordx4 v[74:77], v[86:87], off
	v_lshl_add_u64 v[78:79], s[16:17], 0, v[78:79]
	v_lshl_add_u64 v[92:93], v[54:55], 1, v[78:79]
	s_mov_b32 s16, 0xa000
	s_waitcnt vmcnt(1)
	v_pk_mul_f32 v[72:73], v[68:69], v[72:73]
	v_pk_mul_f32 v[70:71], v[66:67], v[70:71]
	s_waitcnt vmcnt(0)
	v_pk_add_f32 v[76:77], v[76:77], 1.0 op_sel_hi:[1,0]
	v_pk_add_f32 v[74:75], v[74:75], 1.0 op_sel_hi:[1,0]
	v_pk_mul_f32 v[72:73], v[72:73], v[76:77]
	v_pk_mul_f32 v[70:71], v[70:71], v[74:75]
	v_and_b32_sdwa v76, v73, v170 dst_sel:DWORD dst_unused:UNUSED_PAD src0_sel:WORD_1 src1_sel:DWORD
	v_and_b32_sdwa v77, v71, v170 dst_sel:DWORD dst_unused:UNUSED_PAD src0_sel:WORD_1 src1_sel:DWORD
	v_and_b32_sdwa v74, v72, v170 dst_sel:DWORD dst_unused:UNUSED_PAD src0_sel:WORD_1 src1_sel:DWORD
	v_and_b32_sdwa v75, v70, v170 dst_sel:DWORD dst_unused:UNUSED_PAD src0_sel:WORD_1 src1_sel:DWORD
	v_add3_u32 v73, v73, v76, s56
	v_add3_u32 v71, v71, v77, s56
	v_add3_u32 v70, v70, v75, s56
	v_add3_u32 v72, v72, v74, s56
	v_and_b32_e32 v73, 0xffff0000, v73
	v_and_b32_e32 v74, 0xffff0000, v71
	v_or_b32_sdwa v71, v73, v72 dst_sel:DWORD dst_unused:UNUSED_PAD src0_sel:DWORD src1_sel:WORD_1
	v_or_b32_sdwa v70, v74, v70 dst_sel:DWORD dst_unused:UNUSED_PAD src0_sel:DWORD src1_sel:WORD_1
	global_store_dwordx2 v[92:93], v[70:71], off
	global_load_dwordx4 v[70:73], v[82:83], off offset:64
	s_nop 0
	global_load_dwordx4 v[74:77], v[84:85], off offset:64
	s_waitcnt vmcnt(0)
	v_pk_fma_f32 v[72:73], v[90:91], v[72:73], v[76:77]
	v_pk_fma_f32 v[70:71], v[88:89], v[70:71], v[74:75]
	global_store_dwordx4 v[84:85], v[70:73], off offset:64
	global_load_dwordx4 v[74:77], v[52:53], off offset:64
	global_load_dwordx4 v[78:81], v[86:87], off offset:64
	s_waitcnt vmcnt(1)
	v_pk_mul_f32 v[76:77], v[72:73], v[76:77]
	v_pk_mul_f32 v[74:75], v[70:71], v[74:75]
	s_waitcnt vmcnt(0)
	v_pk_add_f32 v[80:81], v[80:81], 1.0 op_sel_hi:[1,0]
	v_pk_add_f32 v[78:79], v[78:79], 1.0 op_sel_hi:[1,0]
	v_pk_mul_f32 v[76:77], v[76:77], v[80:81]
	v_pk_mul_f32 v[74:75], v[74:75], v[78:79]
	v_and_b32_sdwa v80, v77, v170 dst_sel:DWORD dst_unused:UNUSED_PAD src0_sel:WORD_1 src1_sel:DWORD
	v_and_b32_sdwa v81, v75, v170 dst_sel:DWORD dst_unused:UNUSED_PAD src0_sel:WORD_1 src1_sel:DWORD
	v_and_b32_sdwa v78, v76, v170 dst_sel:DWORD dst_unused:UNUSED_PAD src0_sel:WORD_1 src1_sel:DWORD
	v_and_b32_sdwa v79, v74, v170 dst_sel:DWORD dst_unused:UNUSED_PAD src0_sel:WORD_1 src1_sel:DWORD
	v_add3_u32 v77, v77, v80, s56
	v_add3_u32 v75, v75, v81, s56
	v_add3_u32 v74, v74, v79, s56
	v_add3_u32 v76, v76, v78, s56
	v_and_b32_e32 v77, 0xffff0000, v77
	v_and_b32_e32 v78, 0xffff0000, v75
	v_or_b32_sdwa v75, v77, v76 dst_sel:DWORD dst_unused:UNUSED_PAD src0_sel:DWORD src1_sel:WORD_1
	v_or_b32_sdwa v74, v78, v74 dst_sel:DWORD dst_unused:UNUSED_PAD src0_sel:DWORD src1_sel:WORD_1
	global_store_dwordx2 v[92:93], v[74:75], off offset:32
	global_load_dwordx4 v[74:77], v[82:83], off offset:128
	s_nop 0
	global_load_dwordx4 v[78:81], v[84:85], off offset:128
	s_waitcnt vmcnt(0)
	v_pk_fma_f32 v[58:59], v[58:59], v[76:77], v[80:81]
	v_pk_fma_f32 v[56:57], v[56:57], v[74:75], v[78:79]
	global_store_dwordx4 v[84:85], v[56:59], off offset:128
	global_load_dwordx4 v[74:77], v[52:53], off offset:128
	global_load_dwordx4 v[78:81], v[86:87], off offset:128
	s_waitcnt vmcnt(1)
	v_pk_mul_f32 v[76:77], v[58:59], v[76:77]
	v_pk_mul_f32 v[74:75], v[56:57], v[74:75]
	s_waitcnt vmcnt(0)
	v_pk_add_f32 v[80:81], v[80:81], 1.0 op_sel_hi:[1,0]
	v_pk_add_f32 v[78:79], v[78:79], 1.0 op_sel_hi:[1,0]
	v_pk_mul_f32 v[76:77], v[76:77], v[80:81]
	v_pk_mul_f32 v[74:75], v[74:75], v[78:79]
	v_and_b32_sdwa v80, v77, v170 dst_sel:DWORD dst_unused:UNUSED_PAD src0_sel:WORD_1 src1_sel:DWORD
	v_and_b32_sdwa v81, v75, v170 dst_sel:DWORD dst_unused:UNUSED_PAD src0_sel:WORD_1 src1_sel:DWORD
	v_and_b32_sdwa v78, v76, v170 dst_sel:DWORD dst_unused:UNUSED_PAD src0_sel:WORD_1 src1_sel:DWORD
	v_and_b32_sdwa v79, v74, v170 dst_sel:DWORD dst_unused:UNUSED_PAD src0_sel:WORD_1 src1_sel:DWORD
	v_add3_u32 v77, v77, v80, s56
	v_add3_u32 v75, v75, v81, s56
	v_add3_u32 v74, v74, v79, s56
	v_add3_u32 v76, v76, v78, s56
	v_and_b32_e32 v77, 0xffff0000, v77
	v_and_b32_e32 v78, 0xffff0000, v75
	v_or_b32_sdwa v75, v77, v76 dst_sel:DWORD dst_unused:UNUSED_PAD src0_sel:DWORD src1_sel:WORD_1
	v_or_b32_sdwa v74, v78, v74 dst_sel:DWORD dst_unused:UNUSED_PAD src0_sel:DWORD src1_sel:WORD_1
	global_store_dwordx2 v[92:93], v[74:75], off offset:64
	global_load_dwordx4 v[74:77], v[82:83], off offset:192
	s_nop 0
	global_load_dwordx4 v[78:81], v[84:85], off offset:192
	s_waitcnt vmcnt(0)
	v_pk_fma_f32 v[76:77], v[50:51], v[76:77], v[80:81]
	v_pk_fma_f32 v[74:75], v[48:49], v[74:75], v[78:79]
	global_store_dwordx4 v[84:85], v[74:77], off offset:192
	global_load_dwordx4 v[78:81], v[52:53], off offset:192
	s_nop 0
	global_load_dwordx4 v[82:85], v[86:87], off offset:192
	v_mul_f32_e32 v48, v67, v67
	v_mul_f32_e32 v49, v71, v71
	v_fmac_f32_e32 v48, v66, v66
	v_fmac_f32_e32 v49, v70, v70
	v_fmac_f32_e32 v48, v68, v68
	v_fmac_f32_e32 v49, v72, v72
	v_fmac_f32_e32 v48, v69, v69
	v_fmac_f32_e32 v49, v73, v73
	v_add_f32_e32 v48, v48, v49
	v_mul_f32_e32 v49, v57, v57
	v_fmac_f32_e32 v49, v56, v56
	v_fmac_f32_e32 v49, v58, v58
	v_fmac_f32_e32 v49, v59, v59
	v_add_f32_e32 v48, v48, v49
	v_mul_f32_e32 v49, v75, v75
	v_fmac_f32_e32 v49, v74, v74
	v_fmac_f32_e32 v49, v76, v76
	v_fmac_f32_e32 v49, v77, v77
	v_add_f32_e32 v50, v48, v49
	ds_bpermute_b32 v51, v105, v50
	v_lshrrev_b32_e32 v48, 6, v65
	v_mul_lo_u32 v48, v48, s16
	v_ashrrev_i32_e32 v49, 31, v48
	v_lshl_add_u64 v[48:49], s[38:39], 0, v[48:49]
	s_waitcnt lgkmcnt(0)
	v_add_f32_e32 v50, v50, v51
	ds_bpermute_b32 v51, v104, v50
	v_lshl_add_u64 v[48:49], v[62:63], 2, v[48:49]
	s_waitcnt vmcnt(1)
	v_pk_mul_f32 v[56:57], v[76:77], v[80:81]
	v_pk_mul_f32 v[58:59], v[74:75], v[78:79]
	s_waitcnt vmcnt(0)
	v_pk_add_f32 v[66:67], v[84:85], 1.0 op_sel_hi:[1,0]
	v_pk_add_f32 v[68:69], v[82:83], 1.0 op_sel_hi:[1,0]
	v_pk_mul_f32 v[56:57], v[56:57], v[66:67]
	v_pk_mul_f32 v[58:59], v[58:59], v[68:69]
	v_and_b32_sdwa v67, v57, v170 dst_sel:DWORD dst_unused:UNUSED_PAD src0_sel:WORD_1 src1_sel:DWORD
	v_and_b32_sdwa v68, v59, v170 dst_sel:DWORD dst_unused:UNUSED_PAD src0_sel:WORD_1 src1_sel:DWORD
	v_and_b32_sdwa v65, v56, v170 dst_sel:DWORD dst_unused:UNUSED_PAD src0_sel:WORD_1 src1_sel:DWORD
	v_and_b32_sdwa v66, v58, v170 dst_sel:DWORD dst_unused:UNUSED_PAD src0_sel:WORD_1 src1_sel:DWORD
	v_add3_u32 v57, v57, v67, s56
	v_add3_u32 v59, v59, v68, s56
	v_add3_u32 v58, v58, v66, s56
	v_add3_u32 v56, v56, v65, s56
	v_and_b32_e32 v57, 0xffff0000, v57
	v_and_b32_e32 v59, 0xffff0000, v59
	v_or_b32_sdwa v57, v57, v56 dst_sel:DWORD dst_unused:UNUSED_PAD src0_sel:DWORD src1_sel:WORD_1
	v_or_b32_sdwa v56, v59, v58 dst_sel:DWORD dst_unused:UNUSED_PAD src0_sel:DWORD src1_sel:WORD_1
	global_store_dwordx2 v[92:93], v[56:57], off offset:96
	s_and_saveexec_b64 s[24:25], s[36:37]
	s_cbranch_execz .LBB0_409
	s_waitcnt lgkmcnt(0)
	v_add_f32_e32 v50, v50, v51
	global_store_dword v[48:49], v50, off

.LBB0_419:
	s_add_i32 s2, s3, 2
	v_add_u32_e32 v127, v89, v90
	ds_read_b128 v[100:103], v127 offset:16384
	ds_read_b128 v[106:109], v127 offset:18432
	ds_read_b128 v[110:113], v127 offset:20480
	ds_read_b128 v[114:117], v127 offset:22528
	v_add_u32_e32 v126, v88, v90
	ds_read_b128 v[92:95], v126
	ds_read_b128 v[96:99], v126 offset:2048
	s_add_i32 s3, s3, 4
	s_min_u32 s3, s3, 15
	v_add_u32_e32 v128, v88, v91
	v_add_u32_e32 v130, v89, v91
	s_lshl_b32 s92, s3, 7
	ds_read_b128 v[118:121], v130 offset:18432
	ds_read_b128 v[122:125], v130 offset:20480
	ds_read_b128 v[132:135], v130 offset:22528
	s_waitcnt lgkmcnt(4)
	v_mfma_f32_16x16x32_bf16 v[76:79], v[100:103], v[92:95], v[76:79]
	v_lshl_add_u64 v[44:45], v[80:81], 0, s[92:93]
	v_add_co_u32_e32 v46, vcc, s11, v44
	v_mfma_f32_16x16x32_bf16 v[68:71], v[106:109], v[92:95], v[68:71]
	s_nop 0
	v_addc_co_u32_e32 v47, vcc, 0, v45, vcc
	v_mfma_f32_16x16x32_bf16 v[52:55], v[110:113], v[92:95], v[52:55]
	v_mfma_f32_16x16x32_bf16 v[40:43], v[114:117], v[92:95], v[40:43]
	s_waitcnt lgkmcnt(3)
	v_mfma_f32_16x16x32_bf16 v[92:95], v[100:103], v[96:99], v[36:39]
	s_nop 2
	ds_read_b128 v[36:39], v128
	v_mfma_f32_16x16x32_bf16 v[100:103], v[106:109], v[96:99], v[8:11]
	v_mfma_f32_16x16x32_bf16 v[106:109], v[110:113], v[96:99], v[4:7]
	ds_read_b128 v[110:113], v128 offset:2048
	v_mfma_f32_16x16x32_bf16 v[96:99], v[114:117], v[96:99], v[0:3]
	ds_read_b128 v[114:117], v130 offset:16384
	global_load_dwordx4 v[72:75], v[44:45], off
	s_waitcnt vmcnt(1)
	ds_write_b128 v87, v[12:15] offset:53248
	global_load_dwordx4 v[64:67], v[46:47], off
	v_add_co_u32_e32 v46, vcc, s33, v44
	ds_write_b128 v87, v[16:19] offset:49152
	s_nop 0
	v_addc_co_u32_e32 v47, vcc, 0, v45, vcc
	v_add_co_u32_e32 v44, vcc, s59, v44
	global_load_dwordx4 v[60:63], v[46:47], off
	s_nop 0
	v_addc_co_u32_e32 v45, vcc, 0, v45, vcc
	ds_write_b128 v87, v[20:23] offset:45056
	global_load_dwordx4 v[56:59], v[44:45], off
	v_lshl_add_u64 v[44:45], v[82:83], 0, s[92:93]
	ds_write_b128 v87, v[28:31] offset:32768
	s_waitcnt lgkmcnt(4)
	v_mfma_f32_16x16x32_bf16 v[0:3], v[114:117], v[36:39], v[76:79]
	v_mfma_f32_16x16x32_bf16 v[4:7], v[118:121], v[36:39], v[68:71]
	global_load_dwordx4 v[48:51], v[44:45], off
	v_add_co_u32_e32 v44, vcc, s11, v44
	ds_write_b128 v87, v[32:35] offset:36864
	s_nop 0
	v_addc_co_u32_e32 v45, vcc, 0, v45, vcc
	v_mfma_f32_16x16x32_bf16 v[8:11], v[122:125], v[36:39], v[52:55]
	v_mfma_f32_16x16x32_bf16 v[36:39], v[132:135], v[36:39], v[40:43]
	global_load_dwordx4 v[44:47], v[44:45], off
	ds_write_b128 v87, v[24:27] offset:40960
	v_mfma_f32_16x16x32_bf16 v[40:43], v[114:117], v[110:113], v[92:95]
	v_mfma_f32_16x16x32_bf16 v[52:55], v[118:121], v[110:113], v[100:103]
	v_mfma_f32_16x16x32_bf16 v[68:71], v[122:125], v[110:113], v[106:109]
	v_mfma_f32_16x16x32_bf16 v[76:79], v[132:135], v[110:113], v[96:99]
	s_waitcnt lgkmcnt(0)
	s_barrier
	ds_read_b128 v[100:103], v127 offset:49152
	ds_read_b128 v[106:109], v127 offset:51200
	ds_read_b128 v[110:113], v127 offset:53248
	ds_read_b128 v[114:117], v127 offset:55296
	ds_read_b128 v[92:95], v126 offset:32768
	ds_read_b128 v[96:99], v126 offset:34816
	s_min_u32 s3, s2, 12
	s_lshl_b32 s92, s3, 7
	ds_read_b128 v[118:121], v130 offset:51200
	ds_read_b128 v[122:125], v130 offset:53248
	ds_read_b128 v[132:135], v130 offset:55296
	s_waitcnt lgkmcnt(4)
	v_mfma_f32_16x16x32_bf16 v[0:3], v[100:103], v[92:95], v[0:3]
	v_lshl_add_u64 v[12:13], v[80:81], 0, s[92:93]
	v_add_co_u32_e32 v14, vcc, s11, v12
	v_mfma_f32_16x16x32_bf16 v[4:7], v[106:109], v[92:95], v[4:7]
	s_nop 0
	v_addc_co_u32_e32 v15, vcc, 0, v13, vcc
	v_mfma_f32_16x16x32_bf16 v[8:11], v[110:113], v[92:95], v[8:11]
	v_mfma_f32_16x16x32_bf16 v[36:39], v[114:117], v[92:95], v[36:39]
	s_waitcnt lgkmcnt(3)
	v_mfma_f32_16x16x32_bf16 v[92:95], v[100:103], v[96:99], v[40:43]
	s_nop 2
	ds_read_b128 v[40:43], v128 offset:32768
	v_mfma_f32_16x16x32_bf16 v[100:103], v[106:109], v[96:99], v[52:55]
	v_mfma_f32_16x16x32_bf16 v[106:109], v[110:113], v[96:99], v[68:71]
	ds_read_b128 v[110:113], v128 offset:34816
	v_mfma_f32_16x16x32_bf16 v[96:99], v[114:117], v[96:99], v[76:79]
	ds_read_b128 v[114:117], v130 offset:49152
	global_load_dwordx4 v[28:31], v[12:13], off offset:384
	s_waitcnt vmcnt(1)
	ds_write_b128 v87, v[44:47] offset:20480
	global_load_dwordx4 v[32:35], v[14:15], off offset:384
	v_add_co_u32_e32 v14, vcc, s33, v12
	ds_write_b128 v87, v[48:51] offset:16384
	s_nop 0
	v_addc_co_u32_e32 v15, vcc, 0, v13, vcc
	v_add_co_u32_e32 v12, vcc, s59, v12
	global_load_dwordx4 v[24:27], v[14:15], off offset:384
	s_nop 0
	v_addc_co_u32_e32 v13, vcc, 0, v13, vcc
	ds_write_b128 v87, v[56:59] offset:12288
	global_load_dwordx4 v[20:23], v[12:13], off offset:384
	v_lshl_add_u64 v[12:13], v[82:83], 0, s[92:93]
	ds_write_b128 v87, v[72:75]
	s_waitcnt lgkmcnt(4)
	v_mfma_f32_16x16x32_bf16 v[76:79], v[114:117], v[40:43], v[0:3]
	v_mfma_f32_16x16x32_bf16 v[68:71], v[118:121], v[40:43], v[4:7]
	global_load_dwordx4 v[16:19], v[12:13], off offset:384
	v_add_co_u32_e32 v12, vcc, s11, v12
	ds_write_b128 v87, v[64:67] offset:4096
	s_nop 0
	v_addc_co_u32_e32 v13, vcc, 0, v13, vcc
	v_mfma_f32_16x16x32_bf16 v[52:55], v[122:125], v[40:43], v[8:11]
	v_mfma_f32_16x16x32_bf16 v[40:43], v[132:135], v[40:43], v[36:39]
	global_load_dwordx4 v[12:15], v[12:13], off offset:384
	ds_write_b128 v87, v[60:63] offset:8192
	v_mfma_f32_16x16x32_bf16 v[36:39], v[114:117], v[110:113], v[92:95]
	v_mfma_f32_16x16x32_bf16 v[8:11], v[118:121], v[110:113], v[100:103]
	v_mfma_f32_16x16x32_bf16 v[4:7], v[122:125], v[110:113], v[106:109]
	v_mfma_f32_16x16x32_bf16 v[0:3], v[132:135], v[110:113], v[96:99]
	s_cmp_lt_u32 s2, 14
	s_mov_b32 s3, s2
	s_waitcnt lgkmcnt(0)
	s_barrier
	s_cbranch_scc1 .LBB0_419
	v_readlane_b32 s2, v251, 18
	s_waitcnt vmcnt(1)
	s_nop 0
	v_add_u32_e32 v18, s2, v86
	v_readlane_b32 s2, v251, 19
	s_waitcnt vmcnt(0)
	v_add_u32_e32 v13, 0xffffe000, v18
	v_or_b32_e32 v12, v18, v85
	v_lshl_or_b32 v19, v84, 2, s2
	v_lshrrev_b32_e32 v13, 10, v13
	s_movk_i32 s2, 0x1800
	v_mad_u32_u24 v13, v13, s2, s2
	v_cmp_lt_i32_e32 vcc, s13, v12
	v_lshlrev_b32_e32 v128, 2, v19
	v_readlane_b32 s2, v250, 15
	v_cndmask_b32_e32 v14, 0, v13, vcc
	v_ashrrev_i32_e32 v15, 31, v14
	v_lshlrev_b64 v[24:25], 2, v[14:15]
	v_ashrrev_i32_e32 v13, 31, v12
	v_lshl_add_u64 v[14:15], s[40:41], 0, v[24:25]
	v_lshl_add_u64 v[48:49], v[14:15], 0, v[128:129]
	v_lshlrev_b64 v[14:15], 12, v[12:13]
	v_readlane_b32 s3, v250, 16
	v_lshl_add_u64 v[28:29], s[42:43], 0, v[24:25]
	v_lshlrev_b64 v[32:33], 11, v[12:13]
	v_lshl_add_u64 v[14:15], s[2:3], 0, v[14:15]
	v_lshl_add_u64 v[50:51], v[14:15], 0, v[128:129]
	global_load_dwordx4 v[72:75], v[48:49], off
	global_load_dwordx4 v[80:83], v[48:49], off offset:64
	global_load_dwordx4 v[88:91], v[48:49], off offset:128
	global_load_dwordx4 v[136:139], v[48:49], off offset:192
	global_load_dwordx4 v[194:197], v[50:51], off
	global_load_dwordx4 v[198:201], v[50:51], off offset:64
	global_load_dwordx4 v[202:205], v[50:51], off offset:128
	global_load_dwordx4 v[206:209], v[50:51], off offset:192
	v_add_co_u32_e32 v58, vcc, 0x10000, v50
	s_nop 1
	v_addc_co_u32_e32 v59, vcc, 0, v51, vcc
	global_load_dwordx4 v[210:213], v[58:59], off
	global_load_dwordx4 v[214:217], v[58:59], off offset:64
	global_load_dwordx4 v[218:221], v[58:59], off offset:128
	global_load_dwordx4 v[222:225], v[58:59], off offset:192
	v_readlane_b32 s2, v250, 21
	v_readlane_b32 s3, v250, 22
	v_cmp_eq_u32_e32 vcc, 0, v84
	s_waitcnt vmcnt(4)
	v_pk_fma_f32 v[22:23], v[78:79], v[74:75], v[196:197]
	v_pk_fma_f32 v[20:21], v[76:77], v[72:73], v[194:195]
	global_store_dwordx4 v[50:51], v[20:23], off
	v_lshl_add_u64 v[14:15], v[28:29], 0, v[128:129]
	global_load_dwordx4 v[140:143], v128, s[0:1]
	global_load_dwordx4 v[144:147], v128, s[0:1] offset:64
	global_load_dwordx4 v[148:151], v128, s[0:1] offset:128
	global_load_dwordx4 v[152:155], v128, s[0:1] offset:192
	global_load_dwordx4 v[156:159], v[14:15], off
	global_load_dwordx4 v[160:163], v[14:15], off offset:64
	global_load_dwordx4 v[180:183], v[14:15], off offset:128
	global_load_dwordx4 v[190:193], v[14:15], off offset:192
	v_lshlrev_b32_e32 v16, 1, v19
	v_mov_b32_e32 v17, v129
	v_lshl_add_u64 v[32:33], s[2:3], 0, v[32:33]
	v_lshl_add_u64 v[56:57], v[32:33], 0, v[16:17]
	s_waitcnt vmcnt(0)
	v_pk_mul_f32 v[26:27], v[22:23], v[142:143]
	v_pk_mul_f32 v[24:25], v[20:21], v[140:141]
	s_waitcnt vmcnt(0)
	v_pk_add_f32 v[30:31], v[158:159], 1.0 op_sel_hi:[1,0]
	v_pk_add_f32 v[28:29], v[156:157], 1.0 op_sel_hi:[1,0]
	v_pk_mul_f32 v[26:27], v[26:27], v[30:31]
	v_pk_mul_f32 v[24:25], v[24:25], v[28:29]
	v_and_b32_sdwa v19, v26, v170 dst_sel:DWORD dst_unused:UNUSED_PAD src0_sel:WORD_1 src1_sel:DWORD
	v_and_b32_sdwa v29, v27, v170 dst_sel:DWORD dst_unused:UNUSED_PAD src0_sel:WORD_1 src1_sel:DWORD
	v_and_b32_sdwa v30, v25, v170 dst_sel:DWORD dst_unused:UNUSED_PAD src0_sel:WORD_1 src1_sel:DWORD
	v_and_b32_sdwa v28, v24, v170 dst_sel:DWORD dst_unused:UNUSED_PAD src0_sel:WORD_1 src1_sel:DWORD
	v_add3_u32 v19, v26, v19, s56
	v_add3_u32 v26, v27, v29, s56
	v_add3_u32 v25, v25, v30, s56
	v_add3_u32 v24, v24, v28, s56
	v_and_b32_e32 v26, 0xffff0000, v26
	v_and_b32_e32 v27, 0xffff0000, v25
	v_or_b32_sdwa v25, v26, v19 dst_sel:DWORD dst_unused:UNUSED_PAD src0_sel:DWORD src1_sel:WORD_1
	v_or_b32_sdwa v24, v27, v24 dst_sel:DWORD dst_unused:UNUSED_PAD src0_sel:DWORD src1_sel:WORD_1
	global_store_dwordx2 v[56:57], v[24:25], off
	s_nop 0
	s_waitcnt vmcnt(0)
	v_pk_fma_f32 v[26:27], v[70:71], v[82:83], v[200:201]
	v_pk_fma_f32 v[24:25], v[68:69], v[80:81], v[198:199]
	global_store_dwordx4 v[50:51], v[24:27], off offset:64
	v_pk_mul_f32 v[30:31], v[26:27], v[146:147]
	v_pk_mul_f32 v[28:29], v[24:25], v[144:145]
	v_pk_add_f32 v[34:35], v[162:163], 1.0 op_sel_hi:[1,0]
	v_pk_add_f32 v[32:33], v[160:161], 1.0 op_sel_hi:[1,0]
	v_pk_mul_f32 v[30:31], v[30:31], v[34:35]
	v_pk_mul_f32 v[28:29], v[28:29], v[32:33]
	v_and_b32_sdwa v19, v30, v170 dst_sel:DWORD dst_unused:UNUSED_PAD src0_sel:WORD_1 src1_sel:DWORD
	v_and_b32_sdwa v33, v31, v170 dst_sel:DWORD dst_unused:UNUSED_PAD src0_sel:WORD_1 src1_sel:DWORD
	v_and_b32_sdwa v34, v29, v170 dst_sel:DWORD dst_unused:UNUSED_PAD src0_sel:WORD_1 src1_sel:DWORD
	v_and_b32_sdwa v32, v28, v170 dst_sel:DWORD dst_unused:UNUSED_PAD src0_sel:WORD_1 src1_sel:DWORD
	v_add3_u32 v19, v30, v19, s56
	v_add3_u32 v30, v31, v33, s56
	v_add3_u32 v29, v29, v34, s56
	v_add3_u32 v28, v28, v32, s56
	v_and_b32_e32 v30, 0xffff0000, v30
	v_and_b32_e32 v31, 0xffff0000, v29
	v_or_b32_sdwa v29, v30, v19 dst_sel:DWORD dst_unused:UNUSED_PAD src0_sel:DWORD src1_sel:WORD_1
	v_or_b32_sdwa v28, v31, v28 dst_sel:DWORD dst_unused:UNUSED_PAD src0_sel:DWORD src1_sel:WORD_1
	global_store_dwordx2 v[56:57], v[28:29], off offset:32
	s_nop 0
	v_pk_fma_f32 v[30:31], v[54:55], v[90:91], v[204:205]
	v_pk_fma_f32 v[28:29], v[52:53], v[88:89], v[202:203]
	global_store_dwordx4 v[50:51], v[28:31], off offset:128
	v_pk_mul_f32 v[34:35], v[30:31], v[150:151]
	v_pk_mul_f32 v[32:33], v[28:29], v[148:149]
	v_pk_add_f32 v[46:47], v[182:183], 1.0 op_sel_hi:[1,0]
	v_pk_add_f32 v[44:45], v[180:181], 1.0 op_sel_hi:[1,0]
	v_pk_mul_f32 v[34:35], v[34:35], v[46:47]
	v_pk_mul_f32 v[32:33], v[32:33], v[44:45]
	v_and_b32_sdwa v19, v34, v170 dst_sel:DWORD dst_unused:UNUSED_PAD src0_sel:WORD_1 src1_sel:DWORD
	v_and_b32_sdwa v45, v35, v170 dst_sel:DWORD dst_unused:UNUSED_PAD src0_sel:WORD_1 src1_sel:DWORD
	v_and_b32_sdwa v46, v33, v170 dst_sel:DWORD dst_unused:UNUSED_PAD src0_sel:WORD_1 src1_sel:DWORD
	v_and_b32_sdwa v44, v32, v170 dst_sel:DWORD dst_unused:UNUSED_PAD src0_sel:WORD_1 src1_sel:DWORD
	v_add3_u32 v19, v34, v19, s56
	v_add3_u32 v34, v35, v45, s56
	v_add3_u32 v33, v33, v46, s56
	v_add3_u32 v32, v32, v44, s56
	v_and_b32_e32 v34, 0xffff0000, v34
	v_and_b32_e32 v35, 0xffff0000, v33
	v_or_b32_sdwa v33, v34, v19 dst_sel:DWORD dst_unused:UNUSED_PAD src0_sel:DWORD src1_sel:WORD_1
	v_or_b32_sdwa v32, v35, v32 dst_sel:DWORD dst_unused:UNUSED_PAD src0_sel:DWORD src1_sel:WORD_1
	global_store_dwordx2 v[56:57], v[32:33], off offset:64
	s_nop 0
	v_pk_fma_f32 v[34:35], v[42:43], v[138:139], v[208:209]
	v_pk_fma_f32 v[32:33], v[40:41], v[136:137], v[206:207]
	global_store_dwordx4 v[50:51], v[32:35], off offset:192
	v_mul_f32_e32 v14, v21, v21
	v_mul_f32_e32 v15, v25, v25
	v_fmac_f32_e32 v14, v20, v20
	v_fmac_f32_e32 v15, v24, v24
	v_fmac_f32_e32 v14, v22, v22
	v_fmac_f32_e32 v15, v26, v26
	v_fmac_f32_e32 v14, v23, v23
	v_fmac_f32_e32 v15, v27, v27
	v_add_f32_e32 v14, v14, v15
	v_mul_f32_e32 v15, v29, v29
	v_fmac_f32_e32 v15, v28, v28
	v_fmac_f32_e32 v15, v30, v30
	v_fmac_f32_e32 v15, v31, v31
	v_add_f32_e32 v14, v14, v15
	v_mul_f32_e32 v15, v33, v33
	v_fmac_f32_e32 v15, v32, v32
	v_fmac_f32_e32 v15, v34, v34
	v_fmac_f32_e32 v15, v35, v35
	v_add_f32_e32 v14, v14, v15
	ds_bpermute_b32 v15, v105, v14
	s_waitcnt lgkmcnt(0)
	v_add_f32_e32 v14, v14, v15
	ds_bpermute_b32 v15, v104, v14
	v_pk_mul_f32 v[20:21], v[34:35], v[154:155]
	v_pk_mul_f32 v[22:23], v[32:33], v[152:153]
	v_pk_add_f32 v[24:25], v[192:193], 1.0 op_sel_hi:[1,0]
	v_pk_add_f32 v[26:27], v[190:191], 1.0 op_sel_hi:[1,0]
	v_pk_mul_f32 v[20:21], v[20:21], v[24:25]
	v_pk_mul_f32 v[22:23], v[22:23], v[26:27]
	v_and_b32_sdwa v19, v20, v170 dst_sel:DWORD dst_unused:UNUSED_PAD src0_sel:WORD_1 src1_sel:DWORD
	v_and_b32_sdwa v25, v21, v170 dst_sel:DWORD dst_unused:UNUSED_PAD src0_sel:WORD_1 src1_sel:DWORD
	v_and_b32_sdwa v26, v23, v170 dst_sel:DWORD dst_unused:UNUSED_PAD src0_sel:WORD_1 src1_sel:DWORD
	v_and_b32_sdwa v24, v22, v170 dst_sel:DWORD dst_unused:UNUSED_PAD src0_sel:WORD_1 src1_sel:DWORD
	v_add3_u32 v19, v20, v19, s56
	v_add3_u32 v20, v21, v25, s56
	v_add3_u32 v21, v23, v26, s56
	v_add3_u32 v22, v22, v24, s56
	v_and_b32_e32 v20, 0xffff0000, v20
	v_and_b32_e32 v23, 0xffff0000, v21
	v_or_b32_sdwa v21, v20, v19 dst_sel:DWORD dst_unused:UNUSED_PAD src0_sel:DWORD src1_sel:WORD_1
	v_or_b32_sdwa v20, v23, v22 dst_sel:DWORD dst_unused:UNUSED_PAD src0_sel:DWORD src1_sel:WORD_1
	global_store_dwordx2 v[56:57], v[20:21], off offset:96
	s_and_saveexec_b64 s[2:3], vcc
	s_cbranch_execz .LBB0_422
	v_readlane_b32 s16, v253, 20
	s_add_u32 s24, s38, s16
	s_addc_u32 s25, s39, 0
	v_lshl_add_u64 v[20:21], v[12:13], 2, s[24:25]
	s_waitcnt lgkmcnt(0)
	v_add_f32_e32 v13, v14, v15
	global_store_dword v[20:21], v13, off

.LBB0_582:
	s_add_i32 s0, s1, 2
	v_add_u32_e32 v111, v104, v105
	ds_read_b128 v[136:139], v111 offset:16384
	ds_read_b128 v[140:143], v111 offset:18432
	ds_read_b128 v[144:147], v111 offset:20480
	ds_read_b128 v[148:151], v111 offset:22528
	v_add_u32_e32 v110, v103, v105
	ds_read_b128 v[116:119], v110
	s_add_i32 s1, s1, 4
	ds_read_b128 v[120:123], v110 offset:2048
	s_min_u32 s1, s1, 63
	v_add_u32_e32 v113, v104, v114
	s_lshl_b32 s92, s1, 7
	ds_read_b128 v[124:127], v110 offset:4096
	v_add_u32_e32 v112, v103, v114
	ds_read_b128 v[194:197], v113 offset:16384
	ds_read_b128 v[198:201], v113 offset:18432
	ds_read_b128 v[202:205], v113 offset:20480
	ds_read_b128 v[206:209], v113 offset:22528
	v_lshl_add_u64 v[164:165], v[98:99], 0, s[92:93]
	ds_read_b128 v[132:135], v110 offset:6144
	ds_read_b128 v[152:155], v112
	ds_read_b128 v[156:159], v112 offset:2048
	ds_read_b128 v[160:163], v112 offset:4096
	ds_read_b128 v[190:193], v112 offset:6144
	s_waitcnt lgkmcnt(11)
	v_mfma_f32_16x16x32_bf16 v[92:95], v[136:139], v[116:119], v[92:95]
	v_mfma_f32_16x16x32_bf16 v[88:91], v[140:143], v[116:119], v[88:91]
	v_mfma_f32_16x16x32_bf16 v[52:55], v[144:147], v[116:119], v[52:55]
	v_mfma_f32_16x16x32_bf16 v[48:51], v[148:151], v[116:119], v[48:51]
	global_load_dwordx4 v[116:119], v[164:165], off
	s_waitcnt vmcnt(6)
	ds_write_b128 v109, v[56:59] offset:32768
	v_add_co_u32_e32 v56, vcc, s7, v164
	s_waitcnt lgkmcnt(11)
	v_mfma_f32_16x16x32_bf16 v[44:47], v[136:139], v[120:123], v[44:47]
	v_addc_co_u32_e32 v57, vcc, 0, v165, vcc
	v_mfma_f32_16x16x32_bf16 v[40:43], v[140:143], v[120:123], v[40:43]
	v_mfma_f32_16x16x32_bf16 v[36:39], v[144:147], v[120:123], v[36:39]
	v_mfma_f32_16x16x32_bf16 v[32:35], v[148:151], v[120:123], v[32:35]
	global_load_dwordx4 v[120:123], v[56:57], off
	v_add_co_u32_e32 v56, vcc, s52, v164
	ds_write_b128 v109, v[60:63] offset:36864
	s_nop 0
	v_addc_co_u32_e32 v57, vcc, 0, v165, vcc
	s_waitcnt lgkmcnt(11)
	v_mfma_f32_16x16x32_bf16 v[28:31], v[136:139], v[124:127], v[28:31]
	v_mfma_f32_16x16x32_bf16 v[24:27], v[140:143], v[124:127], v[24:27]
	v_mfma_f32_16x16x32_bf16 v[20:23], v[144:147], v[124:127], v[20:23]
	v_mfma_f32_16x16x32_bf16 v[16:19], v[148:151], v[124:127], v[16:19]
	global_load_dwordx4 v[124:127], v[56:57], off
	v_add_co_u32_e32 v56, vcc, s34, v164
	ds_write_b128 v109, v[64:67] offset:40960
	s_nop 0
	v_addc_co_u32_e32 v57, vcc, 0, v165, vcc
	v_lshl_add_u64 v[64:65], v[100:101], 0, s[92:93]
	v_add_co_u32_e32 v66, vcc, s7, v64
	s_waitcnt lgkmcnt(7)
	v_mfma_f32_16x16x32_bf16 v[12:15], v[136:139], v[132:135], v[12:15]
	v_addc_co_u32_e32 v67, vcc, 0, v65, vcc
	v_mfma_f32_16x16x32_bf16 v[8:11], v[140:143], v[132:135], v[8:11]
	v_mfma_f32_16x16x32_bf16 v[4:7], v[144:147], v[132:135], v[4:7]
	v_mfma_f32_16x16x32_bf16 v[0:3], v[148:151], v[132:135], v[0:3]
	global_load_dwordx4 v[132:135], v[56:57], off
	s_waitcnt vmcnt(7)
	ds_write_b128 v109, v[72:75] offset:45056
	s_waitcnt lgkmcnt(7)
	v_mfma_f32_16x16x32_bf16 v[56:59], v[194:197], v[152:155], v[92:95]
	v_mfma_f32_16x16x32_bf16 v[60:63], v[198:201], v[152:155], v[88:91]
	v_mfma_f32_16x16x32_bf16 v[52:55], v[202:205], v[152:155], v[52:55]
	v_mfma_f32_16x16x32_bf16 v[48:51], v[206:209], v[152:155], v[48:51]
	global_load_dwordx4 v[136:139], v[64:65], off
	ds_write_b128 v109, v[68:71] offset:49152
	s_waitcnt lgkmcnt(7)
	v_mfma_f32_16x16x32_bf16 v[44:47], v[194:197], v[156:159], v[44:47]
	v_mfma_f32_16x16x32_bf16 v[40:43], v[198:201], v[156:159], v[40:43]
	v_mfma_f32_16x16x32_bf16 v[36:39], v[202:205], v[156:159], v[36:39]
	v_mfma_f32_16x16x32_bf16 v[32:35], v[206:209], v[156:159], v[32:35]
	global_load_dwordx4 v[140:143], v[66:67], off
	v_add_co_u32_e32 v66, vcc, s52, v64
	s_waitcnt vmcnt(8)
	ds_write_b128 v109, v[76:79] offset:53248
	v_addc_co_u32_e32 v67, vcc, 0, v65, vcc
	v_add_co_u32_e32 v64, vcc, s34, v64
	s_waitcnt lgkmcnt(7)
	v_mfma_f32_16x16x32_bf16 v[28:31], v[194:197], v[160:163], v[28:31]
	v_addc_co_u32_e32 v65, vcc, 0, v65, vcc
	v_mfma_f32_16x16x32_bf16 v[24:27], v[198:201], v[160:163], v[24:27]
	v_mfma_f32_16x16x32_bf16 v[20:23], v[202:205], v[160:163], v[20:23]
	v_mfma_f32_16x16x32_bf16 v[16:19], v[206:209], v[160:163], v[16:19]
	global_load_dwordx4 v[144:147], v[66:67], off
	s_waitcnt vmcnt(8)
	ds_write_b128 v109, v[80:83] offset:57344
	s_waitcnt lgkmcnt(7)
	v_mfma_f32_16x16x32_bf16 v[12:15], v[194:197], v[190:193], v[12:15]
	v_mfma_f32_16x16x32_bf16 v[8:11], v[198:201], v[190:193], v[8:11]
	v_mfma_f32_16x16x32_bf16 v[4:7], v[202:205], v[190:193], v[4:7]
	v_mfma_f32_16x16x32_bf16 v[0:3], v[206:209], v[190:193], v[0:3]
	global_load_dwordx4 v[148:151], v[64:65], off
	s_waitcnt vmcnt(8)
	ds_write_b128 v109, v[84:87] offset:61440
	s_waitcnt lgkmcnt(0)
	s_barrier
	ds_read_b128 v[84:87], v111 offset:51200
	ds_read_b128 v[80:83], v111 offset:49152
	ds_read_b128 v[88:91], v111 offset:53248
	ds_read_b128 v[92:95], v111 offset:55296
	ds_read_b128 v[64:67], v110 offset:32768
	s_min_u32 s1, s0, 60
	s_lshl_b32 s92, s1, 7
	ds_read_b128 v[68:71], v110 offset:34816
	v_lshl_add_u64 v[164:165], v[98:99], 0, s[92:93]
	ds_read_b128 v[72:75], v110 offset:36864
	ds_read_b128 v[76:79], v110 offset:38912
	ds_read_b128 v[152:155], v112 offset:32768
	ds_read_b128 v[156:159], v112 offset:34816
	ds_read_b128 v[160:163], v112 offset:36864
	ds_read_b128 v[190:193], v112 offset:38912
	ds_read_b128 v[194:197], v113 offset:49152
	ds_read_b128 v[198:201], v113 offset:51200
	ds_read_b128 v[202:205], v113 offset:53248
	ds_read_b128 v[206:209], v113 offset:55296
	s_waitcnt lgkmcnt(11)
	v_mfma_f32_16x16x32_bf16 v[214:217], v[84:87], v[64:67], v[60:63]
	v_mfma_f32_16x16x32_bf16 v[210:213], v[80:83], v[64:67], v[56:59]
	s_nop 1
	v_add_co_u32_e32 v60, vcc, s7, v164
	s_nop 1
	v_addc_co_u32_e32 v61, vcc, 0, v165, vcc
	v_mfma_f32_16x16x32_bf16 v[52:55], v[88:91], v[64:67], v[52:55]
	v_mfma_f32_16x16x32_bf16 v[48:51], v[92:95], v[64:67], v[48:51]
	v_add_co_u32_e32 v64, vcc, s52, v164
	global_load_dwordx4 v[56:59], v[164:165], off offset:384
	s_nop 0
	v_addc_co_u32_e32 v65, vcc, 0, v165, vcc
	s_waitcnt vmcnt(8)
	ds_write_b128 v109, v[116:119]
	s_waitcnt lgkmcnt(11)
	v_mfma_f32_16x16x32_bf16 v[44:47], v[80:83], v[68:71], v[44:47]
	v_mfma_f32_16x16x32_bf16 v[40:43], v[84:87], v[68:71], v[40:43]
	v_mfma_f32_16x16x32_bf16 v[36:39], v[88:91], v[68:71], v[36:39]
	v_mfma_f32_16x16x32_bf16 v[32:35], v[92:95], v[68:71], v[32:35]
	v_add_co_u32_e32 v68, vcc, s34, v164
	global_load_dwordx4 v[60:63], v[60:61], off offset:384
	s_waitcnt vmcnt(8)
	ds_write_b128 v109, v[120:123] offset:4096
	s_waitcnt lgkmcnt(11)
	v_mfma_f32_16x16x32_bf16 v[28:31], v[80:83], v[72:75], v[28:31]
	v_addc_co_u32_e32 v69, vcc, 0, v165, vcc
	v_mfma_f32_16x16x32_bf16 v[24:27], v[84:87], v[72:75], v[24:27]
	v_mfma_f32_16x16x32_bf16 v[20:23], v[88:91], v[72:75], v[20:23]
	v_mfma_f32_16x16x32_bf16 v[16:19], v[92:95], v[72:75], v[16:19]
	global_load_dwordx4 v[64:67], v[64:65], off offset:384
	s_waitcnt vmcnt(8)
	ds_write_b128 v109, v[124:127] offset:8192
	s_waitcnt lgkmcnt(11)
	v_mfma_f32_16x16x32_bf16 v[8:11], v[84:87], v[76:79], v[8:11]
	v_lshl_add_u64 v[84:85], v[100:101], 0, s[92:93]
	v_mfma_f32_16x16x32_bf16 v[12:15], v[80:83], v[76:79], v[12:15]
	v_mfma_f32_16x16x32_bf16 v[4:7], v[88:91], v[76:79], v[4:7]
	v_mfma_f32_16x16x32_bf16 v[0:3], v[92:95], v[76:79], v[0:3]
	v_add_co_u32_e32 v76, vcc, s7, v84
	global_load_dwordx4 v[72:75], v[68:69], off offset:384
	s_nop 0
	v_addc_co_u32_e32 v77, vcc, 0, v85, vcc
	v_add_co_u32_e32 v80, vcc, s52, v84
	s_waitcnt vmcnt(8)
	ds_write_b128 v109, v[132:135] offset:12288
	v_addc_co_u32_e32 v81, vcc, 0, v85, vcc
	s_waitcnt lgkmcnt(7)
	v_mfma_f32_16x16x32_bf16 v[92:95], v[194:197], v[152:155], v[210:213]
	s_waitcnt lgkmcnt(6)
	v_mfma_f32_16x16x32_bf16 v[88:91], v[198:201], v[152:155], v[214:217]
	s_waitcnt lgkmcnt(5)
	v_mfma_f32_16x16x32_bf16 v[52:55], v[202:205], v[152:155], v[52:55]
	s_waitcnt lgkmcnt(4)
	v_mfma_f32_16x16x32_bf16 v[48:51], v[206:209], v[152:155], v[48:51]
	global_load_dwordx4 v[68:71], v[84:85], off offset:384
	v_add_co_u32_e32 v84, vcc, s34, v84
	s_waitcnt vmcnt(8)
	ds_write_b128 v109, v[136:139] offset:16384
	v_addc_co_u32_e32 v85, vcc, 0, v85, vcc
	v_mfma_f32_16x16x32_bf16 v[44:47], v[194:197], v[156:159], v[44:47]
	v_mfma_f32_16x16x32_bf16 v[40:43], v[198:201], v[156:159], v[40:43]
	v_mfma_f32_16x16x32_bf16 v[36:39], v[202:205], v[156:159], v[36:39]
	v_mfma_f32_16x16x32_bf16 v[32:35], v[206:209], v[156:159], v[32:35]
	global_load_dwordx4 v[76:79], v[76:77], off offset:384
	s_waitcnt vmcnt(8)
	ds_write_b128 v109, v[140:143] offset:20480
	v_mfma_f32_16x16x32_bf16 v[28:31], v[194:197], v[160:163], v[28:31]
	v_mfma_f32_16x16x32_bf16 v[24:27], v[198:201], v[160:163], v[24:27]
	v_mfma_f32_16x16x32_bf16 v[20:23], v[202:205], v[160:163], v[20:23]
	v_mfma_f32_16x16x32_bf16 v[16:19], v[206:209], v[160:163], v[16:19]
	global_load_dwordx4 v[80:83], v[80:81], off offset:384
	s_waitcnt vmcnt(8)
	ds_write_b128 v109, v[144:147] offset:24576
	v_mfma_f32_16x16x32_bf16 v[12:15], v[194:197], v[190:193], v[12:15]
	v_mfma_f32_16x16x32_bf16 v[8:11], v[198:201], v[190:193], v[8:11]
	v_mfma_f32_16x16x32_bf16 v[4:7], v[202:205], v[190:193], v[4:7]
	v_mfma_f32_16x16x32_bf16 v[0:3], v[206:209], v[190:193], v[0:3]
	global_load_dwordx4 v[84:87], v[84:85], off offset:384
	s_waitcnt vmcnt(8)
	ds_write_b128 v109, v[148:151] offset:28672
	s_cmp_lt_u32 s0, 62
	s_mov_b32 s1, s0
	s_waitcnt lgkmcnt(0)
	s_barrier
	s_cbranch_scc1 .LBB0_582
	s_or_b32 s0, s69, 1
	s_mul_i32 s1, s69, 0x12000
	v_readlane_b32 s26, v250, 25
	v_readlane_b32 s27, v250, 26
	s_add_u32 s1, s26, s1
	s_addc_u32 s24, s27, 0
	s_add_u32 s38, s1, 0x5000
	v_readlane_b32 s1, v251, 5
	v_lshlrev_b32_e32 v114, 6, v102
	v_lshlrev_b32_e32 v115, 2, v97
	s_waitcnt vmcnt(5)
	v_add_u32_e32 v64, s1, v108
	v_readlane_b32 s1, v251, 6
	v_add_u32_e32 v56, 0xffffe000, v64
	v_or_b32_e32 v62, v64, v107
	v_or_b32_e32 v65, s1, v114
	v_lshrrev_b32_e32 v56, 10, v56
	s_movk_i32 s1, 0x1800
	v_mad_u32_u24 v56, v56, s1, s1
	v_cmp_lt_i32_e32 vcc, s13, v62
	v_or_b32_e32 v58, v65, v115
	s_addc_u32 s39, s24, 0
	v_cndmask_b32_e32 v56, 0, v56, vcc
	v_ashrrev_i32_e32 v57, 31, v56
	s_waitcnt vmcnt(4)
	v_lshlrev_b64 v[74:75], 2, v[56:57]
	v_ashrrev_i32_e32 v59, 31, v58
	v_ashrrev_i32_e32 v63, 31, v62
	v_lshl_add_u64 v[56:57], s[38:39], 0, v[74:75]
	v_lshlrev_b64 v[60:61], 2, v[58:59]
	v_readlane_b32 s16, v250, 15
	s_waitcnt vmcnt(1)
	v_lshl_add_u64 v[82:83], v[56:57], 0, v[60:61]
	v_lshlrev_b64 v[56:57], 12, v[62:63]
	v_readlane_b32 s17, v250, 16
	v_readlane_b32 s68, v250, 41
	s_mul_i32 s24, s0, 0x12000
	v_lshl_add_u64 v[56:57], s[16:17], 0, v[56:57]
	s_waitcnt vmcnt(0)
	v_lshl_add_u64 v[84:85], v[56:57], 0, v[60:61]
	global_load_dwordx4 v[116:119], v[82:83], off
	global_load_dwordx4 v[120:123], v[82:83], off offset:64
	global_load_dwordx4 v[124:127], v[82:83], off offset:128
	global_load_dwordx4 v[132:135], v[82:83], off offset:192
	global_load_dwordx4 v[190:193], v[84:85], off
	global_load_dwordx4 v[194:197], v[84:85], off offset:64
	global_load_dwordx4 v[198:201], v[84:85], off offset:128
	global_load_dwordx4 v[202:205], v[84:85], off offset:192
	v_add_co_u32_e32 v164, vcc, 0x10000, v84
	s_nop 1
	v_addc_co_u32_e32 v165, vcc, 0, v85, vcc
	v_add_co_u32_e32 v222, vcc, 0x20000, v84
	s_nop 1
	v_addc_co_u32_e32 v223, vcc, 0, v85, vcc
	v_add_co_u32_e32 v224, vcc, 0x30000, v84
	s_nop 1
	v_addc_co_u32_e32 v225, vcc, 0, v85, vcc
	global_load_dwordx4 v[206:209], v[164:165], off
	global_load_dwordx4 v[210:213], v[164:165], off offset:64
	global_load_dwordx4 v[214:217], v[164:165], off offset:128
	global_load_dwordx4 v[218:221], v[164:165], off offset:192
	s_lshl_b32 s0, s0, 12
	v_readlane_b32 s70, v250, 43
	v_readlane_b32 s71, v250, 44
	s_add_u32 s0, s70, s0
	s_addc_u32 s1, s71, 0
	s_add_u32 s24, s26, s24
	s_addc_u32 s25, s27, 0
	s_add_u32 s40, s24, 0x1000
	s_addc_u32 s41, s25, 0
	v_lshl_add_u64 v[74:75], s[40:41], 0, v[74:75]
	v_lshl_add_u64 v[56:57], s[0:1], 0, v[60:61]
	v_lshl_add_u64 v[86:87], v[74:75], 0, v[60:61]
	v_readlane_b32 s16, v250, 21
	v_lshlrev_b64 v[78:79], 11, v[62:63]
	v_readlane_b32 s17, v250, 22
	v_readlane_b32 s69, v250, 42
	v_readlane_b32 s69, v254, 49
	v_lshl_add_u64 v[78:79], s[16:17], 0, v[78:79]
	s_mul_i32 s24, s69, 0x140000
	s_add_u32 s24, s86, s24
	s_mov_b32 s16, 0xa000
	s_addc_u32 s25, s87, 0
	s_add_u32 s26, s24, 0xafba000
	s_addc_u32 s27, s25, 0
	v_cmp_eq_u32_e64 s[36:37], 0, v97
	v_readlane_b32 s72, v250, 45
	v_readlane_b32 s73, v250, 46
	v_readlane_b32 s74, v250, 47
	v_readlane_b32 s75, v250, 48
	v_readlane_b32 s76, v250, 49
	v_readlane_b32 s77, v250, 50
	v_readlane_b32 s78, v250, 51
	v_readlane_b32 s79, v250, 52
	v_readlane_b32 s80, v250, 53
	v_readlane_b32 s81, v250, 54
	v_readlane_b32 s82, v250, 55
	v_readlane_b32 s83, v250, 56
	s_waitcnt vmcnt(4)
	v_pk_fma_f32 v[68:69], v[94:95], v[118:119], v[192:193]
	v_pk_fma_f32 v[66:67], v[92:93], v[116:117], v[190:191]
	global_store_dwordx4 v[84:85], v[66:69], off
	global_load_dwordx4 v[136:139], v[56:57], off
	global_load_dwordx4 v[140:143], v[56:57], off offset:64
	global_load_dwordx4 v[144:147], v[56:57], off offset:128
	global_load_dwordx4 v[148:151], v[56:57], off offset:192
	global_load_dwordx4 v[152:155], v[86:87], off
	global_load_dwordx4 v[156:159], v[86:87], off offset:64
	global_load_dwordx4 v[160:163], v[86:87], off offset:128
	global_load_dwordx4 v[180:183], v[86:87], off offset:192
	v_lshl_add_u64 v[92:93], v[58:59], 1, v[78:79]
	s_waitcnt vmcnt(0)
	v_pk_mul_f32 v[72:73], v[68:69], v[138:139]
	v_pk_mul_f32 v[70:71], v[66:67], v[136:137]
	s_waitcnt vmcnt(0)
	v_pk_add_f32 v[76:77], v[154:155], 1.0 op_sel_hi:[1,0]
	v_pk_add_f32 v[74:75], v[152:153], 1.0 op_sel_hi:[1,0]
	v_pk_mul_f32 v[72:73], v[72:73], v[76:77]
	v_pk_mul_f32 v[70:71], v[70:71], v[74:75]
	v_and_b32_sdwa v76, v73, v170 dst_sel:DWORD dst_unused:UNUSED_PAD src0_sel:WORD_1 src1_sel:DWORD
	v_and_b32_sdwa v77, v71, v170 dst_sel:DWORD dst_unused:UNUSED_PAD src0_sel:WORD_1 src1_sel:DWORD
	v_and_b32_sdwa v74, v72, v170 dst_sel:DWORD dst_unused:UNUSED_PAD src0_sel:WORD_1 src1_sel:DWORD
	v_and_b32_sdwa v75, v70, v170 dst_sel:DWORD dst_unused:UNUSED_PAD src0_sel:WORD_1 src1_sel:DWORD
	v_add3_u32 v73, v73, v76, s56
	v_add3_u32 v71, v71, v77, s56
	v_add3_u32 v70, v70, v75, s56
	v_add3_u32 v72, v72, v74, s56
	v_and_b32_e32 v73, 0xffff0000, v73
	v_and_b32_e32 v74, 0xffff0000, v71
	v_or_b32_sdwa v71, v73, v72 dst_sel:DWORD dst_unused:UNUSED_PAD src0_sel:DWORD src1_sel:WORD_1
	v_or_b32_sdwa v70, v74, v70 dst_sel:DWORD dst_unused:UNUSED_PAD src0_sel:DWORD src1_sel:WORD_1
	global_store_dwordx2 v[92:93], v[70:71], off
	s_nop 0
	s_waitcnt vmcnt(0)
	v_pk_fma_f32 v[72:73], v[90:91], v[122:123], v[196:197]
	v_pk_fma_f32 v[70:71], v[88:89], v[120:121], v[194:195]
	global_store_dwordx4 v[84:85], v[70:73], off offset:64
	v_pk_mul_f32 v[76:77], v[72:73], v[142:143]
	v_pk_mul_f32 v[74:75], v[70:71], v[140:141]
	v_pk_add_f32 v[80:81], v[158:159], 1.0 op_sel_hi:[1,0]
	v_pk_add_f32 v[78:79], v[156:157], 1.0 op_sel_hi:[1,0]
	v_pk_mul_f32 v[76:77], v[76:77], v[80:81]
	v_pk_mul_f32 v[74:75], v[74:75], v[78:79]
	v_and_b32_sdwa v80, v77, v170 dst_sel:DWORD dst_unused:UNUSED_PAD src0_sel:WORD_1 src1_sel:DWORD
	v_and_b32_sdwa v81, v75, v170 dst_sel:DWORD dst_unused:UNUSED_PAD src0_sel:WORD_1 src1_sel:DWORD
	v_and_b32_sdwa v78, v76, v170 dst_sel:DWORD dst_unused:UNUSED_PAD src0_sel:WORD_1 src1_sel:DWORD
	v_and_b32_sdwa v79, v74, v170 dst_sel:DWORD dst_unused:UNUSED_PAD src0_sel:WORD_1 src1_sel:DWORD
	v_add3_u32 v77, v77, v80, s56
	v_add3_u32 v75, v75, v81, s56
	v_add3_u32 v74, v74, v79, s56
	v_add3_u32 v76, v76, v78, s56
	v_and_b32_e32 v77, 0xffff0000, v77
	v_and_b32_e32 v78, 0xffff0000, v75
	v_or_b32_sdwa v75, v77, v76 dst_sel:DWORD dst_unused:UNUSED_PAD src0_sel:DWORD src1_sel:WORD_1
	v_or_b32_sdwa v74, v78, v74 dst_sel:DWORD dst_unused:UNUSED_PAD src0_sel:DWORD src1_sel:WORD_1
	global_store_dwordx2 v[92:93], v[74:75], off offset:32
	s_nop 0
	v_pk_fma_f32 v[54:55], v[54:55], v[126:127], v[200:201]
	v_pk_fma_f32 v[52:53], v[52:53], v[124:125], v[198:199]
	global_store_dwordx4 v[84:85], v[52:55], off offset:128
	v_pk_mul_f32 v[76:77], v[54:55], v[146:147]
	v_pk_mul_f32 v[74:75], v[52:53], v[144:145]
	v_pk_add_f32 v[80:81], v[162:163], 1.0 op_sel_hi:[1,0]
	v_pk_add_f32 v[78:79], v[160:161], 1.0 op_sel_hi:[1,0]
	v_pk_mul_f32 v[76:77], v[76:77], v[80:81]
	v_pk_mul_f32 v[74:75], v[74:75], v[78:79]
	v_and_b32_sdwa v80, v77, v170 dst_sel:DWORD dst_unused:UNUSED_PAD src0_sel:WORD_1 src1_sel:DWORD
	v_and_b32_sdwa v81, v75, v170 dst_sel:DWORD dst_unused:UNUSED_PAD src0_sel:WORD_1 src1_sel:DWORD
	v_and_b32_sdwa v78, v76, v170 dst_sel:DWORD dst_unused:UNUSED_PAD src0_sel:WORD_1 src1_sel:DWORD
	v_and_b32_sdwa v79, v74, v170 dst_sel:DWORD dst_unused:UNUSED_PAD src0_sel:WORD_1 src1_sel:DWORD
	v_add3_u32 v77, v77, v80, s56
	v_add3_u32 v75, v75, v81, s56
	v_add3_u32 v74, v74, v79, s56
	v_add3_u32 v76, v76, v78, s56
	v_and_b32_e32 v77, 0xffff0000, v77
	v_and_b32_e32 v78, 0xffff0000, v75
	v_or_b32_sdwa v75, v77, v76 dst_sel:DWORD dst_unused:UNUSED_PAD src0_sel:DWORD src1_sel:WORD_1
	v_or_b32_sdwa v74, v78, v74 dst_sel:DWORD dst_unused:UNUSED_PAD src0_sel:DWORD src1_sel:WORD_1
	global_store_dwordx2 v[92:93], v[74:75], off offset:64
	s_nop 0
	v_pk_fma_f32 v[76:77], v[50:51], v[134:135], v[204:205]
	v_pk_fma_f32 v[74:75], v[48:49], v[132:133], v[202:203]
	global_store_dwordx4 v[84:85], v[74:77], off offset:192
	s_nop 0
	v_mul_f32_e32 v50, v67, v67
	v_mul_f32_e32 v51, v71, v71
	v_fmac_f32_e32 v50, v66, v66
	v_fmac_f32_e32 v51, v70, v70
	v_fmac_f32_e32 v50, v68, v68
	v_fmac_f32_e32 v51, v72, v72
	v_fmac_f32_e32 v50, v69, v69
	v_fmac_f32_e32 v51, v73, v73
	v_add_f32_e32 v50, v50, v51
	v_mul_f32_e32 v51, v53, v53
	v_fmac_f32_e32 v51, v52, v52
	v_fmac_f32_e32 v51, v54, v54
	v_fmac_f32_e32 v51, v55, v55
	v_add_f32_e32 v50, v50, v51
	v_mul_f32_e32 v51, v75, v75
	v_xor_b32_e32 v48, 16, v176
	v_fmac_f32_e32 v51, v74, v74
	v_cmp_lt_i32_e32 vcc, v48, v177
	v_fmac_f32_e32 v51, v76, v76
	v_fmac_f32_e32 v51, v77, v77
	v_cndmask_b32_e32 v48, v176, v48, vcc
	v_lshlrev_b32_e32 v105, 2, v48
	v_add_f32_e32 v50, v50, v51
	ds_bpermute_b32 v51, v105, v50
	v_xor_b32_e32 v49, 32, v176
	v_cmp_lt_i32_e32 vcc, v49, v177
	v_lshrrev_b32_e32 v48, 6, v65
	v_mul_lo_u32 v48, v48, s16
	v_cndmask_b32_e32 v49, v176, v49, vcc
	v_lshlrev_b32_e32 v104, 2, v49
	s_waitcnt lgkmcnt(0)
	v_add_f32_e32 v50, v50, v51
	ds_bpermute_b32 v51, v104, v50
	v_ashrrev_i32_e32 v49, 31, v48
	v_lshl_add_u64 v[48:49], s[26:27], 0, v[48:49]
	v_lshl_add_u64 v[48:49], v[62:63], 2, v[48:49]
	v_pk_mul_f32 v[52:53], v[76:77], v[150:151]
	v_pk_mul_f32 v[54:55], v[74:75], v[148:149]
	v_pk_add_f32 v[66:67], v[182:183], 1.0 op_sel_hi:[1,0]
	v_pk_add_f32 v[68:69], v[180:181], 1.0 op_sel_hi:[1,0]
	v_pk_mul_f32 v[52:53], v[52:53], v[66:67]
	v_pk_mul_f32 v[54:55], v[54:55], v[68:69]
	v_and_b32_sdwa v67, v53, v170 dst_sel:DWORD dst_unused:UNUSED_PAD src0_sel:WORD_1 src1_sel:DWORD
	v_and_b32_sdwa v68, v55, v170 dst_sel:DWORD dst_unused:UNUSED_PAD src0_sel:WORD_1 src1_sel:DWORD
	v_and_b32_sdwa v65, v52, v170 dst_sel:DWORD dst_unused:UNUSED_PAD src0_sel:WORD_1 src1_sel:DWORD
	v_and_b32_sdwa v66, v54, v170 dst_sel:DWORD dst_unused:UNUSED_PAD src0_sel:WORD_1 src1_sel:DWORD
	v_add3_u32 v53, v53, v67, s56
	v_add3_u32 v55, v55, v68, s56
	v_add3_u32 v54, v54, v66, s56
	v_add3_u32 v52, v52, v65, s56
	v_and_b32_e32 v53, 0xffff0000, v53
	v_and_b32_e32 v55, 0xffff0000, v55
	v_or_b32_sdwa v53, v53, v52 dst_sel:DWORD dst_unused:UNUSED_PAD src0_sel:DWORD src1_sel:WORD_1
	v_or_b32_sdwa v52, v55, v54 dst_sel:DWORD dst_unused:UNUSED_PAD src0_sel:DWORD src1_sel:WORD_1
	global_store_dwordx2 v[92:93], v[52:53], off offset:96
	s_and_saveexec_b64 s[24:25], s[36:37]
	s_cbranch_execz .LBB0_585
	s_waitcnt lgkmcnt(0)
	v_add_f32_e32 v50, v50, v51
	global_store_dword v[48:49], v50, off

.LBB0_596:
	s_add_i32 s29, s42, 2
	ds_read_b128 v[136:139], v111 offset:16384
	ds_read_b128 v[140:143], v111 offset:18432
	ds_read_b128 v[144:147], v111 offset:20480
	ds_read_b128 v[148:151], v111 offset:22528
	ds_read_b128 v[116:119], v110
	s_add_i32 s42, s42, 4
	ds_read_b128 v[120:123], v110 offset:2048
	s_min_u32 s42, s42, 63
	s_lshl_b32 s92, s42, 7
	ds_read_b128 v[124:127], v110 offset:4096
	ds_read_b128 v[194:197], v113 offset:16384
	ds_read_b128 v[198:201], v113 offset:18432
	ds_read_b128 v[202:205], v113 offset:20480
	ds_read_b128 v[206:209], v113 offset:22528
	v_lshl_add_u64 v[164:165], v[100:101], 0, s[92:93]
	ds_read_b128 v[132:135], v110 offset:6144
	ds_read_b128 v[152:155], v112
	ds_read_b128 v[156:159], v112 offset:2048
	ds_read_b128 v[160:163], v112 offset:4096
	ds_read_b128 v[190:193], v112 offset:6144
	s_waitcnt lgkmcnt(11)
	v_mfma_f32_16x16x32_bf16 v[92:95], v[136:139], v[116:119], v[92:95]
	v_mfma_f32_16x16x32_bf16 v[88:91], v[140:143], v[116:119], v[88:91]
	v_mfma_f32_16x16x32_bf16 v[56:59], v[144:147], v[116:119], v[56:59]
	v_mfma_f32_16x16x32_bf16 v[48:51], v[148:151], v[116:119], v[48:51]
	global_load_dwordx4 v[116:119], v[164:165], off
	s_waitcnt vmcnt(6)
	ds_write_b128 v109, v[52:55] offset:32768
	v_add_co_u32_e32 v52, vcc, s7, v164
	s_waitcnt lgkmcnt(11)
	v_mfma_f32_16x16x32_bf16 v[44:47], v[136:139], v[120:123], v[44:47]
	v_addc_co_u32_e32 v53, vcc, 0, v165, vcc
	v_mfma_f32_16x16x32_bf16 v[40:43], v[140:143], v[120:123], v[40:43]
	v_mfma_f32_16x16x32_bf16 v[36:39], v[144:147], v[120:123], v[36:39]
	v_mfma_f32_16x16x32_bf16 v[32:35], v[148:151], v[120:123], v[32:35]
	global_load_dwordx4 v[120:123], v[52:53], off
	v_add_co_u32_e32 v52, vcc, s52, v164
	ds_write_b128 v109, v[60:63] offset:36864
	s_nop 0
	v_addc_co_u32_e32 v53, vcc, 0, v165, vcc
	s_waitcnt lgkmcnt(11)
	v_mfma_f32_16x16x32_bf16 v[28:31], v[136:139], v[124:127], v[28:31]
	v_mfma_f32_16x16x32_bf16 v[24:27], v[140:143], v[124:127], v[24:27]
	v_mfma_f32_16x16x32_bf16 v[20:23], v[144:147], v[124:127], v[20:23]
	v_mfma_f32_16x16x32_bf16 v[16:19], v[148:151], v[124:127], v[16:19]
	global_load_dwordx4 v[124:127], v[52:53], off
	v_add_co_u32_e32 v52, vcc, s34, v164
	ds_write_b128 v109, v[64:67] offset:40960
	s_nop 0
	v_addc_co_u32_e32 v53, vcc, 0, v165, vcc
	v_lshl_add_u64 v[64:65], v[102:103], 0, s[92:93]
	v_add_co_u32_e32 v66, vcc, s7, v64
	s_waitcnt lgkmcnt(7)
	v_mfma_f32_16x16x32_bf16 v[12:15], v[136:139], v[132:135], v[12:15]
	v_addc_co_u32_e32 v67, vcc, 0, v65, vcc
	v_mfma_f32_16x16x32_bf16 v[8:11], v[140:143], v[132:135], v[8:11]
	v_mfma_f32_16x16x32_bf16 v[4:7], v[144:147], v[132:135], v[4:7]
	v_mfma_f32_16x16x32_bf16 v[0:3], v[148:151], v[132:135], v[0:3]
	global_load_dwordx4 v[132:135], v[52:53], off
	s_waitcnt vmcnt(7)
	ds_write_b128 v109, v[72:75] offset:45056
	s_waitcnt lgkmcnt(7)
	v_mfma_f32_16x16x32_bf16 v[52:55], v[194:197], v[152:155], v[92:95]
	v_mfma_f32_16x16x32_bf16 v[60:63], v[198:201], v[152:155], v[88:91]
	v_mfma_f32_16x16x32_bf16 v[56:59], v[202:205], v[152:155], v[56:59]
	v_mfma_f32_16x16x32_bf16 v[48:51], v[206:209], v[152:155], v[48:51]
	global_load_dwordx4 v[136:139], v[64:65], off
	ds_write_b128 v109, v[68:71] offset:49152
	s_waitcnt lgkmcnt(7)
	v_mfma_f32_16x16x32_bf16 v[44:47], v[194:197], v[156:159], v[44:47]
	v_mfma_f32_16x16x32_bf16 v[40:43], v[198:201], v[156:159], v[40:43]
	v_mfma_f32_16x16x32_bf16 v[36:39], v[202:205], v[156:159], v[36:39]
	v_mfma_f32_16x16x32_bf16 v[32:35], v[206:209], v[156:159], v[32:35]
	global_load_dwordx4 v[140:143], v[66:67], off
	v_add_co_u32_e32 v66, vcc, s52, v64
	s_waitcnt vmcnt(8)
	ds_write_b128 v109, v[76:79] offset:53248
	v_addc_co_u32_e32 v67, vcc, 0, v65, vcc
	v_add_co_u32_e32 v64, vcc, s34, v64
	s_waitcnt lgkmcnt(7)
	v_mfma_f32_16x16x32_bf16 v[28:31], v[194:197], v[160:163], v[28:31]
	v_addc_co_u32_e32 v65, vcc, 0, v65, vcc
	v_mfma_f32_16x16x32_bf16 v[24:27], v[198:201], v[160:163], v[24:27]
	v_mfma_f32_16x16x32_bf16 v[20:23], v[202:205], v[160:163], v[20:23]
	v_mfma_f32_16x16x32_bf16 v[16:19], v[206:209], v[160:163], v[16:19]
	global_load_dwordx4 v[144:147], v[66:67], off
	s_waitcnt vmcnt(8)
	ds_write_b128 v109, v[80:83] offset:57344
	s_waitcnt lgkmcnt(7)
	v_mfma_f32_16x16x32_bf16 v[12:15], v[194:197], v[190:193], v[12:15]
	v_mfma_f32_16x16x32_bf16 v[8:11], v[198:201], v[190:193], v[8:11]
	v_mfma_f32_16x16x32_bf16 v[4:7], v[202:205], v[190:193], v[4:7]
	v_mfma_f32_16x16x32_bf16 v[0:3], v[206:209], v[190:193], v[0:3]
	global_load_dwordx4 v[148:151], v[64:65], off
	s_waitcnt vmcnt(8)
	ds_write_b128 v109, v[84:87] offset:61440
	s_waitcnt lgkmcnt(0)
	s_barrier
	ds_read_b128 v[84:87], v111 offset:51200
	ds_read_b128 v[80:83], v111 offset:49152
	ds_read_b128 v[88:91], v111 offset:53248
	ds_read_b128 v[92:95], v111 offset:55296
	ds_read_b128 v[64:67], v110 offset:32768
	s_min_u32 s42, s29, 60
	s_lshl_b32 s92, s42, 7
	ds_read_b128 v[68:71], v110 offset:34816
	v_lshl_add_u64 v[164:165], v[100:101], 0, s[92:93]
	ds_read_b128 v[72:75], v110 offset:36864
	ds_read_b128 v[76:79], v110 offset:38912
	ds_read_b128 v[152:155], v112 offset:32768
	ds_read_b128 v[156:159], v112 offset:34816
	ds_read_b128 v[160:163], v112 offset:36864
	ds_read_b128 v[190:193], v112 offset:38912
	ds_read_b128 v[194:197], v113 offset:49152
	ds_read_b128 v[198:201], v113 offset:51200
	ds_read_b128 v[202:205], v113 offset:53248
	ds_read_b128 v[206:209], v113 offset:55296
	s_waitcnt lgkmcnt(11)
	v_mfma_f32_16x16x32_bf16 v[214:217], v[84:87], v[64:67], v[60:63]
	v_mfma_f32_16x16x32_bf16 v[210:213], v[80:83], v[64:67], v[52:55]
	s_nop 1
	v_add_co_u32_e32 v60, vcc, s7, v164
	s_nop 1
	v_addc_co_u32_e32 v61, vcc, 0, v165, vcc
	v_mfma_f32_16x16x32_bf16 v[56:59], v[88:91], v[64:67], v[56:59]
	v_mfma_f32_16x16x32_bf16 v[48:51], v[92:95], v[64:67], v[48:51]
	v_add_co_u32_e32 v64, vcc, s52, v164
	global_load_dwordx4 v[52:55], v[164:165], off offset:384
	s_nop 0
	v_addc_co_u32_e32 v65, vcc, 0, v165, vcc
	s_waitcnt vmcnt(8)
	ds_write_b128 v109, v[116:119]
	s_waitcnt lgkmcnt(11)
	v_mfma_f32_16x16x32_bf16 v[44:47], v[80:83], v[68:71], v[44:47]
	v_mfma_f32_16x16x32_bf16 v[40:43], v[84:87], v[68:71], v[40:43]
	v_mfma_f32_16x16x32_bf16 v[36:39], v[88:91], v[68:71], v[36:39]
	v_mfma_f32_16x16x32_bf16 v[32:35], v[92:95], v[68:71], v[32:35]
	v_add_co_u32_e32 v68, vcc, s34, v164
	global_load_dwordx4 v[60:63], v[60:61], off offset:384
	s_waitcnt vmcnt(8)
	ds_write_b128 v109, v[120:123] offset:4096
	s_waitcnt lgkmcnt(11)
	v_mfma_f32_16x16x32_bf16 v[28:31], v[80:83], v[72:75], v[28:31]
	v_addc_co_u32_e32 v69, vcc, 0, v165, vcc
	v_mfma_f32_16x16x32_bf16 v[24:27], v[84:87], v[72:75], v[24:27]
	v_mfma_f32_16x16x32_bf16 v[20:23], v[88:91], v[72:75], v[20:23]
	v_mfma_f32_16x16x32_bf16 v[16:19], v[92:95], v[72:75], v[16:19]
	global_load_dwordx4 v[64:67], v[64:65], off offset:384
	s_waitcnt vmcnt(8)
	ds_write_b128 v109, v[124:127] offset:8192
	s_waitcnt lgkmcnt(11)
	v_mfma_f32_16x16x32_bf16 v[8:11], v[84:87], v[76:79], v[8:11]
	v_lshl_add_u64 v[84:85], v[102:103], 0, s[92:93]
	v_mfma_f32_16x16x32_bf16 v[12:15], v[80:83], v[76:79], v[12:15]
	v_mfma_f32_16x16x32_bf16 v[4:7], v[88:91], v[76:79], v[4:7]
	v_mfma_f32_16x16x32_bf16 v[0:3], v[92:95], v[76:79], v[0:3]
	v_add_co_u32_e32 v76, vcc, s7, v84
	global_load_dwordx4 v[72:75], v[68:69], off offset:384
	s_nop 0
	v_addc_co_u32_e32 v77, vcc, 0, v85, vcc
	v_add_co_u32_e32 v80, vcc, s52, v84
	s_waitcnt vmcnt(8)
	ds_write_b128 v109, v[132:135] offset:12288
	v_addc_co_u32_e32 v81, vcc, 0, v85, vcc
	s_waitcnt lgkmcnt(7)
	v_mfma_f32_16x16x32_bf16 v[92:95], v[194:197], v[152:155], v[210:213]
	s_waitcnt lgkmcnt(6)
	v_mfma_f32_16x16x32_bf16 v[88:91], v[198:201], v[152:155], v[214:217]
	s_waitcnt lgkmcnt(5)
	v_mfma_f32_16x16x32_bf16 v[56:59], v[202:205], v[152:155], v[56:59]
	s_waitcnt lgkmcnt(4)
	v_mfma_f32_16x16x32_bf16 v[48:51], v[206:209], v[152:155], v[48:51]
	global_load_dwordx4 v[68:71], v[84:85], off offset:384
	v_add_co_u32_e32 v84, vcc, s34, v84
	s_waitcnt vmcnt(8)
	ds_write_b128 v109, v[136:139] offset:16384
	v_addc_co_u32_e32 v85, vcc, 0, v85, vcc
	v_mfma_f32_16x16x32_bf16 v[44:47], v[194:197], v[156:159], v[44:47]
	v_mfma_f32_16x16x32_bf16 v[40:43], v[198:201], v[156:159], v[40:43]
	v_mfma_f32_16x16x32_bf16 v[36:39], v[202:205], v[156:159], v[36:39]
	v_mfma_f32_16x16x32_bf16 v[32:35], v[206:209], v[156:159], v[32:35]
	global_load_dwordx4 v[76:79], v[76:77], off offset:384
	s_waitcnt vmcnt(8)
	ds_write_b128 v109, v[140:143] offset:20480
	v_mfma_f32_16x16x32_bf16 v[28:31], v[194:197], v[160:163], v[28:31]
	v_mfma_f32_16x16x32_bf16 v[24:27], v[198:201], v[160:163], v[24:27]
	v_mfma_f32_16x16x32_bf16 v[20:23], v[202:205], v[160:163], v[20:23]
	v_mfma_f32_16x16x32_bf16 v[16:19], v[206:209], v[160:163], v[16:19]
	global_load_dwordx4 v[80:83], v[80:81], off offset:384
	s_waitcnt vmcnt(8)
	ds_write_b128 v109, v[144:147] offset:24576
	v_mfma_f32_16x16x32_bf16 v[12:15], v[194:197], v[190:193], v[12:15]
	v_mfma_f32_16x16x32_bf16 v[8:11], v[198:201], v[190:193], v[8:11]
	v_mfma_f32_16x16x32_bf16 v[4:7], v[202:205], v[190:193], v[4:7]
	v_mfma_f32_16x16x32_bf16 v[0:3], v[206:209], v[190:193], v[0:3]
	global_load_dwordx4 v[84:87], v[84:85], off offset:384
	s_waitcnt vmcnt(8)
	ds_write_b128 v109, v[148:151] offset:28672
	s_cmp_lt_u32 s29, 62
	s_mov_b32 s42, s29
	s_waitcnt lgkmcnt(0)
	s_barrier
	s_cbranch_scc1 .LBB0_596
	s_waitcnt vmcnt(5)
	v_add_u32_e32 v64, s24, v108
	v_add_u32_e32 v52, 0xffffe000, v64
	v_or_b32_e32 v62, v64, v107
	v_lshrrev_b32_e32 v52, 10, v52
	s_movk_i32 s16, 0x1800
	v_mad_u32_u24 v52, v52, s16, s16
	v_cmp_lt_i32_e32 vcc, s13, v62
	v_or_b32_e32 v65, s25, v114
	v_or_b32_e32 v54, v65, v115
	v_cndmask_b32_e32 v52, 0, v52, vcc
	v_ashrrev_i32_e32 v53, 31, v52
	s_waitcnt vmcnt(4)
	v_lshlrev_b64 v[74:75], 2, v[52:53]
	v_ashrrev_i32_e32 v55, 31, v54
	v_ashrrev_i32_e32 v63, 31, v62
	v_lshl_add_u64 v[52:53], s[38:39], 0, v[74:75]
	v_lshlrev_b64 v[60:61], 2, v[54:55]
	v_readlane_b32 s16, v250, 15
	s_waitcnt vmcnt(1)
	v_lshl_add_u64 v[82:83], v[52:53], 0, v[60:61]
	v_lshlrev_b64 v[52:53], 12, v[62:63]
	v_readlane_b32 s17, v250, 16
	v_lshl_add_u64 v[74:75], s[40:41], 0, v[74:75]
	s_waitcnt vmcnt(0)
	v_lshl_add_u64 v[86:87], v[74:75], 0, v[60:61]
	v_lshl_add_u64 v[52:53], s[16:17], 0, v[52:53]
	v_lshl_add_u64 v[84:85], v[52:53], 0, v[60:61]
	global_load_dwordx4 v[66:69], v[82:83], off
	global_load_dwordx4 v[70:73], v[84:85], off
	v_lshl_add_u64 v[52:53], s[0:1], 0, v[60:61]
	v_readlane_b32 s16, v250, 21
	v_lshlrev_b64 v[78:79], 11, v[62:63]
	v_readlane_b32 s17, v250, 22
	s_waitcnt vmcnt(0)
	v_pk_fma_f32 v[68:69], v[94:95], v[68:69], v[72:73]
	v_pk_fma_f32 v[66:67], v[92:93], v[66:67], v[70:71]
	global_store_dwordx4 v[84:85], v[66:69], off
	global_load_dwordx4 v[70:73], v[52:53], off
	global_load_dwordx4 v[74:77], v[86:87], off
	v_lshl_add_u64 v[78:79], s[16:17], 0, v[78:79]
	v_lshl_add_u64 v[92:93], v[54:55], 1, v[78:79]
	s_mov_b32 s16, 0xa000
	s_waitcnt vmcnt(1)
	v_pk_mul_f32 v[72:73], v[68:69], v[72:73]
	v_pk_mul_f32 v[70:71], v[66:67], v[70:71]
	s_waitcnt vmcnt(0)
	v_pk_add_f32 v[76:77], v[76:77], 1.0 op_sel_hi:[1,0]
	v_pk_add_f32 v[74:75], v[74:75], 1.0 op_sel_hi:[1,0]
	v_pk_mul_f32 v[72:73], v[72:73], v[76:77]
	v_pk_mul_f32 v[70:71], v[70:71], v[74:75]
	v_and_b32_sdwa v76, v73, v170 dst_sel:DWORD dst_unused:UNUSED_PAD src0_sel:WORD_1 src1_sel:DWORD
	v_and_b32_sdwa v77, v71, v170 dst_sel:DWORD dst_unused:UNUSED_PAD src0_sel:WORD_1 src1_sel:DWORD
	v_and_b32_sdwa v74, v72, v170 dst_sel:DWORD dst_unused:UNUSED_PAD src0_sel:WORD_1 src1_sel:DWORD
	v_and_b32_sdwa v75, v70, v170 dst_sel:DWORD dst_unused:UNUSED_PAD src0_sel:WORD_1 src1_sel:DWORD
	v_add3_u32 v73, v73, v76, s56
	v_add3_u32 v71, v71, v77, s56
	v_add3_u32 v70, v70, v75, s56
	v_add3_u32 v72, v72, v74, s56
	v_and_b32_e32 v73, 0xffff0000, v73
	v_and_b32_e32 v74, 0xffff0000, v71
	v_or_b32_sdwa v71, v73, v72 dst_sel:DWORD dst_unused:UNUSED_PAD src0_sel:DWORD src1_sel:WORD_1
	v_or_b32_sdwa v70, v74, v70 dst_sel:DWORD dst_unused:UNUSED_PAD src0_sel:DWORD src1_sel:WORD_1
	global_store_dwordx2 v[92:93], v[70:71], off
	global_load_dwordx4 v[70:73], v[82:83], off offset:64
	s_nop 0
	global_load_dwordx4 v[74:77], v[84:85], off offset:64
	s_waitcnt vmcnt(0)
	v_pk_fma_f32 v[72:73], v[90:91], v[72:73], v[76:77]
	v_pk_fma_f32 v[70:71], v[88:89], v[70:71], v[74:75]
	global_store_dwordx4 v[84:85], v[70:73], off offset:64
	global_load_dwordx4 v[74:77], v[52:53], off offset:64
	global_load_dwordx4 v[78:81], v[86:87], off offset:64
	s_waitcnt vmcnt(1)
	v_pk_mul_f32 v[76:77], v[72:73], v[76:77]
	v_pk_mul_f32 v[74:75], v[70:71], v[74:75]
	s_waitcnt vmcnt(0)
	v_pk_add_f32 v[80:81], v[80:81], 1.0 op_sel_hi:[1,0]
	v_pk_add_f32 v[78:79], v[78:79], 1.0 op_sel_hi:[1,0]
	v_pk_mul_f32 v[76:77], v[76:77], v[80:81]
	v_pk_mul_f32 v[74:75], v[74:75], v[78:79]
	v_and_b32_sdwa v80, v77, v170 dst_sel:DWORD dst_unused:UNUSED_PAD src0_sel:WORD_1 src1_sel:DWORD
	v_and_b32_sdwa v81, v75, v170 dst_sel:DWORD dst_unused:UNUSED_PAD src0_sel:WORD_1 src1_sel:DWORD
	v_and_b32_sdwa v78, v76, v170 dst_sel:DWORD dst_unused:UNUSED_PAD src0_sel:WORD_1 src1_sel:DWORD
	v_and_b32_sdwa v79, v74, v170 dst_sel:DWORD dst_unused:UNUSED_PAD src0_sel:WORD_1 src1_sel:DWORD
	v_add3_u32 v77, v77, v80, s56
	v_add3_u32 v75, v75, v81, s56
	v_add3_u32 v74, v74, v79, s56
	v_add3_u32 v76, v76, v78, s56
	v_and_b32_e32 v77, 0xffff0000, v77
	v_and_b32_e32 v78, 0xffff0000, v75
	v_or_b32_sdwa v75, v77, v76 dst_sel:DWORD dst_unused:UNUSED_PAD src0_sel:DWORD src1_sel:WORD_1
	v_or_b32_sdwa v74, v78, v74 dst_sel:DWORD dst_unused:UNUSED_PAD src0_sel:DWORD src1_sel:WORD_1
	global_store_dwordx2 v[92:93], v[74:75], off offset:32
	global_load_dwordx4 v[74:77], v[82:83], off offset:128
	s_nop 0
	global_load_dwordx4 v[78:81], v[84:85], off offset:128
	s_waitcnt vmcnt(0)
	v_pk_fma_f32 v[58:59], v[58:59], v[76:77], v[80:81]
	v_pk_fma_f32 v[56:57], v[56:57], v[74:75], v[78:79]
	global_store_dwordx4 v[84:85], v[56:59], off offset:128
	global_load_dwordx4 v[74:77], v[52:53], off offset:128
	global_load_dwordx4 v[78:81], v[86:87], off offset:128
	s_waitcnt vmcnt(1)
	v_pk_mul_f32 v[76:77], v[58:59], v[76:77]
	v_pk_mul_f32 v[74:75], v[56:57], v[74:75]
	s_waitcnt vmcnt(0)
	v_pk_add_f32 v[80:81], v[80:81], 1.0 op_sel_hi:[1,0]
	v_pk_add_f32 v[78:79], v[78:79], 1.0 op_sel_hi:[1,0]
	v_pk_mul_f32 v[76:77], v[76:77], v[80:81]
	v_pk_mul_f32 v[74:75], v[74:75], v[78:79]
	v_and_b32_sdwa v80, v77, v170 dst_sel:DWORD dst_unused:UNUSED_PAD src0_sel:WORD_1 src1_sel:DWORD
	v_and_b32_sdwa v81, v75, v170 dst_sel:DWORD dst_unused:UNUSED_PAD src0_sel:WORD_1 src1_sel:DWORD
	v_and_b32_sdwa v78, v76, v170 dst_sel:DWORD dst_unused:UNUSED_PAD src0_sel:WORD_1 src1_sel:DWORD
	v_and_b32_sdwa v79, v74, v170 dst_sel:DWORD dst_unused:UNUSED_PAD src0_sel:WORD_1 src1_sel:DWORD
	v_add3_u32 v77, v77, v80, s56
	v_add3_u32 v75, v75, v81, s56
	v_add3_u32 v74, v74, v79, s56
	v_add3_u32 v76, v76, v78, s56
	v_and_b32_e32 v77, 0xffff0000, v77
	v_and_b32_e32 v78, 0xffff0000, v75
	v_or_b32_sdwa v75, v77, v76 dst_sel:DWORD dst_unused:UNUSED_PAD src0_sel:DWORD src1_sel:WORD_1
	v_or_b32_sdwa v74, v78, v74 dst_sel:DWORD dst_unused:UNUSED_PAD src0_sel:DWORD src1_sel:WORD_1
	global_store_dwordx2 v[92:93], v[74:75], off offset:64
	global_load_dwordx4 v[74:77], v[82:83], off offset:192
	s_nop 0
	global_load_dwordx4 v[78:81], v[84:85], off offset:192
	s_waitcnt vmcnt(0)
	v_pk_fma_f32 v[76:77], v[50:51], v[76:77], v[80:81]
	v_pk_fma_f32 v[74:75], v[48:49], v[74:75], v[78:79]
	global_store_dwordx4 v[84:85], v[74:77], off offset:192
	global_load_dwordx4 v[78:81], v[52:53], off offset:192
	s_nop 0
	global_load_dwordx4 v[82:85], v[86:87], off offset:192
	v_mul_f32_e32 v48, v67, v67
	v_mul_f32_e32 v49, v71, v71
	v_fmac_f32_e32 v48, v66, v66
	v_fmac_f32_e32 v49, v70, v70
	v_fmac_f32_e32 v48, v68, v68
	v_fmac_f32_e32 v49, v72, v72
	v_fmac_f32_e32 v48, v69, v69
	v_fmac_f32_e32 v49, v73, v73
	v_add_f32_e32 v48, v48, v49
	v_mul_f32_e32 v49, v57, v57
	v_fmac_f32_e32 v49, v56, v56
	v_fmac_f32_e32 v49, v58, v58
	v_fmac_f32_e32 v49, v59, v59
	v_add_f32_e32 v48, v48, v49
	v_mul_f32_e32 v49, v75, v75
	v_fmac_f32_e32 v49, v74, v74
	v_fmac_f32_e32 v49, v76, v76
	v_fmac_f32_e32 v49, v77, v77
	v_add_f32_e32 v50, v48, v49
	ds_bpermute_b32 v51, v105, v50
	v_lshrrev_b32_e32 v48, 6, v65
	v_mul_lo_u32 v48, v48, s16
	v_ashrrev_i32_e32 v49, 31, v48
	v_lshl_add_u64 v[48:49], s[26:27], 0, v[48:49]
	s_waitcnt lgkmcnt(0)
	v_add_f32_e32 v50, v50, v51
	ds_bpermute_b32 v51, v104, v50
	v_lshl_add_u64 v[48:49], v[62:63], 2, v[48:49]
	s_waitcnt vmcnt(1)
	v_pk_mul_f32 v[56:57], v[76:77], v[80:81]
	v_pk_mul_f32 v[58:59], v[74:75], v[78:79]
	s_waitcnt vmcnt(0)
	v_pk_add_f32 v[66:67], v[84:85], 1.0 op_sel_hi:[1,0]
	v_pk_add_f32 v[68:69], v[82:83], 1.0 op_sel_hi:[1,0]
	v_pk_mul_f32 v[56:57], v[56:57], v[66:67]
	v_pk_mul_f32 v[58:59], v[58:59], v[68:69]
	v_and_b32_sdwa v67, v57, v170 dst_sel:DWORD dst_unused:UNUSED_PAD src0_sel:WORD_1 src1_sel:DWORD
	v_and_b32_sdwa v68, v59, v170 dst_sel:DWORD dst_unused:UNUSED_PAD src0_sel:WORD_1 src1_sel:DWORD
	v_and_b32_sdwa v65, v56, v170 dst_sel:DWORD dst_unused:UNUSED_PAD src0_sel:WORD_1 src1_sel:DWORD
	v_and_b32_sdwa v66, v58, v170 dst_sel:DWORD dst_unused:UNUSED_PAD src0_sel:WORD_1 src1_sel:DWORD
	v_add3_u32 v57, v57, v67, s56
	v_add3_u32 v59, v59, v68, s56
	v_add3_u32 v58, v58, v66, s56
	v_add3_u32 v56, v56, v65, s56
	v_and_b32_e32 v57, 0xffff0000, v57
	v_and_b32_e32 v59, 0xffff0000, v59
	v_or_b32_sdwa v57, v57, v56 dst_sel:DWORD dst_unused:UNUSED_PAD src0_sel:DWORD src1_sel:WORD_1
	v_or_b32_sdwa v56, v59, v58 dst_sel:DWORD dst_unused:UNUSED_PAD src0_sel:DWORD src1_sel:WORD_1
	global_store_dwordx2 v[92:93], v[56:57], off offset:96
	s_and_saveexec_b64 s[24:25], s[36:37]
	s_cbranch_execz .LBB0_599
	s_waitcnt lgkmcnt(0)
	v_add_f32_e32 v50, v50, v51
	global_store_dword v[48:49], v50, off

.LBB0_609:
	s_add_i32 s2, s3, 2
	v_add_u32_e32 v127, v89, v90
	ds_read_b128 v[100:103], v127 offset:16384
	ds_read_b128 v[106:109], v127 offset:18432
	ds_read_b128 v[110:113], v127 offset:20480
	ds_read_b128 v[114:117], v127 offset:22528
	v_add_u32_e32 v126, v88, v90
	ds_read_b128 v[92:95], v126
	ds_read_b128 v[96:99], v126 offset:2048
	s_add_i32 s3, s3, 4
	s_min_u32 s3, s3, 63
	v_add_u32_e32 v128, v88, v91
	v_add_u32_e32 v130, v89, v91
	s_lshl_b32 s92, s3, 7
	ds_read_b128 v[118:121], v130 offset:18432
	ds_read_b128 v[122:125], v130 offset:20480
	ds_read_b128 v[132:135], v130 offset:22528
	s_waitcnt lgkmcnt(4)
	v_mfma_f32_16x16x32_bf16 v[76:79], v[100:103], v[92:95], v[76:79]
	v_lshl_add_u64 v[44:45], v[80:81], 0, s[92:93]
	v_add_co_u32_e32 v46, vcc, s7, v44
	v_mfma_f32_16x16x32_bf16 v[68:71], v[106:109], v[92:95], v[68:71]
	s_nop 0
	v_addc_co_u32_e32 v47, vcc, 0, v45, vcc
	v_mfma_f32_16x16x32_bf16 v[52:55], v[110:113], v[92:95], v[52:55]
	v_mfma_f32_16x16x32_bf16 v[40:43], v[114:117], v[92:95], v[40:43]
	s_waitcnt lgkmcnt(3)
	v_mfma_f32_16x16x32_bf16 v[92:95], v[100:103], v[96:99], v[36:39]
	s_nop 2
	ds_read_b128 v[36:39], v128
	v_mfma_f32_16x16x32_bf16 v[100:103], v[106:109], v[96:99], v[8:11]
	v_mfma_f32_16x16x32_bf16 v[106:109], v[110:113], v[96:99], v[4:7]
	ds_read_b128 v[110:113], v128 offset:2048
	v_mfma_f32_16x16x32_bf16 v[96:99], v[114:117], v[96:99], v[0:3]
	ds_read_b128 v[114:117], v130 offset:16384
	global_load_dwordx4 v[72:75], v[44:45], off
	s_waitcnt vmcnt(1)
	ds_write_b128 v87, v[12:15] offset:53248
	global_load_dwordx4 v[64:67], v[46:47], off
	v_add_co_u32_e32 v46, vcc, s52, v44
	ds_write_b128 v87, v[16:19] offset:49152
	s_nop 0
	v_addc_co_u32_e32 v47, vcc, 0, v45, vcc
	v_add_co_u32_e32 v44, vcc, s34, v44
	global_load_dwordx4 v[60:63], v[46:47], off
	s_nop 0
	v_addc_co_u32_e32 v45, vcc, 0, v45, vcc
	ds_write_b128 v87, v[20:23] offset:45056
	global_load_dwordx4 v[56:59], v[44:45], off
	v_lshl_add_u64 v[44:45], v[82:83], 0, s[92:93]
	ds_write_b128 v87, v[28:31] offset:32768
	s_waitcnt lgkmcnt(4)
	v_mfma_f32_16x16x32_bf16 v[0:3], v[114:117], v[36:39], v[76:79]
	v_mfma_f32_16x16x32_bf16 v[4:7], v[118:121], v[36:39], v[68:71]
	global_load_dwordx4 v[48:51], v[44:45], off
	v_add_co_u32_e32 v44, vcc, s7, v44
	ds_write_b128 v87, v[32:35] offset:36864
	s_nop 0
	v_addc_co_u32_e32 v45, vcc, 0, v45, vcc
	v_mfma_f32_16x16x32_bf16 v[8:11], v[122:125], v[36:39], v[52:55]
	v_mfma_f32_16x16x32_bf16 v[36:39], v[132:135], v[36:39], v[40:43]
	global_load_dwordx4 v[44:47], v[44:45], off
	ds_write_b128 v87, v[24:27] offset:40960
	v_mfma_f32_16x16x32_bf16 v[40:43], v[114:117], v[110:113], v[92:95]
	v_mfma_f32_16x16x32_bf16 v[52:55], v[118:121], v[110:113], v[100:103]
	v_mfma_f32_16x16x32_bf16 v[68:71], v[122:125], v[110:113], v[106:109]
	v_mfma_f32_16x16x32_bf16 v[76:79], v[132:135], v[110:113], v[96:99]
	s_waitcnt lgkmcnt(0)
	s_barrier
	ds_read_b128 v[100:103], v127 offset:49152
	ds_read_b128 v[106:109], v127 offset:51200
	ds_read_b128 v[110:113], v127 offset:53248
	ds_read_b128 v[114:117], v127 offset:55296
	ds_read_b128 v[92:95], v126 offset:32768
	ds_read_b128 v[96:99], v126 offset:34816
	s_min_u32 s3, s2, 60
	s_lshl_b32 s92, s3, 7
	ds_read_b128 v[118:121], v130 offset:51200
	ds_read_b128 v[122:125], v130 offset:53248
	ds_read_b128 v[132:135], v130 offset:55296
	s_waitcnt lgkmcnt(4)
	v_mfma_f32_16x16x32_bf16 v[0:3], v[100:103], v[92:95], v[0:3]
	v_lshl_add_u64 v[12:13], v[80:81], 0, s[92:93]
	v_add_co_u32_e32 v14, vcc, s7, v12
	v_mfma_f32_16x16x32_bf16 v[4:7], v[106:109], v[92:95], v[4:7]
	s_nop 0
	v_addc_co_u32_e32 v15, vcc, 0, v13, vcc
	v_mfma_f32_16x16x32_bf16 v[8:11], v[110:113], v[92:95], v[8:11]
	v_mfma_f32_16x16x32_bf16 v[36:39], v[114:117], v[92:95], v[36:39]
	s_waitcnt lgkmcnt(3)
	v_mfma_f32_16x16x32_bf16 v[92:95], v[100:103], v[96:99], v[40:43]
	s_nop 2
	ds_read_b128 v[40:43], v128 offset:32768
	v_mfma_f32_16x16x32_bf16 v[100:103], v[106:109], v[96:99], v[52:55]
	v_mfma_f32_16x16x32_bf16 v[106:109], v[110:113], v[96:99], v[68:71]
	ds_read_b128 v[110:113], v128 offset:34816
	v_mfma_f32_16x16x32_bf16 v[96:99], v[114:117], v[96:99], v[76:79]
	ds_read_b128 v[114:117], v130 offset:49152
	global_load_dwordx4 v[28:31], v[12:13], off offset:384
	s_waitcnt vmcnt(1)
	ds_write_b128 v87, v[44:47] offset:20480
	global_load_dwordx4 v[32:35], v[14:15], off offset:384
	v_add_co_u32_e32 v14, vcc, s52, v12
	ds_write_b128 v87, v[48:51] offset:16384
	s_nop 0
	v_addc_co_u32_e32 v15, vcc, 0, v13, vcc
	v_add_co_u32_e32 v12, vcc, s34, v12
	global_load_dwordx4 v[24:27], v[14:15], off offset:384
	s_nop 0
	v_addc_co_u32_e32 v13, vcc, 0, v13, vcc
	ds_write_b128 v87, v[56:59] offset:12288
	global_load_dwordx4 v[20:23], v[12:13], off offset:384
	v_lshl_add_u64 v[12:13], v[82:83], 0, s[92:93]
	ds_write_b128 v87, v[72:75]
	s_waitcnt lgkmcnt(4)
	v_mfma_f32_16x16x32_bf16 v[76:79], v[114:117], v[40:43], v[0:3]
	v_mfma_f32_16x16x32_bf16 v[68:71], v[118:121], v[40:43], v[4:7]
	global_load_dwordx4 v[16:19], v[12:13], off offset:384
	v_add_co_u32_e32 v12, vcc, s7, v12
	ds_write_b128 v87, v[64:67] offset:4096
	s_nop 0
	v_addc_co_u32_e32 v13, vcc, 0, v13, vcc
	v_mfma_f32_16x16x32_bf16 v[52:55], v[122:125], v[40:43], v[8:11]
	v_mfma_f32_16x16x32_bf16 v[40:43], v[132:135], v[40:43], v[36:39]
	global_load_dwordx4 v[12:15], v[12:13], off offset:384
	ds_write_b128 v87, v[60:63] offset:8192
	v_mfma_f32_16x16x32_bf16 v[36:39], v[114:117], v[110:113], v[92:95]
	v_mfma_f32_16x16x32_bf16 v[8:11], v[118:121], v[110:113], v[100:103]
	v_mfma_f32_16x16x32_bf16 v[4:7], v[122:125], v[110:113], v[106:109]
	v_mfma_f32_16x16x32_bf16 v[0:3], v[132:135], v[110:113], v[96:99]
	s_cmp_lt_u32 s2, 62
	s_mov_b32 s3, s2
	s_waitcnt lgkmcnt(0)
	s_barrier
	s_cbranch_scc1 .LBB0_609
	v_readlane_b32 s2, v251, 18
	s_waitcnt vmcnt(1)
	s_nop 0
	v_add_u32_e32 v18, s2, v86
	v_readlane_b32 s2, v251, 19
	s_waitcnt vmcnt(0)
	v_add_u32_e32 v13, 0xffffe000, v18
	v_or_b32_e32 v12, v18, v85
	v_lshl_or_b32 v19, v84, 2, s2
	v_lshrrev_b32_e32 v13, 10, v13
	s_movk_i32 s2, 0x1800
	v_mad_u32_u24 v13, v13, s2, s2
	v_cmp_lt_i32_e32 vcc, s13, v12
	v_lshlrev_b32_e32 v128, 2, v19
	v_readlane_b32 s2, v250, 15
	v_cndmask_b32_e32 v14, 0, v13, vcc
	v_ashrrev_i32_e32 v15, 31, v14
	v_lshlrev_b64 v[24:25], 2, v[14:15]
	v_ashrrev_i32_e32 v13, 31, v12
	v_lshl_add_u64 v[14:15], s[38:39], 0, v[24:25]
	v_lshl_add_u64 v[48:49], v[14:15], 0, v[128:129]
	v_lshlrev_b64 v[14:15], 12, v[12:13]
	v_readlane_b32 s3, v250, 16
	v_lshl_add_u64 v[28:29], s[40:41], 0, v[24:25]
	v_lshlrev_b64 v[32:33], 11, v[12:13]
	v_lshl_add_u64 v[14:15], s[2:3], 0, v[14:15]
	v_lshl_add_u64 v[50:51], v[14:15], 0, v[128:129]
	global_load_dwordx4 v[72:75], v[48:49], off
	global_load_dwordx4 v[80:83], v[48:49], off offset:64
	global_load_dwordx4 v[88:91], v[48:49], off offset:128
	global_load_dwordx4 v[136:139], v[48:49], off offset:192
	global_load_dwordx4 v[194:197], v[50:51], off
	global_load_dwordx4 v[198:201], v[50:51], off offset:64
	global_load_dwordx4 v[202:205], v[50:51], off offset:128
	global_load_dwordx4 v[206:209], v[50:51], off offset:192
	v_add_co_u32_e32 v58, vcc, 0x10000, v50
	s_nop 1
	v_addc_co_u32_e32 v59, vcc, 0, v51, vcc
	global_load_dwordx4 v[210:213], v[58:59], off
	global_load_dwordx4 v[214:217], v[58:59], off offset:64
	global_load_dwordx4 v[218:221], v[58:59], off offset:128
	global_load_dwordx4 v[222:225], v[58:59], off offset:192
	v_readlane_b32 s2, v250, 21
	v_readlane_b32 s3, v250, 22
	v_cmp_eq_u32_e32 vcc, 0, v84
	s_waitcnt vmcnt(4)
	v_pk_fma_f32 v[22:23], v[78:79], v[74:75], v[196:197]
	v_pk_fma_f32 v[20:21], v[76:77], v[72:73], v[194:195]
	global_store_dwordx4 v[50:51], v[20:23], off
	v_lshl_add_u64 v[14:15], v[28:29], 0, v[128:129]
	global_load_dwordx4 v[140:143], v128, s[0:1]
	global_load_dwordx4 v[144:147], v128, s[0:1] offset:64
	global_load_dwordx4 v[148:151], v128, s[0:1] offset:128
	global_load_dwordx4 v[152:155], v128, s[0:1] offset:192
	global_load_dwordx4 v[156:159], v[14:15], off
	global_load_dwordx4 v[160:163], v[14:15], off offset:64
	global_load_dwordx4 v[180:183], v[14:15], off offset:128
	global_load_dwordx4 v[190:193], v[14:15], off offset:192
	v_lshlrev_b32_e32 v16, 1, v19
	v_mov_b32_e32 v17, v129
	v_lshl_add_u64 v[32:33], s[2:3], 0, v[32:33]
	v_lshl_add_u64 v[56:57], v[32:33], 0, v[16:17]
	s_waitcnt vmcnt(0)
	v_pk_mul_f32 v[26:27], v[22:23], v[142:143]
	v_pk_mul_f32 v[24:25], v[20:21], v[140:141]
	s_waitcnt vmcnt(0)
	v_pk_add_f32 v[30:31], v[158:159], 1.0 op_sel_hi:[1,0]
	v_pk_add_f32 v[28:29], v[156:157], 1.0 op_sel_hi:[1,0]
	v_pk_mul_f32 v[26:27], v[26:27], v[30:31]
	v_pk_mul_f32 v[24:25], v[24:25], v[28:29]
	v_and_b32_sdwa v19, v26, v170 dst_sel:DWORD dst_unused:UNUSED_PAD src0_sel:WORD_1 src1_sel:DWORD
	v_and_b32_sdwa v29, v27, v170 dst_sel:DWORD dst_unused:UNUSED_PAD src0_sel:WORD_1 src1_sel:DWORD
	v_and_b32_sdwa v30, v25, v170 dst_sel:DWORD dst_unused:UNUSED_PAD src0_sel:WORD_1 src1_sel:DWORD
	v_and_b32_sdwa v28, v24, v170 dst_sel:DWORD dst_unused:UNUSED_PAD src0_sel:WORD_1 src1_sel:DWORD
	v_add3_u32 v19, v26, v19, s56
	v_add3_u32 v26, v27, v29, s56
	v_add3_u32 v25, v25, v30, s56
	v_add3_u32 v24, v24, v28, s56
	v_and_b32_e32 v26, 0xffff0000, v26
	v_and_b32_e32 v27, 0xffff0000, v25
	v_or_b32_sdwa v25, v26, v19 dst_sel:DWORD dst_unused:UNUSED_PAD src0_sel:DWORD src1_sel:WORD_1
	v_or_b32_sdwa v24, v27, v24 dst_sel:DWORD dst_unused:UNUSED_PAD src0_sel:DWORD src1_sel:WORD_1
	global_store_dwordx2 v[56:57], v[24:25], off
	s_nop 0
	s_waitcnt vmcnt(0)
	v_pk_fma_f32 v[26:27], v[70:71], v[82:83], v[200:201]
	v_pk_fma_f32 v[24:25], v[68:69], v[80:81], v[198:199]
	global_store_dwordx4 v[50:51], v[24:27], off offset:64
	v_pk_mul_f32 v[30:31], v[26:27], v[146:147]
	v_pk_mul_f32 v[28:29], v[24:25], v[144:145]
	v_pk_add_f32 v[34:35], v[162:163], 1.0 op_sel_hi:[1,0]
	v_pk_add_f32 v[32:33], v[160:161], 1.0 op_sel_hi:[1,0]
	v_pk_mul_f32 v[30:31], v[30:31], v[34:35]
	v_pk_mul_f32 v[28:29], v[28:29], v[32:33]
	v_and_b32_sdwa v19, v30, v170 dst_sel:DWORD dst_unused:UNUSED_PAD src0_sel:WORD_1 src1_sel:DWORD
	v_and_b32_sdwa v33, v31, v170 dst_sel:DWORD dst_unused:UNUSED_PAD src0_sel:WORD_1 src1_sel:DWORD
	v_and_b32_sdwa v34, v29, v170 dst_sel:DWORD dst_unused:UNUSED_PAD src0_sel:WORD_1 src1_sel:DWORD
	v_and_b32_sdwa v32, v28, v170 dst_sel:DWORD dst_unused:UNUSED_PAD src0_sel:WORD_1 src1_sel:DWORD
	v_add3_u32 v19, v30, v19, s56
	v_add3_u32 v30, v31, v33, s56
	v_add3_u32 v29, v29, v34, s56
	v_add3_u32 v28, v28, v32, s56
	v_and_b32_e32 v30, 0xffff0000, v30
	v_and_b32_e32 v31, 0xffff0000, v29
	v_or_b32_sdwa v29, v30, v19 dst_sel:DWORD dst_unused:UNUSED_PAD src0_sel:DWORD src1_sel:WORD_1
	v_or_b32_sdwa v28, v31, v28 dst_sel:DWORD dst_unused:UNUSED_PAD src0_sel:DWORD src1_sel:WORD_1
	global_store_dwordx2 v[56:57], v[28:29], off offset:32
	s_nop 0
	v_pk_fma_f32 v[30:31], v[54:55], v[90:91], v[204:205]
	v_pk_fma_f32 v[28:29], v[52:53], v[88:89], v[202:203]
	global_store_dwordx4 v[50:51], v[28:31], off offset:128
	v_pk_mul_f32 v[34:35], v[30:31], v[150:151]
	v_pk_mul_f32 v[32:33], v[28:29], v[148:149]
	v_pk_add_f32 v[46:47], v[182:183], 1.0 op_sel_hi:[1,0]
	v_pk_add_f32 v[44:45], v[180:181], 1.0 op_sel_hi:[1,0]
	v_pk_mul_f32 v[34:35], v[34:35], v[46:47]
	v_pk_mul_f32 v[32:33], v[32:33], v[44:45]
	v_and_b32_sdwa v19, v34, v170 dst_sel:DWORD dst_unused:UNUSED_PAD src0_sel:WORD_1 src1_sel:DWORD
	v_and_b32_sdwa v45, v35, v170 dst_sel:DWORD dst_unused:UNUSED_PAD src0_sel:WORD_1 src1_sel:DWORD
	v_and_b32_sdwa v46, v33, v170 dst_sel:DWORD dst_unused:UNUSED_PAD src0_sel:WORD_1 src1_sel:DWORD
	v_and_b32_sdwa v44, v32, v170 dst_sel:DWORD dst_unused:UNUSED_PAD src0_sel:WORD_1 src1_sel:DWORD
	v_add3_u32 v19, v34, v19, s56
	v_add3_u32 v34, v35, v45, s56
	v_add3_u32 v33, v33, v46, s56
	v_add3_u32 v32, v32, v44, s56
	v_and_b32_e32 v34, 0xffff0000, v34
	v_and_b32_e32 v35, 0xffff0000, v33
	v_or_b32_sdwa v33, v34, v19 dst_sel:DWORD dst_unused:UNUSED_PAD src0_sel:DWORD src1_sel:WORD_1
	v_or_b32_sdwa v32, v35, v32 dst_sel:DWORD dst_unused:UNUSED_PAD src0_sel:DWORD src1_sel:WORD_1
	global_store_dwordx2 v[56:57], v[32:33], off offset:64
	s_nop 0
	v_pk_fma_f32 v[34:35], v[42:43], v[138:139], v[208:209]
	v_pk_fma_f32 v[32:33], v[40:41], v[136:137], v[206:207]
	global_store_dwordx4 v[50:51], v[32:35], off offset:192
	v_mul_f32_e32 v14, v21, v21
	v_mul_f32_e32 v15, v25, v25
	v_fmac_f32_e32 v14, v20, v20
	v_fmac_f32_e32 v15, v24, v24
	v_fmac_f32_e32 v14, v22, v22
	v_fmac_f32_e32 v15, v26, v26
	v_fmac_f32_e32 v14, v23, v23
	v_fmac_f32_e32 v15, v27, v27
	v_add_f32_e32 v14, v14, v15
	v_mul_f32_e32 v15, v29, v29
	v_fmac_f32_e32 v15, v28, v28
	v_fmac_f32_e32 v15, v30, v30
	v_fmac_f32_e32 v15, v31, v31
	v_add_f32_e32 v14, v14, v15
	v_mul_f32_e32 v15, v33, v33
	v_fmac_f32_e32 v15, v32, v32
	v_fmac_f32_e32 v15, v34, v34
	v_fmac_f32_e32 v15, v35, v35
	v_add_f32_e32 v14, v14, v15
	ds_bpermute_b32 v15, v105, v14
	s_waitcnt lgkmcnt(0)
	v_add_f32_e32 v14, v14, v15
	ds_bpermute_b32 v15, v104, v14
	v_pk_mul_f32 v[20:21], v[34:35], v[154:155]
	v_pk_mul_f32 v[22:23], v[32:33], v[152:153]
	v_pk_add_f32 v[24:25], v[192:193], 1.0 op_sel_hi:[1,0]
	v_pk_add_f32 v[26:27], v[190:191], 1.0 op_sel_hi:[1,0]
	v_pk_mul_f32 v[20:21], v[20:21], v[24:25]
	v_pk_mul_f32 v[22:23], v[22:23], v[26:27]
	v_and_b32_sdwa v19, v20, v170 dst_sel:DWORD dst_unused:UNUSED_PAD src0_sel:WORD_1 src1_sel:DWORD
	v_and_b32_sdwa v25, v21, v170 dst_sel:DWORD dst_unused:UNUSED_PAD src0_sel:WORD_1 src1_sel:DWORD
	v_and_b32_sdwa v26, v23, v170 dst_sel:DWORD dst_unused:UNUSED_PAD src0_sel:WORD_1 src1_sel:DWORD
	v_and_b32_sdwa v24, v22, v170 dst_sel:DWORD dst_unused:UNUSED_PAD src0_sel:WORD_1 src1_sel:DWORD
	v_add3_u32 v19, v20, v19, s56
	v_add3_u32 v20, v21, v25, s56
	v_add3_u32 v21, v23, v26, s56
	v_add3_u32 v22, v22, v24, s56
	v_and_b32_e32 v20, 0xffff0000, v20
	v_and_b32_e32 v23, 0xffff0000, v21
	v_or_b32_sdwa v21, v20, v19 dst_sel:DWORD dst_unused:UNUSED_PAD src0_sel:DWORD src1_sel:WORD_1
	v_or_b32_sdwa v20, v23, v22 dst_sel:DWORD dst_unused:UNUSED_PAD src0_sel:DWORD src1_sel:WORD_1
	global_store_dwordx2 v[56:57], v[20:21], off offset:96
	s_and_saveexec_b64 s[2:3], vcc
	s_cbranch_execz .LBB0_612
	v_readlane_b32 s16, v253, 20
	s_add_u32 s24, s26, s16
	s_addc_u32 s25, s27, 0
	v_lshl_add_u64 v[20:21], v[12:13], 2, s[24:25]
	s_waitcnt lgkmcnt(0)
	v_add_f32_e32 v13, v14, v15
	global_store_dword v[20:21], v13, off

.LBB0_702:
	s_add_i32 s2, s3, 2
	ds_read_b128 v[152:155], v123 offset:16384
	ds_read_b128 v[156:159], v123 offset:18432
	ds_read_b128 v[160:163], v123 offset:20480
	ds_read_b128 v[190:193], v123 offset:22528
	ds_read_b128 v[102:105], v122
	s_add_i32 s3, s3, 4
	ds_read_b128 v[140:143], v122 offset:2048
	s_min_u32 s3, s3, 15
	s_lshl_b32 s92, s3, 7
	ds_read_b128 v[144:147], v122 offset:4096
	v_lshl_add_u64 v[106:107], v[98:99], 0, s[92:93]
	ds_read_b128 v[148:151], v122 offset:6144
	ds_read_b128 v[194:197], v124
	ds_read_b128 v[198:201], v124 offset:2048
	ds_read_b128 v[202:205], v124 offset:4096
	ds_read_b128 v[206:209], v124 offset:6144
	ds_read_b128 v[210:213], v125 offset:16384
	ds_read_b128 v[214:217], v125 offset:18432
	ds_read_b128 v[218:221], v125 offset:20480
	ds_read_b128 v[222:225], v125 offset:22528
	s_waitcnt lgkmcnt(11)
	v_mfma_f32_16x16x32_bf16 v[60:63], v[152:155], v[102:105], v[60:63]
	v_mfma_f32_16x16x32_bf16 v[56:59], v[156:159], v[102:105], v[56:59]
	v_mfma_f32_16x16x32_bf16 v[52:55], v[160:163], v[102:105], v[52:55]
	v_mfma_f32_16x16x32_bf16 v[48:51], v[190:193], v[102:105], v[48:51]
	global_load_dwordx4 v[102:105], v[106:107], off
	s_waitcnt vmcnt(6)
	ds_write_b128 v121, v[64:67] offset:32768
	v_add_co_u32_e32 v64, vcc, s11, v106
	s_waitcnt lgkmcnt(11)
	v_mfma_f32_16x16x32_bf16 v[44:47], v[152:155], v[140:143], v[44:47]
	v_addc_co_u32_e32 v65, vcc, 0, v107, vcc
	v_mfma_f32_16x16x32_bf16 v[40:43], v[156:159], v[140:143], v[40:43]
	v_mfma_f32_16x16x32_bf16 v[36:39], v[160:163], v[140:143], v[36:39]
	v_mfma_f32_16x16x32_bf16 v[32:35], v[190:193], v[140:143], v[32:35]
	global_load_dwordx4 v[140:143], v[64:65], off
	v_add_co_u32_e32 v64, vcc, s33, v106
	ds_write_b128 v121, v[68:71] offset:36864
	s_nop 0
	v_addc_co_u32_e32 v65, vcc, 0, v107, vcc
	s_waitcnt lgkmcnt(11)
	v_mfma_f32_16x16x32_bf16 v[28:31], v[152:155], v[144:147], v[28:31]
	v_mfma_f32_16x16x32_bf16 v[24:27], v[156:159], v[144:147], v[24:27]
	v_mfma_f32_16x16x32_bf16 v[20:23], v[160:163], v[144:147], v[20:23]
	v_mfma_f32_16x16x32_bf16 v[16:19], v[190:193], v[144:147], v[16:19]
	global_load_dwordx4 v[144:147], v[64:65], off
	v_add_co_u32_e32 v64, vcc, s59, v106
	ds_write_b128 v121, v[72:75] offset:40960
	s_nop 0
	v_addc_co_u32_e32 v65, vcc, 0, v107, vcc
	s_waitcnt lgkmcnt(11)
	v_mfma_f32_16x16x32_bf16 v[12:15], v[152:155], v[148:151], v[12:15]
	v_mfma_f32_16x16x32_bf16 v[8:11], v[156:159], v[148:151], v[8:11]
	v_mfma_f32_16x16x32_bf16 v[4:7], v[160:163], v[148:151], v[4:7]
	v_mfma_f32_16x16x32_bf16 v[0:3], v[190:193], v[148:151], v[0:3]
	global_load_dwordx4 v[148:151], v[64:65], off
	v_lshl_add_u64 v[64:65], v[100:101], 0, s[92:93]
	v_add_co_u32_e32 v66, vcc, s11, v64
	s_waitcnt vmcnt(7)
	ds_write_b128 v121, v[80:83] offset:45056
	v_addc_co_u32_e32 v67, vcc, 0, v65, vcc
	s_waitcnt lgkmcnt(7)
	v_mfma_f32_16x16x32_bf16 v[60:63], v[210:213], v[194:197], v[60:63]
	s_waitcnt lgkmcnt(6)
	v_mfma_f32_16x16x32_bf16 v[56:59], v[214:217], v[194:197], v[56:59]
	s_waitcnt lgkmcnt(5)
	v_mfma_f32_16x16x32_bf16 v[52:55], v[218:221], v[194:197], v[52:55]
	s_waitcnt lgkmcnt(4)
	v_mfma_f32_16x16x32_bf16 v[48:51], v[222:225], v[194:197], v[48:51]
	global_load_dwordx4 v[152:155], v[64:65], off
	ds_write_b128 v121, v[76:79] offset:49152
	v_mfma_f32_16x16x32_bf16 v[44:47], v[210:213], v[198:201], v[44:47]
	v_mfma_f32_16x16x32_bf16 v[40:43], v[214:217], v[198:201], v[40:43]
	v_mfma_f32_16x16x32_bf16 v[36:39], v[218:221], v[198:201], v[36:39]
	v_mfma_f32_16x16x32_bf16 v[32:35], v[222:225], v[198:201], v[32:35]
	global_load_dwordx4 v[156:159], v[66:67], off
	v_add_co_u32_e32 v66, vcc, s33, v64
	s_waitcnt vmcnt(8)
	ds_write_b128 v121, v[84:87] offset:53248
	v_addc_co_u32_e32 v67, vcc, 0, v65, vcc
	v_add_co_u32_e32 v64, vcc, s59, v64
	v_mfma_f32_16x16x32_bf16 v[28:31], v[210:213], v[202:205], v[28:31]
	s_nop 0
	v_addc_co_u32_e32 v65, vcc, 0, v65, vcc
	v_mfma_f32_16x16x32_bf16 v[24:27], v[214:217], v[202:205], v[24:27]
	v_mfma_f32_16x16x32_bf16 v[20:23], v[218:221], v[202:205], v[20:23]
	v_mfma_f32_16x16x32_bf16 v[16:19], v[222:225], v[202:205], v[16:19]
	global_load_dwordx4 v[160:163], v[66:67], off
	s_waitcnt vmcnt(8)
	ds_write_b128 v121, v[88:91] offset:57344
	v_mfma_f32_16x16x32_bf16 v[12:15], v[210:213], v[206:209], v[12:15]
	v_mfma_f32_16x16x32_bf16 v[8:11], v[214:217], v[206:209], v[8:11]
	v_mfma_f32_16x16x32_bf16 v[4:7], v[218:221], v[206:209], v[4:7]
	v_mfma_f32_16x16x32_bf16 v[0:3], v[222:225], v[206:209], v[0:3]
	global_load_dwordx4 v[190:193], v[64:65], off
	s_waitcnt vmcnt(8)
	ds_write_b128 v121, v[92:95] offset:61440
	s_waitcnt lgkmcnt(0)
	s_barrier
	ds_read_b128 v[80:83], v123 offset:49152
	ds_read_b128 v[84:87], v123 offset:51200
	ds_read_b128 v[88:91], v123 offset:53248
	ds_read_b128 v[92:95], v123 offset:55296
	ds_read_b128 v[64:67], v122 offset:32768
	ds_read_b128 v[68:71], v122 offset:34816
	s_min_u32 s3, s2, 12
	s_lshl_b32 s92, s3, 7
	ds_read_b128 v[72:75], v122 offset:36864
	ds_read_b128 v[76:79], v122 offset:38912
	v_lshl_add_u64 v[106:107], v[98:99], 0, s[92:93]
	ds_read_b128 v[194:197], v124 offset:32768
	ds_read_b128 v[198:201], v124 offset:34816
	ds_read_b128 v[202:205], v124 offset:36864
	ds_read_b128 v[206:209], v124 offset:38912
	ds_read_b128 v[210:213], v125 offset:49152
	ds_read_b128 v[214:217], v125 offset:51200
	ds_read_b128 v[218:221], v125 offset:53248
	ds_read_b128 v[222:225], v125 offset:55296
	s_waitcnt lgkmcnt(11)
	v_mfma_f32_16x16x32_bf16 v[60:63], v[80:83], v[64:67], v[60:63]
	v_mfma_f32_16x16x32_bf16 v[56:59], v[84:87], v[64:67], v[56:59]
	v_mfma_f32_16x16x32_bf16 v[52:55], v[88:91], v[64:67], v[52:55]
	v_mfma_f32_16x16x32_bf16 v[48:51], v[92:95], v[64:67], v[48:51]
	global_load_dwordx4 v[64:67], v[106:107], off offset:384
	s_waitcnt vmcnt(8)
	ds_write_b128 v121, v[102:105]
	v_add_co_u32_e32 v102, vcc, s11, v106
	s_waitcnt lgkmcnt(11)
	v_mfma_f32_16x16x32_bf16 v[44:47], v[80:83], v[68:71], v[44:47]
	v_addc_co_u32_e32 v103, vcc, 0, v107, vcc
	v_mfma_f32_16x16x32_bf16 v[40:43], v[84:87], v[68:71], v[40:43]
	v_mfma_f32_16x16x32_bf16 v[36:39], v[88:91], v[68:71], v[36:39]
	v_mfma_f32_16x16x32_bf16 v[32:35], v[92:95], v[68:71], v[32:35]
	global_load_dwordx4 v[68:71], v[102:103], off offset:384
	v_add_co_u32_e32 v102, vcc, s33, v106
	s_waitcnt vmcnt(8)
	ds_write_b128 v121, v[140:143] offset:4096
	v_addc_co_u32_e32 v103, vcc, 0, v107, vcc
	s_waitcnt lgkmcnt(11)
	v_mfma_f32_16x16x32_bf16 v[28:31], v[80:83], v[72:75], v[28:31]
	v_mfma_f32_16x16x32_bf16 v[24:27], v[84:87], v[72:75], v[24:27]
	v_mfma_f32_16x16x32_bf16 v[20:23], v[88:91], v[72:75], v[20:23]
	v_mfma_f32_16x16x32_bf16 v[16:19], v[92:95], v[72:75], v[16:19]
	global_load_dwordx4 v[72:75], v[102:103], off offset:384
	s_waitcnt vmcnt(8)
	ds_write_b128 v121, v[144:147] offset:8192
	s_waitcnt lgkmcnt(11)
	v_mfma_f32_16x16x32_bf16 v[12:15], v[80:83], v[76:79], v[12:15]
	v_add_co_u32_e32 v80, vcc, s59, v106
	v_mfma_f32_16x16x32_bf16 v[0:3], v[92:95], v[76:79], v[0:3]
	s_nop 0
	v_addc_co_u32_e32 v81, vcc, 0, v107, vcc
	v_lshl_add_u64 v[92:93], v[100:101], 0, s[92:93]
	v_mfma_f32_16x16x32_bf16 v[8:11], v[84:87], v[76:79], v[8:11]
	v_add_co_u32_e32 v84, vcc, s11, v92
	s_nop 1
	v_addc_co_u32_e32 v85, vcc, 0, v93, vcc
	v_mfma_f32_16x16x32_bf16 v[4:7], v[88:91], v[76:79], v[4:7]
	v_add_co_u32_e32 v88, vcc, s33, v92
	global_load_dwordx4 v[80:83], v[80:81], off offset:384
	s_nop 0
	v_addc_co_u32_e32 v89, vcc, 0, v93, vcc
	s_waitcnt vmcnt(8)
	ds_write_b128 v121, v[148:151] offset:12288
	s_waitcnt lgkmcnt(7)
	v_mfma_f32_16x16x32_bf16 v[60:63], v[210:213], v[194:197], v[60:63]
	s_waitcnt lgkmcnt(6)
	v_mfma_f32_16x16x32_bf16 v[56:59], v[214:217], v[194:197], v[56:59]
	s_waitcnt lgkmcnt(5)
	v_mfma_f32_16x16x32_bf16 v[52:55], v[218:221], v[194:197], v[52:55]
	s_waitcnt lgkmcnt(4)
	v_mfma_f32_16x16x32_bf16 v[48:51], v[222:225], v[194:197], v[48:51]
	global_load_dwordx4 v[76:79], v[92:93], off offset:384
	v_add_co_u32_e32 v92, vcc, s59, v92
	s_waitcnt vmcnt(8)
	ds_write_b128 v121, v[152:155] offset:16384
	v_addc_co_u32_e32 v93, vcc, 0, v93, vcc
	v_mfma_f32_16x16x32_bf16 v[44:47], v[210:213], v[198:201], v[44:47]
	v_mfma_f32_16x16x32_bf16 v[40:43], v[214:217], v[198:201], v[40:43]
	v_mfma_f32_16x16x32_bf16 v[36:39], v[218:221], v[198:201], v[36:39]
	v_mfma_f32_16x16x32_bf16 v[32:35], v[222:225], v[198:201], v[32:35]
	global_load_dwordx4 v[84:87], v[84:85], off offset:384
	s_waitcnt vmcnt(8)
	ds_write_b128 v121, v[156:159] offset:20480
	v_mfma_f32_16x16x32_bf16 v[28:31], v[210:213], v[202:205], v[28:31]
	v_mfma_f32_16x16x32_bf16 v[24:27], v[214:217], v[202:205], v[24:27]
	v_mfma_f32_16x16x32_bf16 v[20:23], v[218:221], v[202:205], v[20:23]
	v_mfma_f32_16x16x32_bf16 v[16:19], v[222:225], v[202:205], v[16:19]
	global_load_dwordx4 v[88:91], v[88:89], off offset:384
	s_waitcnt vmcnt(8)
	ds_write_b128 v121, v[160:163] offset:24576
	v_mfma_f32_16x16x32_bf16 v[12:15], v[210:213], v[206:209], v[12:15]
	v_mfma_f32_16x16x32_bf16 v[8:11], v[214:217], v[206:209], v[8:11]
	v_mfma_f32_16x16x32_bf16 v[4:7], v[218:221], v[206:209], v[4:7]
	v_mfma_f32_16x16x32_bf16 v[0:3], v[222:225], v[206:209], v[0:3]
	global_load_dwordx4 v[92:95], v[92:93], off offset:384
	s_waitcnt vmcnt(8)
	ds_write_b128 v121, v[190:193] offset:28672
	s_cmp_lt_u32 s2, 14
	s_mov_b32 s3, s2
	s_waitcnt lgkmcnt(0)
	s_barrier
	s_cbranch_scc1 .LBB0_702
	s_and_saveexec_b64 s[2:3], s[36:37]
	s_cbranch_execz .LBB0_705
	s_waitcnt vmcnt(7)
	v_add_f32_e32 v64, 0, v96
	v_add_f32_e32 v64, v64, v97
	v_add_f32_e32 v64, v64, v108
	v_add_f32_e32 v64, v64, v109
	v_add_f32_e32 v64, v64, v110
	v_add_f32_e32 v64, v64, v111
	v_add_f32_e32 v64, v64, v118
	v_add_f32_e32 v64, v64, v119
	v_add_f32_e32 v64, v64, v128
	v_add_f32_e32 v64, v64, v132
	v_add_f32_e32 v64, v64, v133
	v_add_f32_e32 v64, v64, v134
	v_add_f32_e32 v64, v64, v135
	v_add_f32_e32 v64, v64, v136
	v_add_f32_e32 v64, v64, v137
	v_add_f32_e32 v64, v64, v138
	v_fmamk_f32 v64, v64, 0x3a800000, v167
	s_mov_b32 s17, 0x800000
	v_mul_f32_e32 v65, 0x4b800000, v64
	v_cmp_gt_f32_e32 vcc, s17, v64
	s_nop 1
	v_cndmask_b32_e32 v64, v64, v65, vcc
	v_rsq_f32_e32 v64, v64
	s_nop 0
	v_mul_f32_e32 v65, 0x45800000, v64
	v_cndmask_b32_e32 v64, v64, v65, vcc
	ds_write_b32 v126, v64

.LBB0_739:
	s_add_i32 s2, s3, 2
	v_add_u32_e32 v130, v105, v106
	ds_read_b128 v[116:119], v130 offset:16384
	ds_read_b128 v[120:123], v130 offset:18432
	ds_read_b128 v[124:127], v130 offset:20480
	ds_read_b128 v[132:135], v130 offset:22528
	v_add_u32_e32 v128, v104, v106
	ds_read_b128 v[108:111], v128
	ds_read_b128 v[112:115], v128 offset:2048
	s_add_i32 s3, s3, 4
	s_min_u32 s3, s3, 15
	v_add_u32_e32 v148, v104, v107
	v_add_u32_e32 v149, v105, v107
	s_lshl_b32 s92, s3, 7
	ds_read_b128 v[136:139], v149 offset:18432
	ds_read_b128 v[140:143], v149 offset:20480
	ds_read_b128 v[144:147], v149 offset:22528
	s_waitcnt lgkmcnt(4)
	v_mfma_f32_16x16x32_bf16 v[72:75], v[116:119], v[108:111], v[72:75]
	v_lshl_add_u64 v[52:53], v[80:81], 0, s[92:93]
	v_add_co_u32_e32 v54, vcc, s11, v52
	v_mfma_f32_16x16x32_bf16 v[48:51], v[120:123], v[108:111], v[48:51]
	s_nop 0
	v_addc_co_u32_e32 v55, vcc, 0, v53, vcc
	v_mfma_f32_16x16x32_bf16 v[44:47], v[124:127], v[108:111], v[44:47]
	v_mfma_f32_16x16x32_bf16 v[40:43], v[132:135], v[108:111], v[40:43]
	s_waitcnt lgkmcnt(3)
	v_mfma_f32_16x16x32_bf16 v[108:111], v[116:119], v[112:115], v[16:19]
	s_nop 2
	ds_read_b128 v[16:19], v148
	v_mfma_f32_16x16x32_bf16 v[116:119], v[120:123], v[112:115], v[8:11]
	v_mfma_f32_16x16x32_bf16 v[120:123], v[124:127], v[112:115], v[4:7]
	ds_read_b128 v[124:127], v148 offset:2048
	v_mfma_f32_16x16x32_bf16 v[112:115], v[132:135], v[112:115], v[0:3]
	ds_read_b128 v[132:135], v149 offset:16384
	global_load_dwordx4 v[76:79], v[52:53], off
	s_waitcnt vmcnt(1)
	ds_write_b128 v103, v[12:15] offset:53248
	global_load_dwordx4 v[68:71], v[54:55], off
	v_add_co_u32_e32 v54, vcc, s33, v52
	ds_write_b128 v103, v[20:23] offset:49152
	s_nop 0
	v_addc_co_u32_e32 v55, vcc, 0, v53, vcc
	v_add_co_u32_e32 v52, vcc, s59, v52
	global_load_dwordx4 v[64:67], v[54:55], off
	s_nop 0
	v_addc_co_u32_e32 v53, vcc, 0, v53, vcc
	ds_write_b128 v103, v[24:27] offset:45056
	global_load_dwordx4 v[60:63], v[52:53], off
	v_lshl_add_u64 v[52:53], v[82:83], 0, s[92:93]
	ds_write_b128 v103, v[36:39] offset:32768
	s_waitcnt lgkmcnt(4)
	v_mfma_f32_16x16x32_bf16 v[0:3], v[132:135], v[16:19], v[72:75]
	v_mfma_f32_16x16x32_bf16 v[4:7], v[136:139], v[16:19], v[48:51]
	global_load_dwordx4 v[56:59], v[52:53], off
	v_add_co_u32_e32 v52, vcc, s11, v52
	ds_write_b128 v103, v[32:35] offset:36864
	s_nop 0
	v_addc_co_u32_e32 v53, vcc, 0, v53, vcc
	v_mfma_f32_16x16x32_bf16 v[8:11], v[140:143], v[16:19], v[44:47]
	v_mfma_f32_16x16x32_bf16 v[16:19], v[144:147], v[16:19], v[40:43]
	global_load_dwordx4 v[52:55], v[52:53], off
	ds_write_b128 v103, v[28:31] offset:40960
	v_mfma_f32_16x16x32_bf16 v[40:43], v[132:135], v[124:127], v[108:111]
	v_mfma_f32_16x16x32_bf16 v[44:47], v[136:139], v[124:127], v[116:119]
	v_mfma_f32_16x16x32_bf16 v[48:51], v[140:143], v[124:127], v[120:123]
	v_mfma_f32_16x16x32_bf16 v[72:75], v[144:147], v[124:127], v[112:115]
	s_waitcnt lgkmcnt(0)
	s_barrier
	ds_read_b128 v[116:119], v130 offset:49152
	ds_read_b128 v[120:123], v130 offset:51200
	ds_read_b128 v[124:127], v130 offset:53248
	ds_read_b128 v[132:135], v130 offset:55296
	ds_read_b128 v[108:111], v128 offset:32768
	ds_read_b128 v[112:115], v128 offset:34816
	s_min_u32 s3, s2, 12
	s_lshl_b32 s92, s3, 7
	ds_read_b128 v[136:139], v149 offset:51200
	ds_read_b128 v[140:143], v149 offset:53248
	ds_read_b128 v[144:147], v149 offset:55296
	s_waitcnt lgkmcnt(4)
	v_mfma_f32_16x16x32_bf16 v[0:3], v[116:119], v[108:111], v[0:3]
	v_lshl_add_u64 v[12:13], v[80:81], 0, s[92:93]
	v_add_co_u32_e32 v14, vcc, s11, v12
	v_mfma_f32_16x16x32_bf16 v[4:7], v[120:123], v[108:111], v[4:7]
	s_nop 0
	v_addc_co_u32_e32 v15, vcc, 0, v13, vcc
	v_mfma_f32_16x16x32_bf16 v[8:11], v[124:127], v[108:111], v[8:11]
	v_mfma_f32_16x16x32_bf16 v[16:19], v[132:135], v[108:111], v[16:19]
	s_waitcnt lgkmcnt(3)
	v_mfma_f32_16x16x32_bf16 v[108:111], v[116:119], v[112:115], v[40:43]
	s_nop 2
	ds_read_b128 v[40:43], v148 offset:32768
	v_mfma_f32_16x16x32_bf16 v[116:119], v[120:123], v[112:115], v[44:47]
	v_mfma_f32_16x16x32_bf16 v[120:123], v[124:127], v[112:115], v[48:51]
	ds_read_b128 v[124:127], v148 offset:34816
	v_mfma_f32_16x16x32_bf16 v[112:115], v[132:135], v[112:115], v[72:75]
	ds_read_b128 v[132:135], v149 offset:49152
	global_load_dwordx4 v[36:39], v[12:13], off offset:384
	s_waitcnt vmcnt(1)
	ds_write_b128 v103, v[52:55] offset:20480
	global_load_dwordx4 v[32:35], v[14:15], off offset:384
	v_add_co_u32_e32 v14, vcc, s33, v12
	ds_write_b128 v103, v[56:59] offset:16384
	s_nop 0
	v_addc_co_u32_e32 v15, vcc, 0, v13, vcc
	v_add_co_u32_e32 v12, vcc, s59, v12
	global_load_dwordx4 v[28:31], v[14:15], off offset:384
	s_nop 0
	v_addc_co_u32_e32 v13, vcc, 0, v13, vcc
	ds_write_b128 v103, v[60:63] offset:12288
	global_load_dwordx4 v[24:27], v[12:13], off offset:384
	v_lshl_add_u64 v[12:13], v[82:83], 0, s[92:93]
	ds_write_b128 v103, v[76:79]
	s_waitcnt lgkmcnt(4)
	v_mfma_f32_16x16x32_bf16 v[72:75], v[132:135], v[40:43], v[0:3]
	v_mfma_f32_16x16x32_bf16 v[48:51], v[136:139], v[40:43], v[4:7]
	global_load_dwordx4 v[20:23], v[12:13], off offset:384
	v_add_co_u32_e32 v12, vcc, s11, v12
	ds_write_b128 v103, v[68:71] offset:4096
	s_nop 0
	v_addc_co_u32_e32 v13, vcc, 0, v13, vcc
	v_mfma_f32_16x16x32_bf16 v[44:47], v[140:143], v[40:43], v[8:11]
	v_mfma_f32_16x16x32_bf16 v[40:43], v[144:147], v[40:43], v[16:19]
	global_load_dwordx4 v[12:15], v[12:13], off offset:384
	ds_write_b128 v103, v[64:67] offset:8192
	v_mfma_f32_16x16x32_bf16 v[16:19], v[132:135], v[124:127], v[108:111]
	v_mfma_f32_16x16x32_bf16 v[8:11], v[136:139], v[124:127], v[116:119]
	v_mfma_f32_16x16x32_bf16 v[4:7], v[140:143], v[124:127], v[120:123]
	v_mfma_f32_16x16x32_bf16 v[0:3], v[144:147], v[124:127], v[112:115]
	s_cmp_lt_u32 s2, 14
	s_mov_b32 s3, s2
	s_waitcnt lgkmcnt(0)
	s_barrier
	s_cbranch_scc1 .LBB0_739
	s_movk_i32 s2, 0x80
	v_cmp_gt_i32_e32 vcc, s2, v85
	s_and_saveexec_b64 s[2:3], vcc
	s_cbranch_execz .LBB0_742
	s_waitcnt vmcnt(0)
	v_add_f32_e32 v12, 0, v102
	v_add_f32_e32 v12, v12, v86
	v_add_f32_e32 v12, v12, v87
	v_add_f32_e32 v12, v12, v88
	v_add_f32_e32 v12, v12, v89
	v_add_f32_e32 v12, v12, v90
	v_add_f32_e32 v12, v12, v91
	v_add_f32_e32 v12, v12, v92
	v_add_f32_e32 v12, v12, v93
	v_add_f32_e32 v12, v12, v95
	v_add_f32_e32 v12, v12, v96
	v_add_f32_e32 v12, v12, v97
	v_add_f32_e32 v12, v12, v98
	v_add_f32_e32 v12, v12, v99
	v_add_f32_e32 v12, v12, v100
	v_add_f32_e32 v12, v12, v101
	v_fmamk_f32 v12, v12, 0x3a800000, v167
	s_mov_b32 s16, 0x800000
	v_mul_f32_e32 v13, 0x4b800000, v12
	v_cmp_gt_f32_e32 vcc, s16, v12
	s_nop 1
	v_cndmask_b32_e32 v12, v12, v13, vcc
	v_rsq_f32_e32 v12, v12
	v_lshl_add_u32 v13, v85, 2, 0
	v_add_u32_e32 v13, 0x10000, v13
	v_mul_f32_e32 v14, 0x45800000, v12
	v_cndmask_b32_e32 v12, v12, v14, vcc
	ds_write_b32 v13, v12
